# speedup vs baseline: 1.0081x; 1.0081x over previous
; #define PG8_STAGE(bufoff, gbase, voff) do { _Pragma("unroll") for (int _i = 0; _i < 2; ++_i) \
;         __builtin_amdgcn_global_load_lds((const unsigned*)((const char*)(gbase) + (voff)[_i]), (LAS unsigned*)(lds + (bufoff) + ldsw + _i * 8192), 16, 0, 0); } while (0)
; #define PG8_LDA(dst, b, h) do { _Pragma("unroll") for (int m = 0; m < 4; ++m) _Pragma("unroll") for (int k = 0; k < 2; ++k) dst[m][k] = *(const LAS bf16x8*)(lds + PG8_SA(b, h) + aoff + m * 2048 + k * 1024); } while (0)
; #define PG8_LDB(dst, b, h) do { _Pragma("unroll") for (int n = 0; n < 2; ++n) _Pragma("unroll") for (int k = 0; k < 2; ++k) dst[n][k] = *(const LAS bf16x8*)(lds + PG8_SB(b, h) + boff + n * 2048 + k * 1024); } while (0)
; #define PG8_MMA(ai, bj, At, Bt) do { __builtin_amdgcn_s_setprio(1); _Pragma("unroll") for (int m = 0; m < 4; ++m) _Pragma("unroll") for (int n = 0; n < 2; ++n) _Pragma("unroll") for (int k = 0; k < 2; ++k) \
;         acc[ai][bj][m][n] = __builtin_amdgcn_mfma_f32_16x16x32_bf16(Bt[n][k], At[m][k], acc[ai][bj][m][n], 0, 0, 0); __builtin_amdgcn_s_setprio(0); } while (0)
; #define PG8_WAIT_V(n) asm volatile("s_waitcnt vmcnt(" #n ")" ::: "memory")
; #define PG8_WAIT_L(n) asm volatile("s_waitcnt lgkmcnt(" #n ")" ::: "memory")
; #define PG8_BAR __builtin_amdgcn_s_barrier()
; #define PG8_SCHED __builtin_amdgcn_sched_barrier(0)
; template <class Epi, class Pre, bool AG = false>
; __device__ __forceinline__ void gemm_phase(LAS unsigned char* lds, const Gemm g, const StaticOrder& S, const Epi& E, const Pre& P) {
;     ...
;             PG8_LDB(B0, 0, 0); PG8_LDB(B1, 0, 1); PG8_SCHED; PG8_LDA(At, 0, 0); PG8_STAGE(PG8_SA(1, 1), a1 + hstepA, voffA);
;             PG8_WAIT_V(8); PG8_WAIT_L(0); PG8_BAR; PG8_MMA(0, 0, At, B0); PG8_MMA(0, 1, At, B1); PG8_BAR; PG8_SCHED;
;             PG8_LDA(At, 0, 1); PG8_STAGE(PG8_SB(0, 0), b2, voffB); PG8_STAGE(PG8_SB(0, 1), b2 + hstep, voffB); PG8_STAGE(PG8_SA(0, 0), a2, voffA);
;             PG8_WAIT_V(8); PG8_WAIT_L(0); PG8_BAR; PG8_MMA(1, 0, At, B0); PG8_MMA(1, 1, At, B1); PG8_BAR; PG8_SCHED;
.Lpw_gu_0_done:
	s_waitcnt lgkmcnt(0)
	s_barrier
	s_setprio 1
	v_mfma_f32_16x16x32_bf16 v[122:125], v[140:143], v[174:177], 0
	v_mfma_f32_16x16x32_bf16 v[114:117], v[150:153], v[174:177], 0
	v_mfma_f32_16x16x32_bf16 v[106:109], v[140:143], v[198:201], 0
	v_mfma_f32_16x16x32_bf16 v[98:101], v[150:153], v[198:201], 0
	v_mfma_f32_16x16x32_bf16 v[90:93], v[140:143], v[206:209], 0
	v_mfma_f32_16x16x32_bf16 v[82:85], v[150:153], v[206:209], 0
	v_mfma_f32_16x16x32_bf16 v[74:77], v[140:143], v[214:217], 0
	v_mfma_f32_16x16x32_bf16 v[66:69], v[150:153], v[214:217], 0
	v_mfma_f32_16x16x32_bf16 v[122:125], v[144:147], v[194:197], v[122:125]
	v_mfma_f32_16x16x32_bf16 v[114:117], v[154:157], v[194:197], v[114:117]
	v_mfma_f32_16x16x32_bf16 v[106:109], v[144:147], v[202:205], v[106:109]
	v_mfma_f32_16x16x32_bf16 v[98:101], v[154:157], v[202:205], v[98:101]
	v_mfma_f32_16x16x32_bf16 v[90:93], v[144:147], v[210:213], v[90:93]
	v_mfma_f32_16x16x32_bf16 v[82:85], v[154:157], v[210:213], v[82:85]
	v_mfma_f32_16x16x32_bf16 v[74:77], v[144:147], v[218:221], v[74:77]
	v_mfma_f32_16x16x32_bf16 v[66:69], v[154:157], v[218:221], v[66:69]
	v_mfma_f32_16x16x32_bf16 v[126:129], v[158:161], v[174:177], 0
	v_mfma_f32_16x16x32_bf16 v[118:121], v[166:169], v[174:177], 0
	v_mfma_f32_16x16x32_bf16 v[110:113], v[158:161], v[198:201], 0
	v_mfma_f32_16x16x32_bf16 v[102:105], v[166:169], v[198:201], 0
	v_mfma_f32_16x16x32_bf16 v[94:97], v[158:161], v[206:209], 0
	v_mfma_f32_16x16x32_bf16 v[86:89], v[166:169], v[206:209], 0
	v_mfma_f32_16x16x32_bf16 v[78:81], v[158:161], v[214:217], 0
	v_mfma_f32_16x16x32_bf16 v[70:73], v[166:169], v[214:217], 0
	v_mfma_f32_16x16x32_bf16 v[126:129], v[162:165], v[194:197], v[126:129]
	v_mfma_f32_16x16x32_bf16 v[118:121], v[170:173], v[194:197], v[118:121]
	v_mfma_f32_16x16x32_bf16 v[110:113], v[162:165], v[202:205], v[110:113]
	v_mfma_f32_16x16x32_bf16 v[102:105], v[170:173], v[202:205], v[102:105]
	v_mfma_f32_16x16x32_bf16 v[94:97], v[162:165], v[210:213], v[94:97]
	v_mfma_f32_16x16x32_bf16 v[86:89], v[170:173], v[210:213], v[86:89]
	v_mfma_f32_16x16x32_bf16 v[78:81], v[162:165], v[218:221], v[78:81]
	v_mfma_f32_16x16x32_bf16 v[70:73], v[170:173], v[218:221], v[70:73]
	s_setprio 0
	s_barrier
	s_add_i32 s84, s84, s31
	v_lshl_add_u64 v[178:179], s[46:47], 0, v[134:135]
	s_mov_b32 m0, s84
	ds_read_b128 v[174:177], v149 offset:16384
	ds_read_b128 v[194:197], v149 offset:17408
	ds_read_b128 v[198:201], v149 offset:18432
	ds_read_b128 v[202:205], v149 offset:19456
	ds_read_b128 v[206:209], v149 offset:20480
	ds_read_b128 v[210:213], v149 offset:21504
	ds_read_b128 v[214:217], v149 offset:22528
	ds_read_b128 v[218:221], v149 offset:23552
	global_load_lds_dwordx4 v[178:179], off
	s_add_i32 m0, s84, 0x2000
	s_add_u32 s84, s46, 0x40000
	v_lshl_add_u64 v[180:181], s[46:47], 0, v[130:131]
	s_addc_u32 s85, s47, 0
	s_add_i32 s86, s86, s31
	global_load_lds_dwordx4 v[180:181], off
	v_lshl_add_u64 v[182:183], s[84:85], 0, v[134:135]
	s_mov_b32 m0, s86
	v_lshl_add_u64 v[188:189], s[54:55], 0, v[132:133]
	global_load_lds_dwordx4 v[182:183], off
	v_lshl_add_u64 v[182:183], s[84:85], 0, v[130:131]
	s_add_i32 m0, s86, 0x2000
	s_nop 0
	global_load_lds_dwordx4 v[182:183], off
	v_lshl_add_u64 v[182:183], s[54:55], 0, v[136:137]
	s_mov_b32 m0, s38
	s_nop 0
	global_load_lds_dwordx4 v[182:183], off
	s_mov_b32 m0, s48
	s_nop 0
	global_load_lds_dwordx4 v[188:189], off
	s_cmp_eq_u32 s70, 0
	s_cbranch_scc1 .Lpw_gu_1
	s_waitcnt vmcnt(16)
	s_branch .Lpw_gu_1_done

; #define PG8_STAGE(bufoff, gbase, voff) do { _Pragma("unroll") for (int _i = 0; _i < 2; ++_i) \
;         __builtin_amdgcn_global_load_lds((const unsigned*)((const char*)(gbase) + (voff)[_i]), (LAS unsigned*)(lds + (bufoff) + ldsw + _i * 8192), 16, 0, 0); } while (0)
; #define PG8_LDA(dst, b, h) do { _Pragma("unroll") for (int m = 0; m < 4; ++m) _Pragma("unroll") for (int k = 0; k < 2; ++k) dst[m][k] = *(const LAS bf16x8*)(lds + PG8_SA(b, h) + aoff + m * 2048 + k * 1024); } while (0)
; #define PG8_LDB(dst, b, h) do { _Pragma("unroll") for (int n = 0; n < 2; ++n) _Pragma("unroll") for (int k = 0; k < 2; ++k) dst[n][k] = *(const LAS bf16x8*)(lds + PG8_SB(b, h) + boff + n * 2048 + k * 1024); } while (0)
; #define PG8_MMA(ai, bj, At, Bt) do { __builtin_amdgcn_s_setprio(1); _Pragma("unroll") for (int m = 0; m < 4; ++m) _Pragma("unroll") for (int n = 0; n < 2; ++n) _Pragma("unroll") for (int k = 0; k < 2; ++k) \
;         acc[ai][bj][m][n] = __builtin_amdgcn_mfma_f32_16x16x32_bf16(Bt[n][k], At[m][k], acc[ai][bj][m][n], 0, 0, 0); __builtin_amdgcn_s_setprio(0); } while (0)
; #define PG8_WAIT_V(n) asm volatile("s_waitcnt vmcnt(" #n ")" ::: "memory")
; #define PG8_WAIT_L(n) asm volatile("s_waitcnt lgkmcnt(" #n ")" ::: "memory")
; #define PG8_BAR __builtin_amdgcn_s_barrier()
; #define PG8_SCHED __builtin_amdgcn_sched_barrier(0)
; template <class Epi, class Pre, bool AG = false>
; __device__ __forceinline__ void gemm_phase(LAS unsigned char* lds, const Gemm g, const StaticOrder& S, const Epi& E, const Pre& P) {
;     ...
;             PG8_WAIT_V(8); PG8_WAIT_L(0); PG8_BAR; PG8_MMA(1, 0, At, B0); PG8_MMA(1, 1, At, B1); PG8_BAR; PG8_SCHED;
;             PG8_LDB(B0, 1, 0); PG8_LDB(B1, 1, 1); PG8_SCHED; PG8_LDA(At, 1, 0); PG8_STAGE(PG8_SA(0, 1), a2 + hstepA, voffA);
;             PG8_WAIT_V(8); PG8_WAIT_L(0); PG8_BAR; PG8_MMA(0, 0, At, B0); PG8_MMA(0, 1, At, B1); PG8_BAR; PG8_SCHED;
.Lpw_gu_1_done:
	s_waitcnt lgkmcnt(0)
	s_barrier
	s_setprio 1
	v_mfma_f32_16x16x32_bf16 v[58:61], v[140:143], v[174:177], 0
	v_mfma_f32_16x16x32_bf16 v[50:53], v[150:153], v[174:177], 0
	v_mfma_f32_16x16x32_bf16 v[42:45], v[140:143], v[198:201], 0
	v_mfma_f32_16x16x32_bf16 v[34:37], v[150:153], v[198:201], 0
	v_mfma_f32_16x16x32_bf16 v[26:29], v[140:143], v[206:209], 0
	v_mfma_f32_16x16x32_bf16 v[18:21], v[150:153], v[206:209], 0
	v_mfma_f32_16x16x32_bf16 v[10:13], v[140:143], v[214:217], 0
	v_mfma_f32_16x16x32_bf16 v[6:9], v[150:153], v[214:217], 0
	v_mfma_f32_16x16x32_bf16 v[58:61], v[144:147], v[194:197], v[58:61]
	v_mfma_f32_16x16x32_bf16 v[50:53], v[154:157], v[194:197], v[50:53]
	v_mfma_f32_16x16x32_bf16 v[42:45], v[144:147], v[202:205], v[42:45]
	v_mfma_f32_16x16x32_bf16 v[34:37], v[154:157], v[202:205], v[34:37]
	v_mfma_f32_16x16x32_bf16 v[26:29], v[144:147], v[210:213], v[26:29]
	v_mfma_f32_16x16x32_bf16 v[18:21], v[154:157], v[210:213], v[18:21]
	v_mfma_f32_16x16x32_bf16 v[10:13], v[144:147], v[218:221], v[10:13]
	v_mfma_f32_16x16x32_bf16 v[6:9], v[154:157], v[218:221], v[6:9]
	v_mfma_f32_16x16x32_bf16 v[62:65], v[158:161], v[174:177], 0
	v_mfma_f32_16x16x32_bf16 v[54:57], v[166:169], v[174:177], 0
	v_mfma_f32_16x16x32_bf16 v[46:49], v[158:161], v[198:201], 0
	v_mfma_f32_16x16x32_bf16 v[38:41], v[166:169], v[198:201], 0
	v_mfma_f32_16x16x32_bf16 v[30:33], v[158:161], v[206:209], 0
	v_mfma_f32_16x16x32_bf16 v[22:25], v[166:169], v[206:209], 0
	v_mfma_f32_16x16x32_bf16 v[14:17], v[158:161], v[214:217], 0
	v_mfma_f32_16x16x32_bf16 v[2:5], v[166:169], v[214:217], 0
	v_mfma_f32_16x16x32_bf16 v[62:65], v[162:165], v[194:197], v[62:65]
	v_mfma_f32_16x16x32_bf16 v[54:57], v[170:173], v[194:197], v[54:57]
	v_mfma_f32_16x16x32_bf16 v[46:49], v[162:165], v[202:205], v[46:49]
	v_mfma_f32_16x16x32_bf16 v[38:41], v[170:173], v[202:205], v[38:41]
	v_mfma_f32_16x16x32_bf16 v[30:33], v[162:165], v[210:213], v[30:33]
	v_mfma_f32_16x16x32_bf16 v[22:25], v[170:173], v[210:213], v[22:25]
	v_mfma_f32_16x16x32_bf16 v[14:17], v[162:165], v[218:221], v[14:17]
	v_mfma_f32_16x16x32_bf16 v[2:5], v[170:173], v[218:221], v[2:5]
	s_setprio 0
	s_barrier
	s_add_i32 s84, 0, 0x18000
	s_add_i32 s85, 0, 0x1c000
	v_add_u32_e32 v154, s84, v148
	v_add_u32_e32 v170, s85, v148
	ds_read_b128 v[140:143], v154
	ds_read_b128 v[144:147], v154 offset:1024
	ds_read_b128 v[150:153], v154 offset:2048
	ds_read_b128 v[154:157], v154 offset:3072
	ds_read_b128 v[158:161], v170
	ds_read_b128 v[162:165], v170 offset:1024
	ds_read_b128 v[166:169], v170 offset:2048
	ds_read_b128 v[170:173], v170 offset:3072
	s_add_u32 s54, s54, 0x40000
	s_addc_u32 s55, s55, 0
	s_mov_b32 m0, s49
	v_lshl_add_u64 v[190:191], s[54:55], 0, v[136:137]
	ds_read_b128 v[174:177], v149 offset:32768
	ds_read_b128 v[194:197], v149 offset:33792
	ds_read_b128 v[198:201], v149 offset:34816
	ds_read_b128 v[202:205], v149 offset:35840
	ds_read_b128 v[206:209], v149 offset:36864
	ds_read_b128 v[210:213], v149 offset:37888
	ds_read_b128 v[214:217], v149 offset:38912
	ds_read_b128 v[218:221], v149 offset:39936
	global_load_lds_dwordx4 v[190:191], off
	v_lshl_add_u64 v[190:191], s[54:55], 0, v[132:133]
	s_mov_b32 m0, s53
	s_nop 0
	global_load_lds_dwordx4 v[190:191], off
	s_waitcnt vmcnt(8)
	s_waitcnt lgkmcnt(0)
	s_barrier
	s_setprio 1
	v_mfma_f32_16x16x32_bf16 v[122:125], v[140:143], v[174:177], v[122:125]
	v_mfma_f32_16x16x32_bf16 v[114:117], v[150:153], v[174:177], v[114:117]
	v_mfma_f32_16x16x32_bf16 v[106:109], v[140:143], v[198:201], v[106:109]
	v_mfma_f32_16x16x32_bf16 v[98:101], v[150:153], v[198:201], v[98:101]
	v_mfma_f32_16x16x32_bf16 v[90:93], v[140:143], v[206:209], v[90:93]
	v_mfma_f32_16x16x32_bf16 v[82:85], v[150:153], v[206:209], v[82:85]
	v_mfma_f32_16x16x32_bf16 v[74:77], v[140:143], v[214:217], v[74:77]
	v_mfma_f32_16x16x32_bf16 v[66:69], v[150:153], v[214:217], v[66:69]
	v_mfma_f32_16x16x32_bf16 v[122:125], v[144:147], v[194:197], v[122:125]
	v_mfma_f32_16x16x32_bf16 v[114:117], v[154:157], v[194:197], v[114:117]
	v_mfma_f32_16x16x32_bf16 v[106:109], v[144:147], v[202:205], v[106:109]
	v_mfma_f32_16x16x32_bf16 v[98:101], v[154:157], v[202:205], v[98:101]
	v_mfma_f32_16x16x32_bf16 v[90:93], v[144:147], v[210:213], v[90:93]
	v_mfma_f32_16x16x32_bf16 v[82:85], v[154:157], v[210:213], v[82:85]
	v_mfma_f32_16x16x32_bf16 v[74:77], v[144:147], v[218:221], v[74:77]
	v_mfma_f32_16x16x32_bf16 v[66:69], v[154:157], v[218:221], v[66:69]
	v_mfma_f32_16x16x32_bf16 v[126:129], v[158:161], v[174:177], v[126:129]
	v_mfma_f32_16x16x32_bf16 v[118:121], v[166:169], v[174:177], v[118:121]
	v_mfma_f32_16x16x32_bf16 v[110:113], v[158:161], v[198:201], v[110:113]
	v_mfma_f32_16x16x32_bf16 v[102:105], v[166:169], v[198:201], v[102:105]
	v_mfma_f32_16x16x32_bf16 v[94:97], v[158:161], v[206:209], v[94:97]
	v_mfma_f32_16x16x32_bf16 v[86:89], v[166:169], v[206:209], v[86:89]
	v_mfma_f32_16x16x32_bf16 v[78:81], v[158:161], v[214:217], v[78:81]
	v_mfma_f32_16x16x32_bf16 v[70:73], v[166:169], v[214:217], v[70:73]
	v_mfma_f32_16x16x32_bf16 v[126:129], v[162:165], v[194:197], v[126:129]
	v_mfma_f32_16x16x32_bf16 v[118:121], v[170:173], v[194:197], v[118:121]
	v_mfma_f32_16x16x32_bf16 v[110:113], v[162:165], v[202:205], v[110:113]
	v_mfma_f32_16x16x32_bf16 v[102:105], v[170:173], v[202:205], v[102:105]
	v_mfma_f32_16x16x32_bf16 v[94:97], v[162:165], v[210:213], v[94:97]
	v_mfma_f32_16x16x32_bf16 v[86:89], v[170:173], v[210:213], v[86:89]
	v_mfma_f32_16x16x32_bf16 v[78:81], v[162:165], v[218:221], v[78:81]
	v_mfma_f32_16x16x32_bf16 v[70:73], v[170:173], v[218:221], v[70:73]
	s_setprio 0
	s_barrier
; #define PG8_STAGE(bufoff, gbase, voff) do { _Pragma("unroll") for (int _i = 0; _i < 2; ++_i) \
;         __builtin_amdgcn_global_load_lds((const unsigned*)((const char*)(gbase) + (voff)[_i]), (LAS unsigned*)(lds + (bufoff) + ldsw + _i * 8192), 16, 0, 0); } while (0)
; #define PG8_LDA(dst, b, h) do { _Pragma("unroll") for (int m = 0; m < 4; ++m) _Pragma("unroll") for (int k = 0; k < 2; ++k) dst[m][k] = *(const LAS bf16x8*)(lds + PG8_SA(b, h) + aoff + m * 2048 + k * 1024); } while (0)
; #define PG8_LDB(dst, b, h) do { _Pragma("unroll") for (int n = 0; n < 2; ++n) _Pragma("unroll") for (int k = 0; k < 2; ++k) dst[n][k] = *(const LAS bf16x8*)(lds + PG8_SB(b, h) + boff + n * 2048 + k * 1024); } while (0)
; #define PG8_MMA(ai, bj, At, Bt) do { __builtin_amdgcn_s_setprio(1); _Pragma("unroll") for (int m = 0; m < 4; ++m) _Pragma("unroll") for (int n = 0; n < 2; ++n) _Pragma("unroll") for (int k = 0; k < 2; ++k) \
;         acc[ai][bj][m][n] = __builtin_amdgcn_mfma_f32_16x16x32_bf16(Bt[n][k], At[m][k], acc[ai][bj][m][n], 0, 0, 0); __builtin_amdgcn_s_setprio(0); } while (0)
; #define PG8_WAIT_V(n) asm volatile("s_waitcnt vmcnt(" #n ")" ::: "memory")
; template <class Epi, class Pre, bool AG = false>
; __device__ __forceinline__ void gemm_phase(LAS unsigned char* lds, const Gemm g, const StaticOrder& S, const Epi& E, const Pre& P) {
;     ...
;             PG8_LDB(B0, 0, 0); PG8_LDB(B1, 0, 1); PG8_SCHED; PG8_LDA(At, 0, 0); PG8_STAGE(PG8_SA(1, 1), a1 + hstepA, voffA);
;             PG8_WAIT_V(8); PG8_WAIT_L(0); PG8_BAR; PG8_MMA(0, 0, At, B0); PG8_MMA(0, 1, At, B1); PG8_BAR; PG8_SCHED;
;             PG8_LDA(At, 0, 1); PG8_STAGE(PG8_SB(0, 0), b2, voffB); PG8_STAGE(PG8_SB(0, 1), b2 + hstep, voffB); PG8_STAGE(PG8_SA(0, 0), a2, voffA);
;             PG8_WAIT_V(8); PG8_WAIT_L(0); PG8_BAR; PG8_MMA(1, 0, At, B0); PG8_MMA(1, 1, At, B1); PG8_BAR; PG8_SCHED;
;             PG8_LDB(B0, 1, 0); PG8_LDB(B1, 1, 1); PG8_SCHED; PG8_LDA(At, 1, 0); PG8_STAGE(PG8_SA(0, 1), a2 + hstepA, voffA);
;             PG8_WAIT_V(8); PG8_WAIT_L(0); PG8_BAR; PG8_MMA(0, 0, At, B0); PG8_MMA(0, 1, At, B1); PG8_BAR; PG8_SCHED;
;             PG8_LDA(At, 1, 1); PG8_STAGE(PG8_SB(1, 0), b3, voffB); PG8_STAGE(PG8_SB(1, 1), b3 + hstep, voffB); PG8_STAGE(PG8_SA(1, 0), a3, voffA);
;             PG8_WAIT_V(8); PG8_WAIT_L(0); PG8_BAR; PG8_MMA(1, 0, At, B0); PG8_MMA(1, 1, At, B1); PG8_BAR; PG8_SCHED;
	s_add_i32 s54, s84, s31
	v_lshl_add_u64 v[178:179], v[178:179], 0, s[66:67]
	s_mov_b32 m0, s54
	ds_read_b128 v[174:177], v149 offset:49152
	ds_read_b128 v[194:197], v149 offset:50176
	ds_read_b128 v[198:201], v149 offset:51200
	ds_read_b128 v[202:205], v149 offset:52224
	ds_read_b128 v[206:209], v149 offset:53248
	ds_read_b128 v[210:213], v149 offset:54272
	ds_read_b128 v[214:217], v149 offset:55296
	ds_read_b128 v[218:221], v149 offset:56320
	global_load_lds_dwordx4 v[178:179], off
	s_add_i32 m0, s54, 0x2000
	s_add_u32 s46, s46, 0x40080
	v_lshl_add_u64 v[178:179], v[180:181], 0, s[66:67]
	s_addc_u32 s47, s47, 0
	s_add_i32 s54, s85, s31
	global_load_lds_dwordx4 v[178:179], off
	v_lshl_add_u64 v[178:179], s[46:47], 0, v[134:135]
	s_mov_b32 m0, s54
	s_nop 0
	global_load_lds_dwordx4 v[178:179], off
	v_lshl_add_u64 v[178:179], s[46:47], 0, v[130:131]
	s_add_i32 m0, s54, 0x2000
	s_nop 0
	global_load_lds_dwordx4 v[178:179], off
	v_lshl_add_u64 v[178:179], v[182:183], 0, s[66:67]
	s_mov_b32 m0, s58
	s_nop 0
	global_load_lds_dwordx4 v[178:179], off
	v_lshl_add_u64 v[178:179], v[188:189], 0, s[66:67]
	s_mov_b32 m0, s59
	s_nop 0
	global_load_lds_dwordx4 v[178:179], off
	s_waitcnt vmcnt(8)
	s_waitcnt lgkmcnt(0)
	s_barrier
	s_setprio 1
	v_mfma_f32_16x16x32_bf16 v[58:61], v[140:143], v[174:177], v[58:61]
	v_mfma_f32_16x16x32_bf16 v[50:53], v[150:153], v[174:177], v[50:53]
	v_mfma_f32_16x16x32_bf16 v[42:45], v[140:143], v[198:201], v[42:45]
	v_mfma_f32_16x16x32_bf16 v[34:37], v[150:153], v[198:201], v[34:37]
	v_mfma_f32_16x16x32_bf16 v[26:29], v[140:143], v[206:209], v[26:29]
	v_mfma_f32_16x16x32_bf16 v[18:21], v[150:153], v[206:209], v[18:21]
	v_mfma_f32_16x16x32_bf16 v[10:13], v[140:143], v[214:217], v[10:13]
	v_mfma_f32_16x16x32_bf16 v[6:9], v[150:153], v[214:217], v[6:9]
	v_mfma_f32_16x16x32_bf16 v[58:61], v[144:147], v[194:197], v[58:61]
	v_mfma_f32_16x16x32_bf16 v[50:53], v[154:157], v[194:197], v[50:53]
	v_mfma_f32_16x16x32_bf16 v[42:45], v[144:147], v[202:205], v[42:45]
	v_mfma_f32_16x16x32_bf16 v[34:37], v[154:157], v[202:205], v[34:37]
	v_mfma_f32_16x16x32_bf16 v[26:29], v[144:147], v[210:213], v[26:29]
	v_mfma_f32_16x16x32_bf16 v[18:21], v[154:157], v[210:213], v[18:21]
	v_mfma_f32_16x16x32_bf16 v[10:13], v[144:147], v[218:221], v[10:13]
	v_mfma_f32_16x16x32_bf16 v[6:9], v[154:157], v[218:221], v[6:9]
	v_mfma_f32_16x16x32_bf16 v[62:65], v[158:161], v[174:177], v[62:65]
	v_mfma_f32_16x16x32_bf16 v[54:57], v[166:169], v[174:177], v[54:57]
	v_mfma_f32_16x16x32_bf16 v[46:49], v[158:161], v[198:201], v[46:49]
	v_mfma_f32_16x16x32_bf16 v[38:41], v[166:169], v[198:201], v[38:41]
	v_mfma_f32_16x16x32_bf16 v[30:33], v[158:161], v[206:209], v[30:33]
	v_mfma_f32_16x16x32_bf16 v[22:25], v[166:169], v[206:209], v[22:25]
	v_mfma_f32_16x16x32_bf16 v[14:17], v[158:161], v[214:217], v[14:17]
	v_mfma_f32_16x16x32_bf16 v[2:5], v[166:169], v[214:217], v[2:5]
	v_mfma_f32_16x16x32_bf16 v[62:65], v[162:165], v[194:197], v[62:65]
	v_mfma_f32_16x16x32_bf16 v[54:57], v[170:173], v[194:197], v[54:57]
	v_mfma_f32_16x16x32_bf16 v[46:49], v[162:165], v[202:205], v[46:49]
	v_mfma_f32_16x16x32_bf16 v[38:41], v[170:173], v[202:205], v[38:41]
	v_mfma_f32_16x16x32_bf16 v[30:33], v[162:165], v[210:213], v[30:33]
	v_mfma_f32_16x16x32_bf16 v[22:25], v[170:173], v[210:213], v[22:25]
	v_mfma_f32_16x16x32_bf16 v[14:17], v[162:165], v[218:221], v[14:17]
	v_mfma_f32_16x16x32_bf16 v[2:5], v[170:173], v[218:221], v[2:5]
	s_setprio 0
	s_barrier
	s_add_i32 s79, s79, 2
	s_add_u32 s44, s44, 0x100
	s_addc_u32 s45, s45, 0
	s_add_u32 s76, s76, 0x100
	s_addc_u32 s77, s77, 0
	s_cmp_gt_u32 s79, 13
	s_cbranch_scc0 .LBB0_212
	s_branch .Lpeel_gu_after
.LBB0_212:
	s_add_u32 s46, s44, 0xfffc0080
	s_addc_u32 s47, s45, -1
	s_add_i32 s84, 0, 0x10000
	s_cmp_eq_u32 s79, 12
	s_cselect_b32 s55, s12, s47
	s_cselect_b32 s54, s13, s46
	s_cselect_b32 s47, s17, s77
	s_cselect_b32 s46, s27, s76
	s_add_i32 s86, 0, 0x14000
	v_add_u32_e32 v154, s84, v148
	v_add_u32_e32 v170, s86, v148
	ds_read_b128 v[140:143], v154
	ds_read_b128 v[144:147], v154 offset:1024
	ds_read_b128 v[150:153], v154 offset:2048
	ds_read_b128 v[154:157], v154 offset:3072
	ds_read_b128 v[158:161], v170
	ds_read_b128 v[162:165], v170 offset:1024
	ds_read_b128 v[166:169], v170 offset:2048
	ds_read_b128 v[170:173], v170 offset:3072
	v_lshl_add_u64 v[178:179], s[44:45], 0, v[0:1]
	s_add_i32 m0, s38, 0xc000
	ds_read_b128 v[174:177], v149
	ds_read_b128 v[194:197], v149 offset:1024
	ds_read_b128 v[198:201], v149 offset:2048
	ds_read_b128 v[202:205], v149 offset:3072
	ds_read_b128 v[206:209], v149 offset:4096
	ds_read_b128 v[210:213], v149 offset:5120
	ds_read_b128 v[214:217], v149 offset:6144
	ds_read_b128 v[218:221], v149 offset:7168
	global_load_lds_dwordx4 v[178:179], off
	v_lshl_add_u64 v[178:179], s[44:45], 0, v[138:139]
	s_add_i32 m0, s38, 0xe000
	s_nop 0
	global_load_lds_dwordx4 v[178:179], off
	s_waitcnt vmcnt(8)
	s_waitcnt lgkmcnt(0)
	s_barrier
; #define PG8_STAGE(bufoff, gbase, voff) do { _Pragma("unroll") for (int _i = 0; _i < 2; ++_i) \
;         __builtin_amdgcn_global_load_lds((const unsigned*)((const char*)(gbase) + (voff)[_i]), (LAS unsigned*)(lds + (bufoff) + ldsw + _i * 8192), 16, 0, 0); } while (0)
; #define PG8_LDA(dst, b, h) do { _Pragma("unroll") for (int m = 0; m < 4; ++m) _Pragma("unroll") for (int k = 0; k < 2; ++k) dst[m][k] = *(const LAS bf16x8*)(lds + PG8_SA(b, h) + aoff + m * 2048 + k * 1024); } while (0)
; #define PG8_MMA(ai, bj, At, Bt) do { __builtin_amdgcn_s_setprio(1); _Pragma("unroll") for (int m = 0; m < 4; ++m) _Pragma("unroll") for (int n = 0; n < 2; ++n) _Pragma("unroll") for (int k = 0; k < 2; ++k) \
;         acc[ai][bj][m][n] = __builtin_amdgcn_mfma_f32_16x16x32_bf16(Bt[n][k], At[m][k], acc[ai][bj][m][n], 0, 0, 0); __builtin_amdgcn_s_setprio(0); } while (0)
; #define PG8_WAIT_V(n) asm volatile("s_waitcnt vmcnt(" #n ")" ::: "memory")
; #define PG8_WAIT_L(n) asm volatile("s_waitcnt lgkmcnt(" #n ")" ::: "memory")
; #define PG8_BAR __builtin_amdgcn_s_barrier()
; #define PG8_SCHED __builtin_amdgcn_sched_barrier(0)
; template <class Epi, class Pre, bool AG = false>
; __device__ __forceinline__ void gemm_phase(LAS unsigned char* lds, const Gemm g, const StaticOrder& S, const Epi& E, const Pre& P) {
;     ...
;             PG8_WAIT_V(8); PG8_WAIT_L(0); PG8_BAR; PG8_MMA(0, 0, At, B0); PG8_MMA(0, 1, At, B1); PG8_BAR; PG8_SCHED;
;             PG8_LDA(At, 0, 1); PG8_STAGE(PG8_SB(0, 0), b2, voffB); PG8_STAGE(PG8_SB(0, 1), b2 + hstep, voffB); PG8_STAGE(PG8_SA(0, 0), a2, voffA);
;             PG8_WAIT_V(8); PG8_WAIT_L(0); PG8_BAR; PG8_MMA(1, 0, At, B0); PG8_MMA(1, 1, At, B1); PG8_BAR; PG8_SCHED;
	s_setprio 1
	v_mfma_f32_16x16x32_bf16 v[122:125], v[140:143], v[174:177], v[122:125]
	v_mfma_f32_16x16x32_bf16 v[114:117], v[150:153], v[174:177], v[114:117]
	v_mfma_f32_16x16x32_bf16 v[106:109], v[140:143], v[198:201], v[106:109]
	v_mfma_f32_16x16x32_bf16 v[98:101], v[150:153], v[198:201], v[98:101]
	v_mfma_f32_16x16x32_bf16 v[90:93], v[140:143], v[206:209], v[90:93]
	v_mfma_f32_16x16x32_bf16 v[82:85], v[150:153], v[206:209], v[82:85]
	v_mfma_f32_16x16x32_bf16 v[74:77], v[140:143], v[214:217], v[74:77]
	v_mfma_f32_16x16x32_bf16 v[66:69], v[150:153], v[214:217], v[66:69]
	v_mfma_f32_16x16x32_bf16 v[122:125], v[144:147], v[194:197], v[122:125]
	v_mfma_f32_16x16x32_bf16 v[114:117], v[154:157], v[194:197], v[114:117]
	v_mfma_f32_16x16x32_bf16 v[106:109], v[144:147], v[202:205], v[106:109]
	v_mfma_f32_16x16x32_bf16 v[98:101], v[154:157], v[202:205], v[98:101]
	v_mfma_f32_16x16x32_bf16 v[90:93], v[144:147], v[210:213], v[90:93]
	v_mfma_f32_16x16x32_bf16 v[82:85], v[154:157], v[210:213], v[82:85]
	v_mfma_f32_16x16x32_bf16 v[74:77], v[144:147], v[218:221], v[74:77]
	v_mfma_f32_16x16x32_bf16 v[66:69], v[154:157], v[218:221], v[66:69]
	v_mfma_f32_16x16x32_bf16 v[126:129], v[158:161], v[174:177], v[126:129]
	v_mfma_f32_16x16x32_bf16 v[118:121], v[166:169], v[174:177], v[118:121]
	v_mfma_f32_16x16x32_bf16 v[110:113], v[158:161], v[198:201], v[110:113]
	v_mfma_f32_16x16x32_bf16 v[102:105], v[166:169], v[198:201], v[102:105]
	v_mfma_f32_16x16x32_bf16 v[94:97], v[158:161], v[206:209], v[94:97]
	v_mfma_f32_16x16x32_bf16 v[86:89], v[166:169], v[206:209], v[86:89]
	v_mfma_f32_16x16x32_bf16 v[78:81], v[158:161], v[214:217], v[78:81]
	v_mfma_f32_16x16x32_bf16 v[70:73], v[166:169], v[214:217], v[70:73]
	v_mfma_f32_16x16x32_bf16 v[126:129], v[162:165], v[194:197], v[126:129]
	v_mfma_f32_16x16x32_bf16 v[118:121], v[170:173], v[194:197], v[118:121]
	v_mfma_f32_16x16x32_bf16 v[110:113], v[162:165], v[202:205], v[110:113]
	v_mfma_f32_16x16x32_bf16 v[102:105], v[170:173], v[202:205], v[102:105]
	v_mfma_f32_16x16x32_bf16 v[94:97], v[162:165], v[210:213], v[94:97]
	v_mfma_f32_16x16x32_bf16 v[86:89], v[170:173], v[210:213], v[86:89]
	v_mfma_f32_16x16x32_bf16 v[78:81], v[162:165], v[218:221], v[78:81]
	v_mfma_f32_16x16x32_bf16 v[70:73], v[170:173], v[218:221], v[70:73]
	s_setprio 0
	s_barrier
	s_add_i32 s84, s84, s31
	v_lshl_add_u64 v[178:179], s[46:47], 0, v[134:135]
	s_mov_b32 m0, s84
	ds_read_b128 v[174:177], v149 offset:16384
	ds_read_b128 v[194:197], v149 offset:17408
	ds_read_b128 v[198:201], v149 offset:18432
	ds_read_b128 v[202:205], v149 offset:19456
	ds_read_b128 v[206:209], v149 offset:20480
	ds_read_b128 v[210:213], v149 offset:21504
	ds_read_b128 v[214:217], v149 offset:22528
	ds_read_b128 v[218:221], v149 offset:23552
	global_load_lds_dwordx4 v[178:179], off
	s_add_i32 m0, s84, 0x2000
	s_add_u32 s84, s46, 0x40000
	v_lshl_add_u64 v[180:181], s[46:47], 0, v[130:131]
	s_addc_u32 s85, s47, 0
	s_add_i32 s86, s86, s31
	global_load_lds_dwordx4 v[180:181], off
	v_lshl_add_u64 v[182:183], s[84:85], 0, v[134:135]
	s_mov_b32 m0, s86
	v_lshl_add_u64 v[188:189], s[54:55], 0, v[132:133]
	global_load_lds_dwordx4 v[182:183], off
	v_lshl_add_u64 v[182:183], s[84:85], 0, v[130:131]
	s_add_i32 m0, s86, 0x2000
	s_nop 0
	global_load_lds_dwordx4 v[182:183], off
	v_lshl_add_u64 v[182:183], s[54:55], 0, v[136:137]
	s_mov_b32 m0, s38
	s_nop 0
	global_load_lds_dwordx4 v[182:183], off
	s_mov_b32 m0, s48
	s_nop 0
	global_load_lds_dwordx4 v[188:189], off
	s_waitcnt vmcnt(8)
	s_waitcnt lgkmcnt(0)
	s_barrier
	s_setprio 1
	v_mfma_f32_16x16x32_bf16 v[58:61], v[140:143], v[174:177], v[58:61]
	v_mfma_f32_16x16x32_bf16 v[50:53], v[150:153], v[174:177], v[50:53]
	v_mfma_f32_16x16x32_bf16 v[42:45], v[140:143], v[198:201], v[42:45]
	v_mfma_f32_16x16x32_bf16 v[34:37], v[150:153], v[198:201], v[34:37]
	v_mfma_f32_16x16x32_bf16 v[26:29], v[140:143], v[206:209], v[26:29]
	v_mfma_f32_16x16x32_bf16 v[18:21], v[150:153], v[206:209], v[18:21]
	v_mfma_f32_16x16x32_bf16 v[10:13], v[140:143], v[214:217], v[10:13]
	v_mfma_f32_16x16x32_bf16 v[6:9], v[150:153], v[214:217], v[6:9]
	v_mfma_f32_16x16x32_bf16 v[58:61], v[144:147], v[194:197], v[58:61]
	v_mfma_f32_16x16x32_bf16 v[50:53], v[154:157], v[194:197], v[50:53]
	v_mfma_f32_16x16x32_bf16 v[42:45], v[144:147], v[202:205], v[42:45]
	v_mfma_f32_16x16x32_bf16 v[34:37], v[154:157], v[202:205], v[34:37]
	v_mfma_f32_16x16x32_bf16 v[26:29], v[144:147], v[210:213], v[26:29]
	v_mfma_f32_16x16x32_bf16 v[18:21], v[154:157], v[210:213], v[18:21]
	v_mfma_f32_16x16x32_bf16 v[10:13], v[144:147], v[218:221], v[10:13]
	v_mfma_f32_16x16x32_bf16 v[6:9], v[154:157], v[218:221], v[6:9]
	v_mfma_f32_16x16x32_bf16 v[62:65], v[158:161], v[174:177], v[62:65]
	v_mfma_f32_16x16x32_bf16 v[54:57], v[166:169], v[174:177], v[54:57]
	v_mfma_f32_16x16x32_bf16 v[46:49], v[158:161], v[198:201], v[46:49]
	v_mfma_f32_16x16x32_bf16 v[38:41], v[166:169], v[198:201], v[38:41]
	v_mfma_f32_16x16x32_bf16 v[30:33], v[158:161], v[206:209], v[30:33]
	v_mfma_f32_16x16x32_bf16 v[22:25], v[166:169], v[206:209], v[22:25]
	v_mfma_f32_16x16x32_bf16 v[14:17], v[158:161], v[214:217], v[14:17]
	v_mfma_f32_16x16x32_bf16 v[2:5], v[166:169], v[214:217], v[2:5]
	v_mfma_f32_16x16x32_bf16 v[62:65], v[162:165], v[194:197], v[62:65]
	v_mfma_f32_16x16x32_bf16 v[54:57], v[170:173], v[194:197], v[54:57]
	v_mfma_f32_16x16x32_bf16 v[46:49], v[162:165], v[202:205], v[46:49]
	v_mfma_f32_16x16x32_bf16 v[38:41], v[170:173], v[202:205], v[38:41]
	v_mfma_f32_16x16x32_bf16 v[30:33], v[162:165], v[210:213], v[30:33]
	v_mfma_f32_16x16x32_bf16 v[22:25], v[170:173], v[210:213], v[22:25]
	v_mfma_f32_16x16x32_bf16 v[14:17], v[162:165], v[218:221], v[14:17]
	v_mfma_f32_16x16x32_bf16 v[2:5], v[170:173], v[218:221], v[2:5]
	s_setprio 0
	s_barrier
; #define PG8_STAGE(bufoff, gbase, voff) do { _Pragma("unroll") for (int _i = 0; _i < 2; ++_i) \
;         __builtin_amdgcn_global_load_lds((const unsigned*)((const char*)(gbase) + (voff)[_i]), (LAS unsigned*)(lds + (bufoff) + ldsw + _i * 8192), 16, 0, 0); } while (0)
; #define PG8_LDA(dst, b, h) do { _Pragma("unroll") for (int m = 0; m < 4; ++m) _Pragma("unroll") for (int k = 0; k < 2; ++k) dst[m][k] = *(const LAS bf16x8*)(lds + PG8_SA(b, h) + aoff + m * 2048 + k * 1024); } while (0)
; #define PG8_LDB(dst, b, h) do { _Pragma("unroll") for (int n = 0; n < 2; ++n) _Pragma("unroll") for (int k = 0; k < 2; ++k) dst[n][k] = *(const LAS bf16x8*)(lds + PG8_SB(b, h) + boff + n * 2048 + k * 1024); } while (0)
; #define PG8_MMA(ai, bj, At, Bt) do { __builtin_amdgcn_s_setprio(1); _Pragma("unroll") for (int m = 0; m < 4; ++m) _Pragma("unroll") for (int n = 0; n < 2; ++n) _Pragma("unroll") for (int k = 0; k < 2; ++k) \
;         acc[ai][bj][m][n] = __builtin_amdgcn_mfma_f32_16x16x32_bf16(Bt[n][k], At[m][k], acc[ai][bj][m][n], 0, 0, 0); __builtin_amdgcn_s_setprio(0); } while (0)
; #define PG8_WAIT_V(n) asm volatile("s_waitcnt vmcnt(" #n ")" ::: "memory")
; #define PG8_WAIT_L(n) asm volatile("s_waitcnt lgkmcnt(" #n ")" ::: "memory")
; #define PG8_BAR __builtin_amdgcn_s_barrier()
; #define PG8_SCHED __builtin_amdgcn_sched_barrier(0)
; template <class Epi, class Pre, bool AG = false>
; __device__ __forceinline__ void gemm_phase(LAS unsigned char* lds, const Gemm g, const StaticOrder& S, const Epi& E, const Pre& P) {
;     ...
;             PG8_LDB(B0, 1, 0); PG8_LDB(B1, 1, 1); PG8_SCHED; PG8_LDA(At, 1, 0); PG8_STAGE(PG8_SA(0, 1), a2 + hstepA, voffA);
;             PG8_WAIT_V(8); PG8_WAIT_L(0); PG8_BAR; PG8_MMA(0, 0, At, B0); PG8_MMA(0, 1, At, B1); PG8_BAR; PG8_SCHED;
	s_add_i32 s84, 0, 0x18000
	s_add_i32 s85, 0, 0x1c000
	v_add_u32_e32 v154, s84, v148
	v_add_u32_e32 v170, s85, v148
	ds_read_b128 v[140:143], v154
	ds_read_b128 v[144:147], v154 offset:1024
	ds_read_b128 v[150:153], v154 offset:2048
	ds_read_b128 v[154:157], v154 offset:3072
	ds_read_b128 v[158:161], v170
	ds_read_b128 v[162:165], v170 offset:1024
	ds_read_b128 v[166:169], v170 offset:2048
	ds_read_b128 v[170:173], v170 offset:3072
	s_add_u32 s54, s54, 0x40000
	s_addc_u32 s55, s55, 0
	s_mov_b32 m0, s49
	v_lshl_add_u64 v[190:191], s[54:55], 0, v[136:137]
	ds_read_b128 v[174:177], v149 offset:32768
	ds_read_b128 v[194:197], v149 offset:33792
	ds_read_b128 v[198:201], v149 offset:34816
	ds_read_b128 v[202:205], v149 offset:35840
	ds_read_b128 v[206:209], v149 offset:36864
	ds_read_b128 v[210:213], v149 offset:37888
	ds_read_b128 v[214:217], v149 offset:38912
	ds_read_b128 v[218:221], v149 offset:39936
	global_load_lds_dwordx4 v[190:191], off
	v_lshl_add_u64 v[190:191], s[54:55], 0, v[132:133]
	s_mov_b32 m0, s53
	s_nop 0
	global_load_lds_dwordx4 v[190:191], off
	s_waitcnt vmcnt(8)
	s_waitcnt lgkmcnt(0)
	s_barrier
	s_setprio 1
	v_mfma_f32_16x16x32_bf16 v[122:125], v[140:143], v[174:177], v[122:125]
	v_mfma_f32_16x16x32_bf16 v[114:117], v[150:153], v[174:177], v[114:117]
	v_mfma_f32_16x16x32_bf16 v[106:109], v[140:143], v[198:201], v[106:109]
	v_mfma_f32_16x16x32_bf16 v[98:101], v[150:153], v[198:201], v[98:101]
	v_mfma_f32_16x16x32_bf16 v[90:93], v[140:143], v[206:209], v[90:93]
	v_mfma_f32_16x16x32_bf16 v[82:85], v[150:153], v[206:209], v[82:85]
	v_mfma_f32_16x16x32_bf16 v[74:77], v[140:143], v[214:217], v[74:77]
	v_mfma_f32_16x16x32_bf16 v[66:69], v[150:153], v[214:217], v[66:69]
	v_mfma_f32_16x16x32_bf16 v[122:125], v[144:147], v[194:197], v[122:125]
	v_mfma_f32_16x16x32_bf16 v[114:117], v[154:157], v[194:197], v[114:117]
	v_mfma_f32_16x16x32_bf16 v[106:109], v[144:147], v[202:205], v[106:109]
	v_mfma_f32_16x16x32_bf16 v[98:101], v[154:157], v[202:205], v[98:101]
	v_mfma_f32_16x16x32_bf16 v[90:93], v[144:147], v[210:213], v[90:93]
	v_mfma_f32_16x16x32_bf16 v[82:85], v[154:157], v[210:213], v[82:85]
	v_mfma_f32_16x16x32_bf16 v[74:77], v[144:147], v[218:221], v[74:77]
	v_mfma_f32_16x16x32_bf16 v[66:69], v[154:157], v[218:221], v[66:69]
	v_mfma_f32_16x16x32_bf16 v[126:129], v[158:161], v[174:177], v[126:129]
	v_mfma_f32_16x16x32_bf16 v[118:121], v[166:169], v[174:177], v[118:121]
	v_mfma_f32_16x16x32_bf16 v[110:113], v[158:161], v[198:201], v[110:113]
	v_mfma_f32_16x16x32_bf16 v[102:105], v[166:169], v[198:201], v[102:105]
	v_mfma_f32_16x16x32_bf16 v[94:97], v[158:161], v[206:209], v[94:97]
	v_mfma_f32_16x16x32_bf16 v[86:89], v[166:169], v[206:209], v[86:89]
	v_mfma_f32_16x16x32_bf16 v[78:81], v[158:161], v[214:217], v[78:81]
	v_mfma_f32_16x16x32_bf16 v[70:73], v[166:169], v[214:217], v[70:73]
	v_mfma_f32_16x16x32_bf16 v[126:129], v[162:165], v[194:197], v[126:129]
	v_mfma_f32_16x16x32_bf16 v[118:121], v[170:173], v[194:197], v[118:121]
	v_mfma_f32_16x16x32_bf16 v[110:113], v[162:165], v[202:205], v[110:113]
	v_mfma_f32_16x16x32_bf16 v[102:105], v[170:173], v[202:205], v[102:105]
	v_mfma_f32_16x16x32_bf16 v[94:97], v[162:165], v[210:213], v[94:97]
	v_mfma_f32_16x16x32_bf16 v[86:89], v[170:173], v[210:213], v[86:89]
	v_mfma_f32_16x16x32_bf16 v[78:81], v[162:165], v[218:221], v[78:81]
	v_mfma_f32_16x16x32_bf16 v[70:73], v[170:173], v[218:221], v[70:73]
	s_setprio 0
	s_barrier
; #define PG8_STAGE(bufoff, gbase, voff) do { _Pragma("unroll") for (int _i = 0; _i < 2; ++_i) \
;         __builtin_amdgcn_global_load_lds((const unsigned*)((const char*)(gbase) + (voff)[_i]), (LAS unsigned*)(lds + (bufoff) + ldsw + _i * 8192), 16, 0, 0); } while (0)
; #define PG8_LDA(dst, b, h) do { _Pragma("unroll") for (int m = 0; m < 4; ++m) _Pragma("unroll") for (int k = 0; k < 2; ++k) dst[m][k] = *(const LAS bf16x8*)(lds + PG8_SA(b, h) + aoff + m * 2048 + k * 1024); } while (0)
; #define PG8_MMA(ai, bj, At, Bt) do { __builtin_amdgcn_s_setprio(1); _Pragma("unroll") for (int m = 0; m < 4; ++m) _Pragma("unroll") for (int n = 0; n < 2; ++n) _Pragma("unroll") for (int k = 0; k < 2; ++k) \
;         acc[ai][bj][m][n] = __builtin_amdgcn_mfma_f32_16x16x32_bf16(Bt[n][k], At[m][k], acc[ai][bj][m][n], 0, 0, 0); __builtin_amdgcn_s_setprio(0); } while (0)
; #define PG8_WAIT_V(n) asm volatile("s_waitcnt vmcnt(" #n ")" ::: "memory")
; #define PG8_WAIT_L(n) asm volatile("s_waitcnt lgkmcnt(" #n ")" ::: "memory")
; #define PG8_BAR __builtin_amdgcn_s_barrier()
; #define PG8_SCHED __builtin_amdgcn_sched_barrier(0)
; template <class Epi, class Pre, bool AG = false>
; __device__ __forceinline__ void gemm_phase(LAS unsigned char* lds, const Gemm g, const StaticOrder& S, const Epi& E, const Pre& P) {
;     ...
;             PG8_LDA(At, 1, 1); PG8_STAGE(PG8_SB(1, 0), b3, voffB); PG8_STAGE(PG8_SB(1, 1), b3 + hstep, voffB); PG8_STAGE(PG8_SA(1, 0), a3, voffA);
;             PG8_WAIT_V(8); PG8_WAIT_L(0); PG8_BAR; PG8_MMA(1, 0, At, B0); PG8_MMA(1, 1, At, B1); PG8_BAR; PG8_SCHED;
;         }
	s_add_i32 s54, s84, s31
	v_lshl_add_u64 v[178:179], v[178:179], 0, s[66:67]
	s_mov_b32 m0, s54
	ds_read_b128 v[174:177], v149 offset:49152
	ds_read_b128 v[194:197], v149 offset:50176
	ds_read_b128 v[198:201], v149 offset:51200
	ds_read_b128 v[202:205], v149 offset:52224
	ds_read_b128 v[206:209], v149 offset:53248
	ds_read_b128 v[210:213], v149 offset:54272
	ds_read_b128 v[214:217], v149 offset:55296
	ds_read_b128 v[218:221], v149 offset:56320
	global_load_lds_dwordx4 v[178:179], off
	s_add_i32 m0, s54, 0x2000
	s_add_u32 s46, s46, 0x40080
	v_lshl_add_u64 v[178:179], v[180:181], 0, s[66:67]
	s_addc_u32 s47, s47, 0
	s_add_i32 s54, s85, s31
	global_load_lds_dwordx4 v[178:179], off
	v_lshl_add_u64 v[178:179], s[46:47], 0, v[134:135]
	s_mov_b32 m0, s54
	s_nop 0
	global_load_lds_dwordx4 v[178:179], off
	v_lshl_add_u64 v[178:179], s[46:47], 0, v[130:131]
	s_add_i32 m0, s54, 0x2000
	s_nop 0
	global_load_lds_dwordx4 v[178:179], off
	v_lshl_add_u64 v[178:179], v[182:183], 0, s[66:67]
	s_mov_b32 m0, s58
	s_nop 0
	global_load_lds_dwordx4 v[178:179], off
	v_lshl_add_u64 v[178:179], v[188:189], 0, s[66:67]
	s_mov_b32 m0, s59
	s_nop 0
	global_load_lds_dwordx4 v[178:179], off
	s_waitcnt vmcnt(8)
	s_waitcnt lgkmcnt(0)
	s_barrier
	s_setprio 1
	v_mfma_f32_16x16x32_bf16 v[58:61], v[140:143], v[174:177], v[58:61]
	v_mfma_f32_16x16x32_bf16 v[50:53], v[150:153], v[174:177], v[50:53]
	v_mfma_f32_16x16x32_bf16 v[42:45], v[140:143], v[198:201], v[42:45]
	v_mfma_f32_16x16x32_bf16 v[34:37], v[150:153], v[198:201], v[34:37]
	v_mfma_f32_16x16x32_bf16 v[26:29], v[140:143], v[206:209], v[26:29]
	v_mfma_f32_16x16x32_bf16 v[18:21], v[150:153], v[206:209], v[18:21]
	v_mfma_f32_16x16x32_bf16 v[10:13], v[140:143], v[214:217], v[10:13]
	v_mfma_f32_16x16x32_bf16 v[6:9], v[150:153], v[214:217], v[6:9]
	v_mfma_f32_16x16x32_bf16 v[58:61], v[144:147], v[194:197], v[58:61]
	v_mfma_f32_16x16x32_bf16 v[50:53], v[154:157], v[194:197], v[50:53]
	v_mfma_f32_16x16x32_bf16 v[42:45], v[144:147], v[202:205], v[42:45]
	v_mfma_f32_16x16x32_bf16 v[34:37], v[154:157], v[202:205], v[34:37]
	v_mfma_f32_16x16x32_bf16 v[26:29], v[144:147], v[210:213], v[26:29]
	v_mfma_f32_16x16x32_bf16 v[18:21], v[154:157], v[210:213], v[18:21]
	v_mfma_f32_16x16x32_bf16 v[10:13], v[144:147], v[218:221], v[10:13]
	v_mfma_f32_16x16x32_bf16 v[6:9], v[154:157], v[218:221], v[6:9]
	v_mfma_f32_16x16x32_bf16 v[62:65], v[158:161], v[174:177], v[62:65]
	v_mfma_f32_16x16x32_bf16 v[54:57], v[166:169], v[174:177], v[54:57]
	v_mfma_f32_16x16x32_bf16 v[46:49], v[158:161], v[198:201], v[46:49]
	v_mfma_f32_16x16x32_bf16 v[38:41], v[166:169], v[198:201], v[38:41]
	v_mfma_f32_16x16x32_bf16 v[30:33], v[158:161], v[206:209], v[30:33]
	v_mfma_f32_16x16x32_bf16 v[22:25], v[166:169], v[206:209], v[22:25]
	v_mfma_f32_16x16x32_bf16 v[14:17], v[158:161], v[214:217], v[14:17]
	v_mfma_f32_16x16x32_bf16 v[2:5], v[166:169], v[214:217], v[2:5]
	v_mfma_f32_16x16x32_bf16 v[62:65], v[162:165], v[194:197], v[62:65]
	v_mfma_f32_16x16x32_bf16 v[54:57], v[170:173], v[194:197], v[54:57]
	v_mfma_f32_16x16x32_bf16 v[46:49], v[162:165], v[202:205], v[46:49]
	v_mfma_f32_16x16x32_bf16 v[38:41], v[170:173], v[202:205], v[38:41]
	v_mfma_f32_16x16x32_bf16 v[30:33], v[162:165], v[210:213], v[30:33]
	v_mfma_f32_16x16x32_bf16 v[22:25], v[170:173], v[210:213], v[22:25]
	v_mfma_f32_16x16x32_bf16 v[14:17], v[162:165], v[218:221], v[14:17]
	v_mfma_f32_16x16x32_bf16 v[2:5], v[170:173], v[218:221], v[2:5]
	s_setprio 0
	s_barrier
	s_add_i32 s79, s79, 2
	s_add_u32 s44, s44, 0x100
	s_addc_u32 s45, s45, 0
	s_add_u32 s76, s76, 0x100
	s_addc_u32 s77, s77, 0
	s_cmp_gt_u32 s79, 13
	s_cbranch_scc0 .LBB0_212

; #define PG8_STAGE(bufoff, gbase, voff) do { _Pragma("unroll") for (int _i = 0; _i < 2; ++_i) \
;         __builtin_amdgcn_global_load_lds((const unsigned*)((const char*)(gbase) + (voff)[_i]), (LAS unsigned*)(lds + (bufoff) + ldsw + _i * 8192), 16, 0, 0); } while (0)
; #define PG8_LDA(dst, b, h) do { _Pragma("unroll") for (int m = 0; m < 4; ++m) _Pragma("unroll") for (int k = 0; k < 2; ++k) dst[m][k] = *(const LAS bf16x8*)(lds + PG8_SA(b, h) + aoff + m * 2048 + k * 1024); } while (0)
; #define PG8_LDB(dst, b, h) do { _Pragma("unroll") for (int n = 0; n < 2; ++n) _Pragma("unroll") for (int k = 0; k < 2; ++k) dst[n][k] = *(const LAS bf16x8*)(lds + PG8_SB(b, h) + boff + n * 2048 + k * 1024); } while (0)
; #define PG8_MMA(ai, bj, At, Bt) do { __builtin_amdgcn_s_setprio(1); _Pragma("unroll") for (int m = 0; m < 4; ++m) _Pragma("unroll") for (int n = 0; n < 2; ++n) _Pragma("unroll") for (int k = 0; k < 2; ++k) \
;         acc[ai][bj][m][n] = __builtin_amdgcn_mfma_f32_16x16x32_bf16(Bt[n][k], At[m][k], acc[ai][bj][m][n], 0, 0, 0); __builtin_amdgcn_s_setprio(0); } while (0)
; #define PG8_WAIT_V(n) asm volatile("s_waitcnt vmcnt(" #n ")" ::: "memory")
; #define PG8_WAIT_L(n) asm volatile("s_waitcnt lgkmcnt(" #n ")" ::: "memory")
; #define PG8_BAR __builtin_amdgcn_s_barrier()
; template <class Epi, class Pre, bool AG = false>
; __device__ __forceinline__ void gemm_phase(LAS unsigned char* lds, const Gemm g, const StaticOrder& S, const Epi& E, const Pre& P) {
;     ...
;             const bool last = (t == nt - 2);
;             const char* a1 = cA + (size_t)(t + 1) * kstepA;
;             const char* a2 = last ? nA : cA + (size_t)(t + 2) * kstepA; const char* b2 = last ? nB : cB + (size_t)(t + 2) * kstep;
;             const char* a3 = a2 + kstepA; const char* b3 = b2 + kstep;
;             if constexpr (Epi::MIDK) { if (t == E.midk_t) E.mid(acc, cur, ui, wr, wc, fr, fq); }
;             PG8_LDB(B0, 0, 0); PG8_LDB(B1, 0, 1); PG8_SCHED; PG8_LDA(At, 0, 0); PG8_STAGE(PG8_SA(1, 1), a1 + hstepA, voffA);
;             PG8_WAIT_V(8); PG8_WAIT_L(0); PG8_BAR; PG8_MMA(0, 0, At, B0); PG8_MMA(0, 1, At, B1); PG8_BAR; PG8_SCHED;
;             PG8_LDA(At, 0, 1); PG8_STAGE(PG8_SB(0, 0), b2, voffB); PG8_STAGE(PG8_SB(0, 1), b2 + hstep, voffB); PG8_STAGE(PG8_SA(0, 0), a2, voffA);
;             PG8_WAIT_V(8); PG8_WAIT_L(0); PG8_BAR; PG8_MMA(1, 0, At, B0); PG8_MMA(1, 1, At, B1); PG8_BAR; PG8_SCHED;
.LBB0_380:
	s_add_u32 s10, s54, 0x100
	s_addc_u32 s11, s55, 0
	s_add_i32 s86, 0, 0x10000
	s_cmp_eq_u32 s85, 40
	s_cselect_b32 s59, s45, s11
	s_cselect_b32 s58, s44, s10
	s_cselect_b32 s57, s47, s84
	s_cselect_b32 s56, s46, s79
	s_add_i32 s87, 0, 0x14000
	v_add_u32_e32 v134, s86, v198
	v_add_u32_e32 v168, s87, v198
	ds_read_b128 v[114:117], v134
	ds_read_b128 v[118:121], v134 offset:1024
	ds_read_b128 v[122:125], v134 offset:2048
	ds_read_b128 v[134:137], v134 offset:3072
	ds_read_b128 v[146:149], v168
	ds_read_b128 v[150:153], v168 offset:1024
	ds_read_b128 v[164:167], v168 offset:2048
	ds_read_b128 v[168:171], v168 offset:3072
	v_lshl_add_u64 v[176:177], s[54:55], 0, v[160:161]
	s_add_i32 m0, s30, 0xc000
	ds_read_b128 v[172:175], v199
	ds_read_b128 v[194:197], v199 offset:1024
	ds_read_b128 v[200:203], v199 offset:2048
	ds_read_b128 v[204:207], v199 offset:3072
	ds_read_b128 v[208:211], v199 offset:4096
	ds_read_b128 v[212:215], v199 offset:5120
	ds_read_b128 v[216:219], v199 offset:6144
	ds_read_b128 v[220:223], v199 offset:7168
	global_load_lds_dwordx4 v[176:177], off
	v_lshl_add_u64 v[176:177], s[54:55], 0, v[162:163]
	s_add_i32 m0, s30, 0xe000
	s_nop 0
	global_load_lds_dwordx4 v[176:177], off
	s_waitcnt vmcnt(8)
	s_waitcnt lgkmcnt(0)
	s_barrier
	s_setprio 1
	v_mfma_f32_16x16x32_bf16 v[142:145], v[114:117], v[172:175], v[142:145]
	v_mfma_f32_16x16x32_bf16 v[138:141], v[122:125], v[172:175], v[138:141]
	v_mfma_f32_16x16x32_bf16 v[110:113], v[114:117], v[200:203], v[110:113]
	v_mfma_f32_16x16x32_bf16 v[106:109], v[122:125], v[200:203], v[106:109]
	v_mfma_f32_16x16x32_bf16 v[94:97], v[114:117], v[208:211], v[94:97]
	v_mfma_f32_16x16x32_bf16 v[90:93], v[122:125], v[208:211], v[90:93]
	v_mfma_f32_16x16x32_bf16 v[78:81], v[114:117], v[216:219], v[78:81]
	v_mfma_f32_16x16x32_bf16 v[74:77], v[122:125], v[216:219], v[74:77]
	v_mfma_f32_16x16x32_bf16 v[142:145], v[118:121], v[194:197], v[142:145]
	v_mfma_f32_16x16x32_bf16 v[138:141], v[134:137], v[194:197], v[138:141]
	v_mfma_f32_16x16x32_bf16 v[110:113], v[118:121], v[204:207], v[110:113]
	v_mfma_f32_16x16x32_bf16 v[106:109], v[134:137], v[204:207], v[106:109]
	v_mfma_f32_16x16x32_bf16 v[94:97], v[118:121], v[212:215], v[94:97]
	v_mfma_f32_16x16x32_bf16 v[90:93], v[134:137], v[212:215], v[90:93]
	v_mfma_f32_16x16x32_bf16 v[78:81], v[118:121], v[220:223], v[78:81]
	v_mfma_f32_16x16x32_bf16 v[74:77], v[134:137], v[220:223], v[74:77]
	v_mfma_f32_16x16x32_bf16 v[130:133], v[146:149], v[172:175], v[130:133]
	v_mfma_f32_16x16x32_bf16 v[126:129], v[164:167], v[172:175], v[126:129]
	v_mfma_f32_16x16x32_bf16 v[102:105], v[146:149], v[200:203], v[102:105]
	v_mfma_f32_16x16x32_bf16 v[98:101], v[164:167], v[200:203], v[98:101]
	v_mfma_f32_16x16x32_bf16 v[86:89], v[146:149], v[208:211], v[86:89]
	v_mfma_f32_16x16x32_bf16 v[82:85], v[164:167], v[208:211], v[82:85]
	v_mfma_f32_16x16x32_bf16 v[70:73], v[146:149], v[216:219], v[70:73]
	v_mfma_f32_16x16x32_bf16 v[66:69], v[164:167], v[216:219], v[66:69]
	v_mfma_f32_16x16x32_bf16 v[130:133], v[150:153], v[194:197], v[130:133]
	v_mfma_f32_16x16x32_bf16 v[126:129], v[168:171], v[194:197], v[126:129]
	v_mfma_f32_16x16x32_bf16 v[102:105], v[150:153], v[204:207], v[102:105]
	v_mfma_f32_16x16x32_bf16 v[98:101], v[168:171], v[204:207], v[98:101]
	v_mfma_f32_16x16x32_bf16 v[86:89], v[150:153], v[212:215], v[86:89]
	v_mfma_f32_16x16x32_bf16 v[82:85], v[168:171], v[212:215], v[82:85]
	v_mfma_f32_16x16x32_bf16 v[70:73], v[150:153], v[220:223], v[70:73]
	v_mfma_f32_16x16x32_bf16 v[66:69], v[168:171], v[220:223], v[66:69]
	s_setprio 0
	s_barrier
	s_add_i32 s54, s86, s25
	v_lshl_add_u64 v[176:177], s[56:57], 0, v[0:1]
	s_mov_b32 m0, s54
	ds_read_b128 v[172:175], v199 offset:16384
	ds_read_b128 v[194:197], v199 offset:17408
	ds_read_b128 v[200:203], v199 offset:18432
	ds_read_b128 v[204:207], v199 offset:19456
	ds_read_b128 v[208:211], v199 offset:20480
	ds_read_b128 v[212:215], v199 offset:21504
	ds_read_b128 v[216:219], v199 offset:22528
	ds_read_b128 v[220:223], v199 offset:23552
	global_load_lds_dwordx4 v[176:177], off
	s_add_i32 m0, s54, 0x2000
	s_add_u32 s54, s56, 0xb0000
	v_lshl_add_u64 v[178:179], s[56:57], 0, v[154:155]
	s_addc_u32 s55, s57, 0
	s_add_i32 s86, s87, s25
	global_load_lds_dwordx4 v[178:179], off
	v_lshl_add_u64 v[180:181], s[54:55], 0, v[0:1]
	s_mov_b32 m0, s86
	v_lshl_add_u64 v[182:183], s[58:59], 0, v[156:157]
	global_load_lds_dwordx4 v[180:181], off
	v_lshl_add_u64 v[180:181], s[54:55], 0, v[154:155]
	s_add_i32 m0, s86, 0x2000
	s_nop 0
	global_load_lds_dwordx4 v[180:181], off
	v_lshl_add_u64 v[180:181], s[58:59], 0, v[158:159]
	s_mov_b32 m0, s30
	s_nop 0
	global_load_lds_dwordx4 v[180:181], off
	s_mov_b32 m0, s31
	s_nop 0
	global_load_lds_dwordx4 v[182:183], off
	s_waitcnt vmcnt(8)
	s_waitcnt lgkmcnt(0)
	s_barrier
; #define PG8_STAGE(bufoff, gbase, voff) do { _Pragma("unroll") for (int _i = 0; _i < 2; ++_i) \
;         __builtin_amdgcn_global_load_lds((const unsigned*)((const char*)(gbase) + (voff)[_i]), (LAS unsigned*)(lds + (bufoff) + ldsw + _i * 8192), 16, 0, 0); } while (0)
; #define PG8_LDA(dst, b, h) do { _Pragma("unroll") for (int m = 0; m < 4; ++m) _Pragma("unroll") for (int k = 0; k < 2; ++k) dst[m][k] = *(const LAS bf16x8*)(lds + PG8_SA(b, h) + aoff + m * 2048 + k * 1024); } while (0)
; #define PG8_LDB(dst, b, h) do { _Pragma("unroll") for (int n = 0; n < 2; ++n) _Pragma("unroll") for (int k = 0; k < 2; ++k) dst[n][k] = *(const LAS bf16x8*)(lds + PG8_SB(b, h) + boff + n * 2048 + k * 1024); } while (0)
; #define PG8_MMA(ai, bj, At, Bt) do { __builtin_amdgcn_s_setprio(1); _Pragma("unroll") for (int m = 0; m < 4; ++m) _Pragma("unroll") for (int n = 0; n < 2; ++n) _Pragma("unroll") for (int k = 0; k < 2; ++k) \
;         acc[ai][bj][m][n] = __builtin_amdgcn_mfma_f32_16x16x32_bf16(Bt[n][k], At[m][k], acc[ai][bj][m][n], 0, 0, 0); __builtin_amdgcn_s_setprio(0); } while (0)
; #define PG8_WAIT_V(n) asm volatile("s_waitcnt vmcnt(" #n ")" ::: "memory")
; #define PG8_WAIT_L(n) asm volatile("s_waitcnt lgkmcnt(" #n ")" ::: "memory")
; #define PG8_BAR __builtin_amdgcn_s_barrier()
; #define PG8_SCHED __builtin_amdgcn_sched_barrier(0)
; template <class Epi, class Pre, bool AG = false>
; __device__ __forceinline__ void gemm_phase(LAS unsigned char* lds, const Gemm g, const StaticOrder& S, const Epi& E, const Pre& P) {
;     ...
;             PG8_WAIT_V(8); PG8_WAIT_L(0); PG8_BAR; PG8_MMA(1, 0, At, B0); PG8_MMA(1, 1, At, B1); PG8_BAR; PG8_SCHED;
;             PG8_LDB(B0, 1, 0); PG8_LDB(B1, 1, 1); PG8_SCHED; PG8_LDA(At, 1, 0); PG8_STAGE(PG8_SA(0, 1), a2 + hstepA, voffA);
;             PG8_WAIT_V(8); PG8_WAIT_L(0); PG8_BAR; PG8_MMA(0, 0, At, B0); PG8_MMA(0, 1, At, B1); PG8_BAR; PG8_SCHED;
	s_setprio 1
	v_mfma_f32_16x16x32_bf16 v[62:65], v[114:117], v[172:175], v[62:65]
	v_mfma_f32_16x16x32_bf16 v[58:61], v[122:125], v[172:175], v[58:61]
	v_mfma_f32_16x16x32_bf16 v[46:49], v[114:117], v[200:203], v[46:49]
	v_mfma_f32_16x16x32_bf16 v[42:45], v[122:125], v[200:203], v[42:45]
	v_mfma_f32_16x16x32_bf16 v[30:33], v[114:117], v[208:211], v[30:33]
	v_mfma_f32_16x16x32_bf16 v[26:29], v[122:125], v[208:211], v[26:29]
	v_mfma_f32_16x16x32_bf16 v[14:17], v[114:117], v[216:219], v[14:17]
	v_mfma_f32_16x16x32_bf16 v[10:13], v[122:125], v[216:219], v[10:13]
	v_mfma_f32_16x16x32_bf16 v[62:65], v[118:121], v[194:197], v[62:65]
	v_mfma_f32_16x16x32_bf16 v[58:61], v[134:137], v[194:197], v[58:61]
	v_mfma_f32_16x16x32_bf16 v[46:49], v[118:121], v[204:207], v[46:49]
	v_mfma_f32_16x16x32_bf16 v[42:45], v[134:137], v[204:207], v[42:45]
	v_mfma_f32_16x16x32_bf16 v[30:33], v[118:121], v[212:215], v[30:33]
	v_mfma_f32_16x16x32_bf16 v[26:29], v[134:137], v[212:215], v[26:29]
	v_mfma_f32_16x16x32_bf16 v[14:17], v[118:121], v[220:223], v[14:17]
	v_mfma_f32_16x16x32_bf16 v[10:13], v[134:137], v[220:223], v[10:13]
	v_mfma_f32_16x16x32_bf16 v[54:57], v[146:149], v[172:175], v[54:57]
	v_mfma_f32_16x16x32_bf16 v[50:53], v[164:167], v[172:175], v[50:53]
	v_mfma_f32_16x16x32_bf16 v[38:41], v[146:149], v[200:203], v[38:41]
	v_mfma_f32_16x16x32_bf16 v[34:37], v[164:167], v[200:203], v[34:37]
	v_mfma_f32_16x16x32_bf16 v[22:25], v[146:149], v[208:211], v[22:25]
	v_mfma_f32_16x16x32_bf16 v[18:21], v[164:167], v[208:211], v[18:21]
	v_mfma_f32_16x16x32_bf16 v[6:9], v[146:149], v[216:219], v[6:9]
	v_mfma_f32_16x16x32_bf16 v[2:5], v[164:167], v[216:219], v[2:5]
	v_mfma_f32_16x16x32_bf16 v[54:57], v[150:153], v[194:197], v[54:57]
	v_mfma_f32_16x16x32_bf16 v[50:53], v[168:171], v[194:197], v[50:53]
	v_mfma_f32_16x16x32_bf16 v[38:41], v[150:153], v[204:207], v[38:41]
	v_mfma_f32_16x16x32_bf16 v[34:37], v[168:171], v[204:207], v[34:37]
	v_mfma_f32_16x16x32_bf16 v[22:25], v[150:153], v[212:215], v[22:25]
	v_mfma_f32_16x16x32_bf16 v[18:21], v[168:171], v[212:215], v[18:21]
	v_mfma_f32_16x16x32_bf16 v[6:9], v[150:153], v[220:223], v[6:9]
	v_mfma_f32_16x16x32_bf16 v[2:5], v[168:171], v[220:223], v[2:5]
	s_setprio 0
	s_barrier
	s_add_i32 s86, 0, 0x18000
	s_add_i32 s87, 0, 0x1c000
	v_add_u32_e32 v134, s86, v198
	v_add_u32_e32 v168, s87, v198
	ds_read_b128 v[114:117], v134
	ds_read_b128 v[118:121], v134 offset:1024
	ds_read_b128 v[122:125], v134 offset:2048
	ds_read_b128 v[134:137], v134 offset:3072
	ds_read_b128 v[146:149], v168
	ds_read_b128 v[150:153], v168 offset:1024
	ds_read_b128 v[164:167], v168 offset:2048
	ds_read_b128 v[168:171], v168 offset:3072
	s_add_u32 s54, s58, 0xb0000
	s_addc_u32 s55, s59, 0
	s_mov_b32 m0, s38
	v_lshl_add_u64 v[188:189], s[54:55], 0, v[158:159]
	ds_read_b128 v[172:175], v199 offset:32768
	ds_read_b128 v[194:197], v199 offset:33792
	ds_read_b128 v[200:203], v199 offset:34816
	ds_read_b128 v[204:207], v199 offset:35840
	ds_read_b128 v[208:211], v199 offset:36864
	ds_read_b128 v[212:215], v199 offset:37888
	ds_read_b128 v[216:219], v199 offset:38912
	ds_read_b128 v[220:223], v199 offset:39936
	global_load_lds_dwordx4 v[188:189], off
	v_lshl_add_u64 v[188:189], s[54:55], 0, v[156:157]
	s_mov_b32 m0, s48
	s_nop 0
	global_load_lds_dwordx4 v[188:189], off
	s_waitcnt vmcnt(8)
	s_waitcnt lgkmcnt(0)
	s_barrier
	s_setprio 1
	v_mfma_f32_16x16x32_bf16 v[142:145], v[114:117], v[172:175], v[142:145]
	v_mfma_f32_16x16x32_bf16 v[138:141], v[122:125], v[172:175], v[138:141]
	v_mfma_f32_16x16x32_bf16 v[110:113], v[114:117], v[200:203], v[110:113]
	v_mfma_f32_16x16x32_bf16 v[106:109], v[122:125], v[200:203], v[106:109]
	v_mfma_f32_16x16x32_bf16 v[94:97], v[114:117], v[208:211], v[94:97]
	v_mfma_f32_16x16x32_bf16 v[90:93], v[122:125], v[208:211], v[90:93]
	v_mfma_f32_16x16x32_bf16 v[78:81], v[114:117], v[216:219], v[78:81]
	v_mfma_f32_16x16x32_bf16 v[74:77], v[122:125], v[216:219], v[74:77]
	v_mfma_f32_16x16x32_bf16 v[142:145], v[118:121], v[194:197], v[142:145]
	v_mfma_f32_16x16x32_bf16 v[138:141], v[134:137], v[194:197], v[138:141]
	v_mfma_f32_16x16x32_bf16 v[110:113], v[118:121], v[204:207], v[110:113]
	v_mfma_f32_16x16x32_bf16 v[106:109], v[134:137], v[204:207], v[106:109]
	v_mfma_f32_16x16x32_bf16 v[94:97], v[118:121], v[212:215], v[94:97]
	v_mfma_f32_16x16x32_bf16 v[90:93], v[134:137], v[212:215], v[90:93]
	v_mfma_f32_16x16x32_bf16 v[78:81], v[118:121], v[220:223], v[78:81]
	v_mfma_f32_16x16x32_bf16 v[74:77], v[134:137], v[220:223], v[74:77]
	v_mfma_f32_16x16x32_bf16 v[130:133], v[146:149], v[172:175], v[130:133]
	v_mfma_f32_16x16x32_bf16 v[126:129], v[164:167], v[172:175], v[126:129]
	v_mfma_f32_16x16x32_bf16 v[102:105], v[146:149], v[200:203], v[102:105]
	v_mfma_f32_16x16x32_bf16 v[98:101], v[164:167], v[200:203], v[98:101]
	v_mfma_f32_16x16x32_bf16 v[86:89], v[146:149], v[208:211], v[86:89]
	v_mfma_f32_16x16x32_bf16 v[82:85], v[164:167], v[208:211], v[82:85]
	v_mfma_f32_16x16x32_bf16 v[70:73], v[146:149], v[216:219], v[70:73]
	v_mfma_f32_16x16x32_bf16 v[66:69], v[164:167], v[216:219], v[66:69]
	v_mfma_f32_16x16x32_bf16 v[130:133], v[150:153], v[194:197], v[130:133]
	v_mfma_f32_16x16x32_bf16 v[126:129], v[168:171], v[194:197], v[126:129]
	v_mfma_f32_16x16x32_bf16 v[102:105], v[150:153], v[204:207], v[102:105]
	v_mfma_f32_16x16x32_bf16 v[98:101], v[168:171], v[204:207], v[98:101]
	v_mfma_f32_16x16x32_bf16 v[86:89], v[150:153], v[212:215], v[86:89]
	v_mfma_f32_16x16x32_bf16 v[82:85], v[168:171], v[212:215], v[82:85]
	v_mfma_f32_16x16x32_bf16 v[70:73], v[150:153], v[220:223], v[70:73]
	v_mfma_f32_16x16x32_bf16 v[66:69], v[168:171], v[220:223], v[66:69]
	s_setprio 0
	s_barrier
; #define PG8_STAGE(bufoff, gbase, voff) do { _Pragma("unroll") for (int _i = 0; _i < 2; ++_i) \
;         __builtin_amdgcn_global_load_lds((const unsigned*)((const char*)(gbase) + (voff)[_i]), (LAS unsigned*)(lds + (bufoff) + ldsw + _i * 8192), 16, 0, 0); } while (0)
; #define PG8_LDA(dst, b, h) do { _Pragma("unroll") for (int m = 0; m < 4; ++m) _Pragma("unroll") for (int k = 0; k < 2; ++k) dst[m][k] = *(const LAS bf16x8*)(lds + PG8_SA(b, h) + aoff + m * 2048 + k * 1024); } while (0)
; #define PG8_MMA(ai, bj, At, Bt) do { __builtin_amdgcn_s_setprio(1); _Pragma("unroll") for (int m = 0; m < 4; ++m) _Pragma("unroll") for (int n = 0; n < 2; ++n) _Pragma("unroll") for (int k = 0; k < 2; ++k) \
;         acc[ai][bj][m][n] = __builtin_amdgcn_mfma_f32_16x16x32_bf16(Bt[n][k], At[m][k], acc[ai][bj][m][n], 0, 0, 0); __builtin_amdgcn_s_setprio(0); } while (0)
; #define PG8_WAIT_V(n) asm volatile("s_waitcnt vmcnt(" #n ")" ::: "memory")
; #define PG8_WAIT_L(n) asm volatile("s_waitcnt lgkmcnt(" #n ")" ::: "memory")
; #define PG8_BAR __builtin_amdgcn_s_barrier()
; #define PG8_SCHED __builtin_amdgcn_sched_barrier(0)
; template <class Epi, class Pre, bool AG = false>
; __device__ __forceinline__ void gemm_phase(LAS unsigned char* lds, const Gemm g, const StaticOrder& S, const Epi& E, const Pre& P) {
;     ...
;             PG8_LDA(At, 1, 1); PG8_STAGE(PG8_SB(1, 0), b3, voffB); PG8_STAGE(PG8_SB(1, 1), b3 + hstep, voffB); PG8_STAGE(PG8_SA(1, 0), a3, voffA);
;             PG8_WAIT_V(8); PG8_WAIT_L(0); PG8_BAR; PG8_MMA(1, 0, At, B0); PG8_MMA(1, 1, At, B1); PG8_BAR; PG8_SCHED;
;         }
;         if (wr == 0) PG8_BAR;
	s_add_i32 s54, s86, s25
	v_lshl_add_u64 v[176:177], v[176:177], 0, s[66:67]
	s_mov_b32 m0, s54
	ds_read_b128 v[172:175], v199 offset:49152
	ds_read_b128 v[194:197], v199 offset:50176
	ds_read_b128 v[200:203], v199 offset:51200
	ds_read_b128 v[204:207], v199 offset:52224
	ds_read_b128 v[208:211], v199 offset:53248
	ds_read_b128 v[212:215], v199 offset:54272
	ds_read_b128 v[216:219], v199 offset:55296
	ds_read_b128 v[220:223], v199 offset:56320
	global_load_lds_dwordx4 v[176:177], off
	s_add_i32 m0, s54, 0x2000
	s_add_u32 s54, s56, 0xb0080
	v_lshl_add_u64 v[176:177], v[178:179], 0, s[66:67]
	s_addc_u32 s55, s57, 0
	s_add_i32 s56, s87, s25
	global_load_lds_dwordx4 v[176:177], off
	v_lshl_add_u64 v[176:177], s[54:55], 0, v[0:1]
	s_mov_b32 m0, s56
	s_nop 0
	global_load_lds_dwordx4 v[176:177], off
	v_lshl_add_u64 v[176:177], s[54:55], 0, v[154:155]
	s_add_i32 m0, s56, 0x2000
	s_nop 0
	global_load_lds_dwordx4 v[176:177], off
	v_lshl_add_u64 v[176:177], v[180:181], 0, s[66:67]
	s_mov_b32 m0, s61
	s_nop 0
	global_load_lds_dwordx4 v[176:177], off
	v_lshl_add_u64 v[176:177], v[182:183], 0, s[66:67]
	s_mov_b32 m0, s70
	s_nop 0
	global_load_lds_dwordx4 v[176:177], off
	s_waitcnt vmcnt(8)
	s_waitcnt lgkmcnt(0)
	s_barrier
	s_setprio 1
	v_mfma_f32_16x16x32_bf16 v[62:65], v[114:117], v[172:175], v[62:65]
	v_mfma_f32_16x16x32_bf16 v[58:61], v[122:125], v[172:175], v[58:61]
	v_mfma_f32_16x16x32_bf16 v[46:49], v[114:117], v[200:203], v[46:49]
	v_mfma_f32_16x16x32_bf16 v[42:45], v[122:125], v[200:203], v[42:45]
	v_mfma_f32_16x16x32_bf16 v[30:33], v[114:117], v[208:211], v[30:33]
	v_mfma_f32_16x16x32_bf16 v[26:29], v[122:125], v[208:211], v[26:29]
	v_mfma_f32_16x16x32_bf16 v[14:17], v[114:117], v[216:219], v[14:17]
	v_mfma_f32_16x16x32_bf16 v[10:13], v[122:125], v[216:219], v[10:13]
	v_mfma_f32_16x16x32_bf16 v[62:65], v[118:121], v[194:197], v[62:65]
	v_mfma_f32_16x16x32_bf16 v[58:61], v[134:137], v[194:197], v[58:61]
	v_mfma_f32_16x16x32_bf16 v[46:49], v[118:121], v[204:207], v[46:49]
	v_mfma_f32_16x16x32_bf16 v[42:45], v[134:137], v[204:207], v[42:45]
	v_mfma_f32_16x16x32_bf16 v[30:33], v[118:121], v[212:215], v[30:33]
	v_mfma_f32_16x16x32_bf16 v[26:29], v[134:137], v[212:215], v[26:29]
	v_mfma_f32_16x16x32_bf16 v[14:17], v[118:121], v[220:223], v[14:17]
	v_mfma_f32_16x16x32_bf16 v[10:13], v[134:137], v[220:223], v[10:13]
	v_mfma_f32_16x16x32_bf16 v[54:57], v[146:149], v[172:175], v[54:57]
	v_mfma_f32_16x16x32_bf16 v[50:53], v[164:167], v[172:175], v[50:53]
	v_mfma_f32_16x16x32_bf16 v[38:41], v[146:149], v[200:203], v[38:41]
	v_mfma_f32_16x16x32_bf16 v[34:37], v[164:167], v[200:203], v[34:37]
	v_mfma_f32_16x16x32_bf16 v[22:25], v[146:149], v[208:211], v[22:25]
	v_mfma_f32_16x16x32_bf16 v[18:21], v[164:167], v[208:211], v[18:21]
	v_mfma_f32_16x16x32_bf16 v[6:9], v[146:149], v[216:219], v[6:9]
	v_mfma_f32_16x16x32_bf16 v[2:5], v[164:167], v[216:219], v[2:5]
	v_mfma_f32_16x16x32_bf16 v[54:57], v[150:153], v[194:197], v[54:57]
	v_mfma_f32_16x16x32_bf16 v[50:53], v[168:171], v[194:197], v[50:53]
	v_mfma_f32_16x16x32_bf16 v[38:41], v[150:153], v[204:207], v[38:41]
	v_mfma_f32_16x16x32_bf16 v[34:37], v[168:171], v[204:207], v[34:37]
	v_mfma_f32_16x16x32_bf16 v[22:25], v[150:153], v[212:215], v[22:25]
	v_mfma_f32_16x16x32_bf16 v[18:21], v[168:171], v[212:215], v[18:21]
	v_mfma_f32_16x16x32_bf16 v[6:9], v[150:153], v[220:223], v[6:9]
	v_mfma_f32_16x16x32_bf16 v[2:5], v[168:171], v[220:223], v[2:5]
	s_setprio 0
	s_barrier
	s_add_i32 s85, s85, 2
	s_add_u32 s79, s79, 0x100
	s_addc_u32 s84, s84, 0
	s_cmp_gt_u32 s85, 41
	s_mov_b64 s[54:55], s[10:11]
	s_cbranch_scc0 .LBB0_380
	s_and_b64 vcc, exec, s[42:43]
	s_cbranch_vccz .LBB0_383
	s_barrier

; #define PG8_STAGE(bufoff, gbase, voff) do { _Pragma("unroll") for (int _i = 0; _i < 2; ++_i) \
;         __builtin_amdgcn_global_load_lds((const unsigned*)((const char*)(gbase) + (voff)[_i]), (LAS unsigned*)(lds + (bufoff) + ldsw + _i * 8192), 16, 0, 0); } while (0)
; #define PG8_LDA(dst, b, h) do { _Pragma("unroll") for (int m = 0; m < 4; ++m) _Pragma("unroll") for (int k = 0; k < 2; ++k) dst[m][k] = *(const LAS bf16x8*)(lds + PG8_SA(b, h) + aoff + m * 2048 + k * 1024); } while (0)
; #define PG8_LDB(dst, b, h) do { _Pragma("unroll") for (int n = 0; n < 2; ++n) _Pragma("unroll") for (int k = 0; k < 2; ++k) dst[n][k] = *(const LAS bf16x8*)(lds + PG8_SB(b, h) + boff + n * 2048 + k * 1024); } while (0)
; #define PG8_MMA(ai, bj, At, Bt) do { __builtin_amdgcn_s_setprio(1); _Pragma("unroll") for (int m = 0; m < 4; ++m) _Pragma("unroll") for (int n = 0; n < 2; ++n) _Pragma("unroll") for (int k = 0; k < 2; ++k) \
;         acc[ai][bj][m][n] = __builtin_amdgcn_mfma_f32_16x16x32_bf16(Bt[n][k], At[m][k], acc[ai][bj][m][n], 0, 0, 0); __builtin_amdgcn_s_setprio(0); } while (0)
; #define PG8_WAIT_V(n) asm volatile("s_waitcnt vmcnt(" #n ")" ::: "memory")
; #define PG8_WAIT_L(n) asm volatile("s_waitcnt lgkmcnt(" #n ")" ::: "memory")
; #define PG8_BAR __builtin_amdgcn_s_barrier()
; template <class Epi, class Pre, bool AG = false>
; __device__ __forceinline__ void gemm_phase(LAS unsigned char* lds, const Gemm g, const StaticOrder& S, const Epi& E, const Pre& P) {
;     ...
;             const bool last = (t == nt - 2);
;             const char* a1 = cA + (size_t)(t + 1) * kstepA;
;             const char* a2 = last ? nA : cA + (size_t)(t + 2) * kstepA; const char* b2 = last ? nB : cB + (size_t)(t + 2) * kstep;
;             const char* a3 = a2 + kstepA; const char* b3 = b2 + kstep;
;             if constexpr (Epi::MIDK) { if (t == E.midk_t) E.mid(acc, cur, ui, wr, wc, fr, fq); }
;             PG8_LDB(B0, 0, 0); PG8_LDB(B1, 0, 1); PG8_SCHED; PG8_LDA(At, 0, 0); PG8_STAGE(PG8_SA(1, 1), a1 + hstepA, voffA);
;             PG8_WAIT_V(8); PG8_WAIT_L(0); PG8_BAR; PG8_MMA(0, 0, At, B0); PG8_MMA(0, 1, At, B1); PG8_BAR; PG8_SCHED;
;             PG8_LDA(At, 0, 1); PG8_STAGE(PG8_SB(0, 0), b2, voffB); PG8_STAGE(PG8_SB(0, 1), b2 + hstep, voffB); PG8_STAGE(PG8_SA(0, 0), a2, voffA);
;             PG8_WAIT_V(8); PG8_WAIT_L(0); PG8_BAR; PG8_MMA(1, 0, At, B0); PG8_MMA(1, 1, At, B1); PG8_BAR; PG8_SCHED;
.LBB0_479:
	s_add_u32 s14, s10, 0xfffc0080
	s_addc_u32 s21, s11, -1
	s_add_i32 vcc_lo, 0, 0x10000
	s_cmp_eq_u32 s87, 12
	s_cselect_b32 s57, s12, s21
	s_cselect_b32 s56, s13, s14
	s_cselect_b32 s55, s45, s86
	s_cselect_b32 s54, s71, s85
	s_add_i32 s14, 0, 0x14000
	v_add_u32_e32 v152, vcc_lo, v164
	v_add_u32_e32 v170, s14, v164
	ds_read_b128 v[130:133], v152
	ds_read_b128 v[134:137], v152 offset:1024
	ds_read_b128 v[148:151], v152 offset:2048
	ds_read_b128 v[152:155], v152 offset:3072
	ds_read_b128 v[156:159], v170
	ds_read_b128 v[160:163], v170 offset:1024
	ds_read_b128 v[166:169], v170 offset:2048
	ds_read_b128 v[170:173], v170 offset:3072
	v_lshl_add_u64 v[182:183], s[10:11], 0, v[0:1]
	s_add_i32 m0, s49, 0xc000
	ds_read_b128 v[174:177], v165
	ds_read_b128 v[178:181], v165 offset:1024
	ds_read_b128 v[188:191], v165 offset:2048
	ds_read_b128 v[194:197], v165 offset:3072
	ds_read_b128 v[198:201], v165 offset:4096
	ds_read_b128 v[202:205], v165 offset:5120
	ds_read_b128 v[206:209], v165 offset:6144
	ds_read_b128 v[210:213], v165 offset:7168
	global_load_lds_dwordx4 v[182:183], off
	v_lshl_add_u64 v[182:183], s[10:11], 0, v[146:147]
	s_add_i32 m0, s49, 0xe000
	s_nop 0
	global_load_lds_dwordx4 v[182:183], off
	s_waitcnt vmcnt(8)
	s_waitcnt lgkmcnt(0)
	s_barrier
	s_setprio 1
	v_mfma_f32_16x16x32_bf16 v[126:129], v[130:133], v[174:177], v[126:129]
	v_mfma_f32_16x16x32_bf16 v[122:125], v[148:151], v[174:177], v[122:125]
	v_mfma_f32_16x16x32_bf16 v[110:113], v[130:133], v[188:191], v[110:113]
	v_mfma_f32_16x16x32_bf16 v[106:109], v[148:151], v[188:191], v[106:109]
	v_mfma_f32_16x16x32_bf16 v[94:97], v[130:133], v[198:201], v[94:97]
	v_mfma_f32_16x16x32_bf16 v[90:93], v[148:151], v[198:201], v[90:93]
	v_mfma_f32_16x16x32_bf16 v[78:81], v[130:133], v[206:209], v[78:81]
	v_mfma_f32_16x16x32_bf16 v[74:77], v[148:151], v[206:209], v[74:77]
	v_mfma_f32_16x16x32_bf16 v[126:129], v[134:137], v[178:181], v[126:129]
	v_mfma_f32_16x16x32_bf16 v[122:125], v[152:155], v[178:181], v[122:125]
	v_mfma_f32_16x16x32_bf16 v[110:113], v[134:137], v[194:197], v[110:113]
	v_mfma_f32_16x16x32_bf16 v[106:109], v[152:155], v[194:197], v[106:109]
	v_mfma_f32_16x16x32_bf16 v[94:97], v[134:137], v[202:205], v[94:97]
	v_mfma_f32_16x16x32_bf16 v[90:93], v[152:155], v[202:205], v[90:93]
	v_mfma_f32_16x16x32_bf16 v[78:81], v[134:137], v[210:213], v[78:81]
	v_mfma_f32_16x16x32_bf16 v[74:77], v[152:155], v[210:213], v[74:77]
	v_mfma_f32_16x16x32_bf16 v[118:121], v[156:159], v[174:177], v[118:121]
	v_mfma_f32_16x16x32_bf16 v[114:117], v[166:169], v[174:177], v[114:117]
	v_mfma_f32_16x16x32_bf16 v[102:105], v[156:159], v[188:191], v[102:105]
	v_mfma_f32_16x16x32_bf16 v[98:101], v[166:169], v[188:191], v[98:101]
	v_mfma_f32_16x16x32_bf16 v[86:89], v[156:159], v[198:201], v[86:89]
	v_mfma_f32_16x16x32_bf16 v[82:85], v[166:169], v[198:201], v[82:85]
	v_mfma_f32_16x16x32_bf16 v[70:73], v[156:159], v[206:209], v[70:73]
	v_mfma_f32_16x16x32_bf16 v[66:69], v[166:169], v[206:209], v[66:69]
	v_mfma_f32_16x16x32_bf16 v[118:121], v[160:163], v[178:181], v[118:121]
	v_mfma_f32_16x16x32_bf16 v[114:117], v[170:173], v[178:181], v[114:117]
	v_mfma_f32_16x16x32_bf16 v[102:105], v[160:163], v[194:197], v[102:105]
	v_mfma_f32_16x16x32_bf16 v[98:101], v[170:173], v[194:197], v[98:101]
	v_mfma_f32_16x16x32_bf16 v[86:89], v[160:163], v[202:205], v[86:89]
	v_mfma_f32_16x16x32_bf16 v[82:85], v[170:173], v[202:205], v[82:85]
	v_mfma_f32_16x16x32_bf16 v[70:73], v[160:163], v[210:213], v[70:73]
	v_mfma_f32_16x16x32_bf16 v[66:69], v[170:173], v[210:213], v[66:69]
	s_setprio 0
	s_barrier
	s_add_i32 s21, vcc_lo, s48
	v_lshl_add_u64 v[182:183], s[54:55], 0, v[142:143]
	s_mov_b32 m0, s21
	ds_read_b128 v[174:177], v165 offset:16384
	ds_read_b128 v[178:181], v165 offset:17408
	ds_read_b128 v[188:191], v165 offset:18432
	ds_read_b128 v[194:197], v165 offset:19456
	ds_read_b128 v[198:201], v165 offset:20480
	ds_read_b128 v[202:205], v165 offset:21504
	ds_read_b128 v[206:209], v165 offset:22528
	ds_read_b128 v[210:213], v165 offset:23552
	global_load_lds_dwordx4 v[182:183], off
	s_add_i32 m0, s21, 0x2000
	s_add_u32 vcc_lo, s54, 0x40000
	v_lshl_add_u64 v[184:185], s[54:55], 0, v[138:139]
	s_addc_u32 vcc_hi, s55, 0
	s_add_i32 s14, s14, s48
	global_load_lds_dwordx4 v[184:185], off
	v_lshl_add_u64 v[186:187], vcc, 0, v[142:143]
	s_mov_b32 m0, s14
	v_lshl_add_u64 v[192:193], s[56:57], 0, v[140:141]
	global_load_lds_dwordx4 v[186:187], off
	v_lshl_add_u64 v[186:187], vcc, 0, v[138:139]
	s_add_i32 m0, s14, 0x2000
	s_nop 0
	global_load_lds_dwordx4 v[186:187], off
	v_lshl_add_u64 v[186:187], s[56:57], 0, v[144:145]
	s_mov_b32 m0, s49
	s_nop 0
	global_load_lds_dwordx4 v[186:187], off
	s_mov_b32 m0, s38
	s_nop 0
	global_load_lds_dwordx4 v[192:193], off
	s_waitcnt vmcnt(8)
	s_waitcnt lgkmcnt(0)
	s_barrier
; #define PG8_STAGE(bufoff, gbase, voff) do { _Pragma("unroll") for (int _i = 0; _i < 2; ++_i) \
;         __builtin_amdgcn_global_load_lds((const unsigned*)((const char*)(gbase) + (voff)[_i]), (LAS unsigned*)(lds + (bufoff) + ldsw + _i * 8192), 16, 0, 0); } while (0)
; #define PG8_LDA(dst, b, h) do { _Pragma("unroll") for (int m = 0; m < 4; ++m) _Pragma("unroll") for (int k = 0; k < 2; ++k) dst[m][k] = *(const LAS bf16x8*)(lds + PG8_SA(b, h) + aoff + m * 2048 + k * 1024); } while (0)
; #define PG8_LDB(dst, b, h) do { _Pragma("unroll") for (int n = 0; n < 2; ++n) _Pragma("unroll") for (int k = 0; k < 2; ++k) dst[n][k] = *(const LAS bf16x8*)(lds + PG8_SB(b, h) + boff + n * 2048 + k * 1024); } while (0)
; #define PG8_MMA(ai, bj, At, Bt) do { __builtin_amdgcn_s_setprio(1); _Pragma("unroll") for (int m = 0; m < 4; ++m) _Pragma("unroll") for (int n = 0; n < 2; ++n) _Pragma("unroll") for (int k = 0; k < 2; ++k) \
;         acc[ai][bj][m][n] = __builtin_amdgcn_mfma_f32_16x16x32_bf16(Bt[n][k], At[m][k], acc[ai][bj][m][n], 0, 0, 0); __builtin_amdgcn_s_setprio(0); } while (0)
; #define PG8_WAIT_V(n) asm volatile("s_waitcnt vmcnt(" #n ")" ::: "memory")
; #define PG8_WAIT_L(n) asm volatile("s_waitcnt lgkmcnt(" #n ")" ::: "memory")
; #define PG8_BAR __builtin_amdgcn_s_barrier()
; #define PG8_SCHED __builtin_amdgcn_sched_barrier(0)
; template <class Epi, class Pre, bool AG = false>
; __device__ __forceinline__ void gemm_phase(LAS unsigned char* lds, const Gemm g, const StaticOrder& S, const Epi& E, const Pre& P) {
;     ...
;             PG8_WAIT_V(8); PG8_WAIT_L(0); PG8_BAR; PG8_MMA(1, 0, At, B0); PG8_MMA(1, 1, At, B1); PG8_BAR; PG8_SCHED;
;             PG8_LDB(B0, 1, 0); PG8_LDB(B1, 1, 1); PG8_SCHED; PG8_LDA(At, 1, 0); PG8_STAGE(PG8_SA(0, 1), a2 + hstepA, voffA);
;             PG8_WAIT_V(8); PG8_WAIT_L(0); PG8_BAR; PG8_MMA(0, 0, At, B0); PG8_MMA(0, 1, At, B1); PG8_BAR; PG8_SCHED;
	s_setprio 1
	v_mfma_f32_16x16x32_bf16 v[62:65], v[130:133], v[174:177], v[62:65]
	v_mfma_f32_16x16x32_bf16 v[58:61], v[148:151], v[174:177], v[58:61]
	v_mfma_f32_16x16x32_bf16 v[46:49], v[130:133], v[188:191], v[46:49]
	v_mfma_f32_16x16x32_bf16 v[42:45], v[148:151], v[188:191], v[42:45]
	v_mfma_f32_16x16x32_bf16 v[30:33], v[130:133], v[198:201], v[30:33]
	v_mfma_f32_16x16x32_bf16 v[26:29], v[148:151], v[198:201], v[26:29]
	v_mfma_f32_16x16x32_bf16 v[14:17], v[130:133], v[206:209], v[14:17]
	v_mfma_f32_16x16x32_bf16 v[10:13], v[148:151], v[206:209], v[10:13]
	v_mfma_f32_16x16x32_bf16 v[62:65], v[134:137], v[178:181], v[62:65]
	v_mfma_f32_16x16x32_bf16 v[58:61], v[152:155], v[178:181], v[58:61]
	v_mfma_f32_16x16x32_bf16 v[46:49], v[134:137], v[194:197], v[46:49]
	v_mfma_f32_16x16x32_bf16 v[42:45], v[152:155], v[194:197], v[42:45]
	v_mfma_f32_16x16x32_bf16 v[30:33], v[134:137], v[202:205], v[30:33]
	v_mfma_f32_16x16x32_bf16 v[26:29], v[152:155], v[202:205], v[26:29]
	v_mfma_f32_16x16x32_bf16 v[14:17], v[134:137], v[210:213], v[14:17]
	v_mfma_f32_16x16x32_bf16 v[10:13], v[152:155], v[210:213], v[10:13]
	v_mfma_f32_16x16x32_bf16 v[54:57], v[156:159], v[174:177], v[54:57]
	v_mfma_f32_16x16x32_bf16 v[50:53], v[166:169], v[174:177], v[50:53]
	v_mfma_f32_16x16x32_bf16 v[38:41], v[156:159], v[188:191], v[38:41]
	v_mfma_f32_16x16x32_bf16 v[34:37], v[166:169], v[188:191], v[34:37]
	v_mfma_f32_16x16x32_bf16 v[22:25], v[156:159], v[198:201], v[22:25]
	v_mfma_f32_16x16x32_bf16 v[18:21], v[166:169], v[198:201], v[18:21]
	v_mfma_f32_16x16x32_bf16 v[6:9], v[156:159], v[206:209], v[6:9]
	v_mfma_f32_16x16x32_bf16 v[2:5], v[166:169], v[206:209], v[2:5]
	v_mfma_f32_16x16x32_bf16 v[54:57], v[160:163], v[178:181], v[54:57]
	v_mfma_f32_16x16x32_bf16 v[50:53], v[170:173], v[178:181], v[50:53]
	v_mfma_f32_16x16x32_bf16 v[38:41], v[160:163], v[194:197], v[38:41]
	v_mfma_f32_16x16x32_bf16 v[34:37], v[170:173], v[194:197], v[34:37]
	v_mfma_f32_16x16x32_bf16 v[22:25], v[160:163], v[202:205], v[22:25]
	v_mfma_f32_16x16x32_bf16 v[18:21], v[170:173], v[202:205], v[18:21]
	v_mfma_f32_16x16x32_bf16 v[6:9], v[160:163], v[210:213], v[6:9]
	v_mfma_f32_16x16x32_bf16 v[2:5], v[170:173], v[210:213], v[2:5]
	s_setprio 0
	s_barrier
	s_add_i32 s14, 0, 0x18000
	s_add_i32 s21, 0, 0x1c000
	v_add_u32_e32 v152, s14, v164
	v_add_u32_e32 v170, s21, v164
	ds_read_b128 v[130:133], v152
	ds_read_b128 v[134:137], v152 offset:1024
	ds_read_b128 v[148:151], v152 offset:2048
	ds_read_b128 v[152:155], v152 offset:3072
	ds_read_b128 v[156:159], v170
	ds_read_b128 v[160:163], v170 offset:1024
	ds_read_b128 v[166:169], v170 offset:2048
	ds_read_b128 v[170:173], v170 offset:3072
	s_add_u32 s56, s56, 0x40000
	s_addc_u32 s57, s57, 0
	s_mov_b32 m0, s58
	v_lshl_add_u64 v[214:215], s[56:57], 0, v[144:145]
	ds_read_b128 v[174:177], v165 offset:32768
	ds_read_b128 v[178:181], v165 offset:33792
	ds_read_b128 v[188:191], v165 offset:34816
	ds_read_b128 v[194:197], v165 offset:35840
	ds_read_b128 v[198:201], v165 offset:36864
	ds_read_b128 v[202:205], v165 offset:37888
	ds_read_b128 v[206:209], v165 offset:38912
	ds_read_b128 v[210:213], v165 offset:39936
	global_load_lds_dwordx4 v[214:215], off
	v_lshl_add_u64 v[214:215], s[56:57], 0, v[140:141]
	s_mov_b32 m0, s59
	s_nop 0
	global_load_lds_dwordx4 v[214:215], off
	s_waitcnt vmcnt(8)
	s_waitcnt lgkmcnt(0)
	s_barrier
	s_setprio 1
	v_mfma_f32_16x16x32_bf16 v[126:129], v[130:133], v[174:177], v[126:129]
	v_mfma_f32_16x16x32_bf16 v[122:125], v[148:151], v[174:177], v[122:125]
	v_mfma_f32_16x16x32_bf16 v[110:113], v[130:133], v[188:191], v[110:113]
	v_mfma_f32_16x16x32_bf16 v[106:109], v[148:151], v[188:191], v[106:109]
	v_mfma_f32_16x16x32_bf16 v[94:97], v[130:133], v[198:201], v[94:97]
	v_mfma_f32_16x16x32_bf16 v[90:93], v[148:151], v[198:201], v[90:93]
	v_mfma_f32_16x16x32_bf16 v[78:81], v[130:133], v[206:209], v[78:81]
	v_mfma_f32_16x16x32_bf16 v[74:77], v[148:151], v[206:209], v[74:77]
	v_mfma_f32_16x16x32_bf16 v[126:129], v[134:137], v[178:181], v[126:129]
	v_mfma_f32_16x16x32_bf16 v[122:125], v[152:155], v[178:181], v[122:125]
	v_mfma_f32_16x16x32_bf16 v[110:113], v[134:137], v[194:197], v[110:113]
	v_mfma_f32_16x16x32_bf16 v[106:109], v[152:155], v[194:197], v[106:109]
	v_mfma_f32_16x16x32_bf16 v[94:97], v[134:137], v[202:205], v[94:97]
	v_mfma_f32_16x16x32_bf16 v[90:93], v[152:155], v[202:205], v[90:93]
	v_mfma_f32_16x16x32_bf16 v[78:81], v[134:137], v[210:213], v[78:81]
	v_mfma_f32_16x16x32_bf16 v[74:77], v[152:155], v[210:213], v[74:77]
	v_mfma_f32_16x16x32_bf16 v[118:121], v[156:159], v[174:177], v[118:121]
	v_mfma_f32_16x16x32_bf16 v[114:117], v[166:169], v[174:177], v[114:117]
	v_mfma_f32_16x16x32_bf16 v[102:105], v[156:159], v[188:191], v[102:105]
	v_mfma_f32_16x16x32_bf16 v[98:101], v[166:169], v[188:191], v[98:101]
	v_mfma_f32_16x16x32_bf16 v[86:89], v[156:159], v[198:201], v[86:89]
	v_mfma_f32_16x16x32_bf16 v[82:85], v[166:169], v[198:201], v[82:85]
	v_mfma_f32_16x16x32_bf16 v[70:73], v[156:159], v[206:209], v[70:73]
	v_mfma_f32_16x16x32_bf16 v[66:69], v[166:169], v[206:209], v[66:69]
	v_mfma_f32_16x16x32_bf16 v[118:121], v[160:163], v[178:181], v[118:121]
	v_mfma_f32_16x16x32_bf16 v[114:117], v[170:173], v[178:181], v[114:117]
	v_mfma_f32_16x16x32_bf16 v[102:105], v[160:163], v[194:197], v[102:105]
	v_mfma_f32_16x16x32_bf16 v[98:101], v[170:173], v[194:197], v[98:101]
	v_mfma_f32_16x16x32_bf16 v[86:89], v[160:163], v[202:205], v[86:89]
	v_mfma_f32_16x16x32_bf16 v[82:85], v[170:173], v[202:205], v[82:85]
	v_mfma_f32_16x16x32_bf16 v[70:73], v[160:163], v[210:213], v[70:73]
	v_mfma_f32_16x16x32_bf16 v[66:69], v[170:173], v[210:213], v[66:69]
	s_setprio 0
	s_barrier
; #define PG8_STAGE(bufoff, gbase, voff) do { _Pragma("unroll") for (int _i = 0; _i < 2; ++_i) \
;         __builtin_amdgcn_global_load_lds((const unsigned*)((const char*)(gbase) + (voff)[_i]), (LAS unsigned*)(lds + (bufoff) + ldsw + _i * 8192), 16, 0, 0); } while (0)
; #define PG8_LDA(dst, b, h) do { _Pragma("unroll") for (int m = 0; m < 4; ++m) _Pragma("unroll") for (int k = 0; k < 2; ++k) dst[m][k] = *(const LAS bf16x8*)(lds + PG8_SA(b, h) + aoff + m * 2048 + k * 1024); } while (0)
; #define PG8_MMA(ai, bj, At, Bt) do { __builtin_amdgcn_s_setprio(1); _Pragma("unroll") for (int m = 0; m < 4; ++m) _Pragma("unroll") for (int n = 0; n < 2; ++n) _Pragma("unroll") for (int k = 0; k < 2; ++k) \
;         acc[ai][bj][m][n] = __builtin_amdgcn_mfma_f32_16x16x32_bf16(Bt[n][k], At[m][k], acc[ai][bj][m][n], 0, 0, 0); __builtin_amdgcn_s_setprio(0); } while (0)
; #define PG8_WAIT_V(n) asm volatile("s_waitcnt vmcnt(" #n ")" ::: "memory")
; #define PG8_WAIT_L(n) asm volatile("s_waitcnt lgkmcnt(" #n ")" ::: "memory")
; #define PG8_BAR __builtin_amdgcn_s_barrier()
; #define PG8_SCHED __builtin_amdgcn_sched_barrier(0)
; template <class Epi, class Pre, bool AG = false>
; __device__ __forceinline__ void gemm_phase(LAS unsigned char* lds, const Gemm g, const StaticOrder& S, const Epi& E, const Pre& P) {
;     ...
;             PG8_LDA(At, 1, 1); PG8_STAGE(PG8_SB(1, 0), b3, voffB); PG8_STAGE(PG8_SB(1, 1), b3 + hstep, voffB); PG8_STAGE(PG8_SA(1, 0), a3, voffA);
;             PG8_WAIT_V(8); PG8_WAIT_L(0); PG8_BAR; PG8_MMA(1, 0, At, B0); PG8_MMA(1, 1, At, B1); PG8_BAR; PG8_SCHED;
;         }
;         if (wr == 0) PG8_BAR;
	s_add_i32 s14, s14, s48
	v_lshl_add_u64 v[182:183], v[182:183], 0, s[66:67]
	s_mov_b32 m0, s14
	ds_read_b128 v[174:177], v165 offset:49152
	ds_read_b128 v[178:181], v165 offset:50176
	ds_read_b128 v[188:191], v165 offset:51200
	ds_read_b128 v[194:197], v165 offset:52224
	ds_read_b128 v[198:201], v165 offset:53248
	ds_read_b128 v[202:205], v165 offset:54272
	ds_read_b128 v[206:209], v165 offset:55296
	ds_read_b128 v[210:213], v165 offset:56320
	global_load_lds_dwordx4 v[182:183], off
	s_add_i32 m0, s14, 0x2000
	s_add_u32 s54, s54, 0x40080
	v_lshl_add_u64 v[182:183], v[184:185], 0, s[66:67]
	s_addc_u32 s55, s55, 0
	s_add_i32 s14, s21, s48
	global_load_lds_dwordx4 v[182:183], off
	v_lshl_add_u64 v[182:183], s[54:55], 0, v[142:143]
	s_mov_b32 m0, s14
	s_nop 0
	global_load_lds_dwordx4 v[182:183], off
	v_lshl_add_u64 v[182:183], s[54:55], 0, v[138:139]
	s_add_i32 m0, s14, 0x2000
	s_nop 0
	global_load_lds_dwordx4 v[182:183], off
	v_lshl_add_u64 v[182:183], v[186:187], 0, s[66:67]
	s_mov_b32 m0, s53
	s_nop 0
	global_load_lds_dwordx4 v[182:183], off
	v_lshl_add_u64 v[182:183], v[192:193], 0, s[66:67]
	s_mov_b32 m0, s60
	s_nop 0
	global_load_lds_dwordx4 v[182:183], off
	s_waitcnt vmcnt(8)
	s_waitcnt lgkmcnt(0)
	s_barrier
	s_setprio 1
	v_mfma_f32_16x16x32_bf16 v[62:65], v[130:133], v[174:177], v[62:65]
	v_mfma_f32_16x16x32_bf16 v[58:61], v[148:151], v[174:177], v[58:61]
	v_mfma_f32_16x16x32_bf16 v[46:49], v[130:133], v[188:191], v[46:49]
	v_mfma_f32_16x16x32_bf16 v[42:45], v[148:151], v[188:191], v[42:45]
	v_mfma_f32_16x16x32_bf16 v[30:33], v[130:133], v[198:201], v[30:33]
	v_mfma_f32_16x16x32_bf16 v[26:29], v[148:151], v[198:201], v[26:29]
	v_mfma_f32_16x16x32_bf16 v[14:17], v[130:133], v[206:209], v[14:17]
	v_mfma_f32_16x16x32_bf16 v[10:13], v[148:151], v[206:209], v[10:13]
	v_mfma_f32_16x16x32_bf16 v[62:65], v[134:137], v[178:181], v[62:65]
	v_mfma_f32_16x16x32_bf16 v[58:61], v[152:155], v[178:181], v[58:61]
	v_mfma_f32_16x16x32_bf16 v[46:49], v[134:137], v[194:197], v[46:49]
	v_mfma_f32_16x16x32_bf16 v[42:45], v[152:155], v[194:197], v[42:45]
	v_mfma_f32_16x16x32_bf16 v[30:33], v[134:137], v[202:205], v[30:33]
	v_mfma_f32_16x16x32_bf16 v[26:29], v[152:155], v[202:205], v[26:29]
	v_mfma_f32_16x16x32_bf16 v[14:17], v[134:137], v[210:213], v[14:17]
	v_mfma_f32_16x16x32_bf16 v[10:13], v[152:155], v[210:213], v[10:13]
	v_mfma_f32_16x16x32_bf16 v[54:57], v[156:159], v[174:177], v[54:57]
	v_mfma_f32_16x16x32_bf16 v[50:53], v[166:169], v[174:177], v[50:53]
	v_mfma_f32_16x16x32_bf16 v[38:41], v[156:159], v[188:191], v[38:41]
	v_mfma_f32_16x16x32_bf16 v[34:37], v[166:169], v[188:191], v[34:37]
	v_mfma_f32_16x16x32_bf16 v[22:25], v[156:159], v[198:201], v[22:25]
	v_mfma_f32_16x16x32_bf16 v[18:21], v[166:169], v[198:201], v[18:21]
	v_mfma_f32_16x16x32_bf16 v[6:9], v[156:159], v[206:209], v[6:9]
	v_mfma_f32_16x16x32_bf16 v[2:5], v[166:169], v[206:209], v[2:5]
	v_mfma_f32_16x16x32_bf16 v[54:57], v[160:163], v[178:181], v[54:57]
	v_mfma_f32_16x16x32_bf16 v[50:53], v[170:173], v[178:181], v[50:53]
	v_mfma_f32_16x16x32_bf16 v[38:41], v[160:163], v[194:197], v[38:41]
	v_mfma_f32_16x16x32_bf16 v[34:37], v[170:173], v[194:197], v[34:37]
	v_mfma_f32_16x16x32_bf16 v[22:25], v[160:163], v[202:205], v[22:25]
	v_mfma_f32_16x16x32_bf16 v[18:21], v[170:173], v[202:205], v[18:21]
	v_mfma_f32_16x16x32_bf16 v[6:9], v[160:163], v[210:213], v[6:9]
	v_mfma_f32_16x16x32_bf16 v[2:5], v[170:173], v[210:213], v[2:5]
	s_setprio 0
	s_barrier
	s_add_i32 s87, s87, 2
	s_add_u32 s10, s10, 0x100
	s_addc_u32 s11, s11, 0
	s_add_u32 s85, s85, 0x100
	s_addc_u32 s86, s86, 0
	s_cmp_gt_u32 s87, 13
	s_cbranch_scc0 .LBB0_479
	s_and_b64 vcc, exec, s[42:43]
	s_cbranch_vccz .LBB0_482
	s_barrier

; #define PG8_STAGE(bufoff, gbase, voff) do { _Pragma("unroll") for (int _i = 0; _i < 2; ++_i) \
;         __builtin_amdgcn_global_load_lds((const unsigned*)((const char*)(gbase) + (voff)[_i]), (LAS unsigned*)(lds + (bufoff) + ldsw + _i * 8192), 16, 0, 0); } while (0)
; #define PG8_LDA(dst, b, h) do { _Pragma("unroll") for (int m = 0; m < 4; ++m) _Pragma("unroll") for (int k = 0; k < 2; ++k) dst[m][k] = *(const LAS bf16x8*)(lds + PG8_SA(b, h) + aoff + m * 2048 + k * 1024); } while (0)
; #define PG8_LDB(dst, b, h) do { _Pragma("unroll") for (int n = 0; n < 2; ++n) _Pragma("unroll") for (int k = 0; k < 2; ++k) dst[n][k] = *(const LAS bf16x8*)(lds + PG8_SB(b, h) + boff + n * 2048 + k * 1024); } while (0)
; #define PG8_MMA(ai, bj, At, Bt) do { __builtin_amdgcn_s_setprio(1); _Pragma("unroll") for (int m = 0; m < 4; ++m) _Pragma("unroll") for (int n = 0; n < 2; ++n) _Pragma("unroll") for (int k = 0; k < 2; ++k) \
;         acc[ai][bj][m][n] = __builtin_amdgcn_mfma_f32_16x16x32_bf16(Bt[n][k], At[m][k], acc[ai][bj][m][n], 0, 0, 0); __builtin_amdgcn_s_setprio(0); } while (0)
; #define PG8_WAIT_V(n) asm volatile("s_waitcnt vmcnt(" #n ")" ::: "memory")
; #define PG8_WAIT_L(n) asm volatile("s_waitcnt lgkmcnt(" #n ")" ::: "memory")
; #define PG8_BAR __builtin_amdgcn_s_barrier()
; template <class Epi, class Pre, bool AG = false>
; __device__ __forceinline__ void gemm_phase(LAS unsigned char* lds, const Gemm g, const StaticOrder& S, const Epi& E, const Pre& P) {
;     ...
;             const bool last = (t == nt - 2);
;             const char* a1 = cA + (size_t)(t + 1) * kstepA;
;             const char* a2 = last ? nA : cA + (size_t)(t + 2) * kstepA; const char* b2 = last ? nB : cB + (size_t)(t + 2) * kstep;
;             const char* a3 = a2 + kstepA; const char* b3 = b2 + kstep;
;             if constexpr (Epi::MIDK) { if (t == E.midk_t) E.mid(acc, cur, ui, wr, wc, fr, fq); }
;             PG8_LDB(B0, 0, 0); PG8_LDB(B1, 0, 1); PG8_SCHED; PG8_LDA(At, 0, 0); PG8_STAGE(PG8_SA(1, 1), a1 + hstepA, voffA);
;             PG8_WAIT_V(8); PG8_WAIT_L(0); PG8_BAR; PG8_MMA(0, 0, At, B0); PG8_MMA(0, 1, At, B1); PG8_BAR; PG8_SCHED;
;             PG8_LDA(At, 0, 1); PG8_STAGE(PG8_SB(0, 0), b2, voffB); PG8_STAGE(PG8_SB(0, 1), b2 + hstep, voffB); PG8_STAGE(PG8_SA(0, 0), a2, voffA);
;             PG8_WAIT_V(8); PG8_WAIT_L(0); PG8_BAR; PG8_MMA(1, 0, At, B0); PG8_MMA(1, 1, At, B1); PG8_BAR; PG8_SCHED;
.LBB0_579:
	s_add_u32 s54, s46, 0xfffc0080
	s_addc_u32 s55, s47, -1
	s_add_i32 s85, 0, 0x10000
	s_cmp_eq_u32 s84, 12
	s_cselect_b32 s57, s12, s55
	s_cselect_b32 s56, s13, s54
	v_add_u32_e32 v144, s85, v146
	s_cselect_b32 s55, s27, s79
	s_cselect_b32 s54, s29, s78
	s_add_i32 s94, 0, 0x14000
	ds_read_b128 v[140:143], v144
	ds_read_b128 v[148:151], v144 offset:1024
	ds_read_b128 v[152:155], v144 offset:2048
	ds_read_b128 v[156:159], v144 offset:3072
	v_add_u32_e32 v144, s94, v146
	ds_read_b128 v[160:163], v144
	ds_read_b128 v[164:167], v144 offset:1024
	ds_read_b128 v[168:171], v144 offset:2048
	ds_read_b128 v[172:175], v144 offset:3072
	v_lshl_add_u64 v[144:145], s[46:47], 0, v[0:1]
	s_add_i32 m0, s38, 0xc000
	ds_read_b128 v[194:197], v147
	ds_read_b128 v[198:201], v147 offset:1024
	ds_read_b128 v[202:205], v147 offset:2048
	ds_read_b128 v[206:209], v147 offset:3072
	ds_read_b128 v[210:213], v147 offset:4096
	ds_read_b128 v[214:217], v147 offset:5120
	ds_read_b128 v[218:221], v147 offset:6144
	ds_read_b128 v[222:225], v147 offset:7168
	global_load_lds_dwordx4 v[144:145], off
	v_lshl_add_u64 v[144:145], s[46:47], 0, v[138:139]
	s_add_i32 m0, s38, 0xe000
	s_nop 0
	global_load_lds_dwordx4 v[144:145], off
	s_waitcnt vmcnt(8)
	s_waitcnt lgkmcnt(0)
	s_barrier
	s_setprio 1
	v_mfma_f32_16x16x32_bf16 v[126:129], v[140:143], v[194:197], v[126:129]
	v_mfma_f32_16x16x32_bf16 v[122:125], v[152:155], v[194:197], v[122:125]
	v_mfma_f32_16x16x32_bf16 v[110:113], v[140:143], v[202:205], v[110:113]
	v_mfma_f32_16x16x32_bf16 v[106:109], v[152:155], v[202:205], v[106:109]
	v_mfma_f32_16x16x32_bf16 v[94:97], v[140:143], v[210:213], v[94:97]
	v_mfma_f32_16x16x32_bf16 v[90:93], v[152:155], v[210:213], v[90:93]
	v_mfma_f32_16x16x32_bf16 v[78:81], v[140:143], v[218:221], v[78:81]
	v_mfma_f32_16x16x32_bf16 v[74:77], v[152:155], v[218:221], v[74:77]
	v_mfma_f32_16x16x32_bf16 v[126:129], v[148:151], v[198:201], v[126:129]
	v_mfma_f32_16x16x32_bf16 v[122:125], v[156:159], v[198:201], v[122:125]
	v_mfma_f32_16x16x32_bf16 v[110:113], v[148:151], v[206:209], v[110:113]
	v_mfma_f32_16x16x32_bf16 v[106:109], v[156:159], v[206:209], v[106:109]
	v_mfma_f32_16x16x32_bf16 v[94:97], v[148:151], v[214:217], v[94:97]
	v_mfma_f32_16x16x32_bf16 v[90:93], v[156:159], v[214:217], v[90:93]
	v_mfma_f32_16x16x32_bf16 v[78:81], v[148:151], v[222:225], v[78:81]
	v_mfma_f32_16x16x32_bf16 v[74:77], v[156:159], v[222:225], v[74:77]
	v_mfma_f32_16x16x32_bf16 v[118:121], v[160:163], v[194:197], v[118:121]
	v_mfma_f32_16x16x32_bf16 v[114:117], v[168:171], v[194:197], v[114:117]
	v_mfma_f32_16x16x32_bf16 v[102:105], v[160:163], v[202:205], v[102:105]
	v_mfma_f32_16x16x32_bf16 v[98:101], v[168:171], v[202:205], v[98:101]
	v_mfma_f32_16x16x32_bf16 v[86:89], v[160:163], v[210:213], v[86:89]
	v_mfma_f32_16x16x32_bf16 v[82:85], v[168:171], v[210:213], v[82:85]
	v_mfma_f32_16x16x32_bf16 v[70:73], v[160:163], v[218:221], v[70:73]
	v_mfma_f32_16x16x32_bf16 v[66:69], v[168:171], v[218:221], v[66:69]
	v_mfma_f32_16x16x32_bf16 v[118:121], v[164:167], v[198:201], v[118:121]
	v_mfma_f32_16x16x32_bf16 v[114:117], v[172:175], v[198:201], v[114:117]
	v_mfma_f32_16x16x32_bf16 v[102:105], v[164:167], v[206:209], v[102:105]
	v_mfma_f32_16x16x32_bf16 v[98:101], v[172:175], v[206:209], v[98:101]
	v_mfma_f32_16x16x32_bf16 v[86:89], v[164:167], v[214:217], v[86:89]
	v_mfma_f32_16x16x32_bf16 v[82:85], v[172:175], v[214:217], v[82:85]
	v_mfma_f32_16x16x32_bf16 v[70:73], v[164:167], v[222:225], v[70:73]
	v_mfma_f32_16x16x32_bf16 v[66:69], v[172:175], v[222:225], v[66:69]
	s_setprio 0
	s_barrier
	s_add_i32 s85, s85, s31
	v_lshl_add_u64 v[144:145], s[54:55], 0, v[134:135]
	s_mov_b32 m0, s85
	ds_read_b128 v[194:197], v147 offset:16384
	ds_read_b128 v[198:201], v147 offset:17408
	ds_read_b128 v[202:205], v147 offset:18432
	ds_read_b128 v[206:209], v147 offset:19456
	ds_read_b128 v[210:213], v147 offset:20480
	ds_read_b128 v[214:217], v147 offset:21504
	ds_read_b128 v[218:221], v147 offset:22528
	ds_read_b128 v[222:225], v147 offset:23552
	global_load_lds_dwordx4 v[144:145], off
	s_add_i32 m0, s85, 0x2000
	s_add_u32 s86, s54, 0x40000
	v_lshl_add_u64 v[176:177], s[54:55], 0, v[130:131]
	s_addc_u32 s87, s55, 0
	s_add_i32 s85, s94, s31
	global_load_lds_dwordx4 v[176:177], off
	v_lshl_add_u64 v[178:179], s[86:87], 0, v[134:135]
	s_mov_b32 m0, s85
	v_lshl_add_u64 v[180:181], s[56:57], 0, v[132:133]
	global_load_lds_dwordx4 v[178:179], off
	v_lshl_add_u64 v[178:179], s[86:87], 0, v[130:131]
	s_add_i32 m0, s85, 0x2000
	s_nop 0
	global_load_lds_dwordx4 v[178:179], off
	v_lshl_add_u64 v[178:179], s[56:57], 0, v[136:137]
	s_mov_b32 m0, s38
	s_nop 0
	global_load_lds_dwordx4 v[178:179], off
	s_mov_b32 m0, s48
	s_nop 0
	global_load_lds_dwordx4 v[180:181], off
	s_waitcnt vmcnt(8)
	s_waitcnt lgkmcnt(0)
	s_barrier
; #define PG8_STAGE(bufoff, gbase, voff) do { _Pragma("unroll") for (int _i = 0; _i < 2; ++_i) \
;         __builtin_amdgcn_global_load_lds((const unsigned*)((const char*)(gbase) + (voff)[_i]), (LAS unsigned*)(lds + (bufoff) + ldsw + _i * 8192), 16, 0, 0); } while (0)
; #define PG8_LDA(dst, b, h) do { _Pragma("unroll") for (int m = 0; m < 4; ++m) _Pragma("unroll") for (int k = 0; k < 2; ++k) dst[m][k] = *(const LAS bf16x8*)(lds + PG8_SA(b, h) + aoff + m * 2048 + k * 1024); } while (0)
; #define PG8_LDB(dst, b, h) do { _Pragma("unroll") for (int n = 0; n < 2; ++n) _Pragma("unroll") for (int k = 0; k < 2; ++k) dst[n][k] = *(const LAS bf16x8*)(lds + PG8_SB(b, h) + boff + n * 2048 + k * 1024); } while (0)
; #define PG8_MMA(ai, bj, At, Bt) do { __builtin_amdgcn_s_setprio(1); _Pragma("unroll") for (int m = 0; m < 4; ++m) _Pragma("unroll") for (int n = 0; n < 2; ++n) _Pragma("unroll") for (int k = 0; k < 2; ++k) \
;         acc[ai][bj][m][n] = __builtin_amdgcn_mfma_f32_16x16x32_bf16(Bt[n][k], At[m][k], acc[ai][bj][m][n], 0, 0, 0); __builtin_amdgcn_s_setprio(0); } while (0)
; #define PG8_WAIT_V(n) asm volatile("s_waitcnt vmcnt(" #n ")" ::: "memory")
; #define PG8_WAIT_L(n) asm volatile("s_waitcnt lgkmcnt(" #n ")" ::: "memory")
; #define PG8_BAR __builtin_amdgcn_s_barrier()
; #define PG8_SCHED __builtin_amdgcn_sched_barrier(0)
; template <class Epi, class Pre, bool AG = false>
; __device__ __forceinline__ void gemm_phase(LAS unsigned char* lds, const Gemm g, const StaticOrder& S, const Epi& E, const Pre& P) {
;     ...
;             PG8_WAIT_V(8); PG8_WAIT_L(0); PG8_BAR; PG8_MMA(1, 0, At, B0); PG8_MMA(1, 1, At, B1); PG8_BAR; PG8_SCHED;
;             PG8_LDB(B0, 1, 0); PG8_LDB(B1, 1, 1); PG8_SCHED; PG8_LDA(At, 1, 0); PG8_STAGE(PG8_SA(0, 1), a2 + hstepA, voffA);
;             PG8_WAIT_V(8); PG8_WAIT_L(0); PG8_BAR; PG8_MMA(0, 0, At, B0); PG8_MMA(0, 1, At, B1); PG8_BAR; PG8_SCHED;
	s_setprio 1
	v_mfma_f32_16x16x32_bf16 v[62:65], v[140:143], v[194:197], v[62:65]
	v_mfma_f32_16x16x32_bf16 v[58:61], v[152:155], v[194:197], v[58:61]
	v_mfma_f32_16x16x32_bf16 v[50:53], v[140:143], v[202:205], v[50:53]
	v_mfma_f32_16x16x32_bf16 v[42:45], v[152:155], v[202:205], v[42:45]
	v_mfma_f32_16x16x32_bf16 v[34:37], v[140:143], v[210:213], v[34:37]
	v_mfma_f32_16x16x32_bf16 v[26:29], v[152:155], v[210:213], v[26:29]
	v_mfma_f32_16x16x32_bf16 v[18:21], v[140:143], v[218:221], v[18:21]
	v_mfma_f32_16x16x32_bf16 v[10:13], v[152:155], v[218:221], v[10:13]
	v_mfma_f32_16x16x32_bf16 v[62:65], v[148:151], v[198:201], v[62:65]
	v_mfma_f32_16x16x32_bf16 v[58:61], v[156:159], v[198:201], v[58:61]
	v_mfma_f32_16x16x32_bf16 v[50:53], v[148:151], v[206:209], v[50:53]
	v_mfma_f32_16x16x32_bf16 v[42:45], v[156:159], v[206:209], v[42:45]
	v_mfma_f32_16x16x32_bf16 v[34:37], v[148:151], v[214:217], v[34:37]
	v_mfma_f32_16x16x32_bf16 v[26:29], v[156:159], v[214:217], v[26:29]
	v_mfma_f32_16x16x32_bf16 v[18:21], v[148:151], v[222:225], v[18:21]
	v_mfma_f32_16x16x32_bf16 v[10:13], v[156:159], v[222:225], v[10:13]
	v_mfma_f32_16x16x32_bf16 v[54:57], v[160:163], v[194:197], v[54:57]
	v_mfma_f32_16x16x32_bf16 v[46:49], v[168:171], v[194:197], v[46:49]
	v_mfma_f32_16x16x32_bf16 v[38:41], v[160:163], v[202:205], v[38:41]
	v_mfma_f32_16x16x32_bf16 v[30:33], v[168:171], v[202:205], v[30:33]
	v_mfma_f32_16x16x32_bf16 v[22:25], v[160:163], v[210:213], v[22:25]
	v_mfma_f32_16x16x32_bf16 v[14:17], v[168:171], v[210:213], v[14:17]
	v_mfma_f32_16x16x32_bf16 v[6:9], v[160:163], v[218:221], v[6:9]
	v_mfma_f32_16x16x32_bf16 v[2:5], v[168:171], v[218:221], v[2:5]
	v_mfma_f32_16x16x32_bf16 v[54:57], v[164:167], v[198:201], v[54:57]
	v_mfma_f32_16x16x32_bf16 v[46:49], v[172:175], v[198:201], v[46:49]
	v_mfma_f32_16x16x32_bf16 v[38:41], v[164:167], v[206:209], v[38:41]
	v_mfma_f32_16x16x32_bf16 v[30:33], v[172:175], v[206:209], v[30:33]
	v_mfma_f32_16x16x32_bf16 v[22:25], v[164:167], v[214:217], v[22:25]
	v_mfma_f32_16x16x32_bf16 v[14:17], v[172:175], v[214:217], v[14:17]
	v_mfma_f32_16x16x32_bf16 v[6:9], v[164:167], v[222:225], v[6:9]
	v_mfma_f32_16x16x32_bf16 v[2:5], v[172:175], v[222:225], v[2:5]
	s_setprio 0
	s_barrier
	s_add_i32 s85, 0, 0x18000
	s_add_i32 s86, 0, 0x1c000
	v_add_u32_e32 v156, s85, v146
	v_add_u32_e32 v172, s86, v146
	ds_read_b128 v[140:143], v156
	ds_read_b128 v[148:151], v156 offset:1024
	ds_read_b128 v[152:155], v156 offset:2048
	ds_read_b128 v[156:159], v156 offset:3072
	ds_read_b128 v[160:163], v172
	ds_read_b128 v[164:167], v172 offset:1024
	ds_read_b128 v[168:171], v172 offset:2048
	ds_read_b128 v[172:175], v172 offset:3072
	s_add_u32 s56, s56, 0x40000
	s_addc_u32 s57, s57, 0
	s_mov_b32 m0, s49
	v_lshl_add_u64 v[182:183], s[56:57], 0, v[136:137]
	ds_read_b128 v[194:197], v147 offset:32768
	ds_read_b128 v[198:201], v147 offset:33792
	ds_read_b128 v[202:205], v147 offset:34816
	ds_read_b128 v[206:209], v147 offset:35840
	ds_read_b128 v[210:213], v147 offset:36864
	ds_read_b128 v[214:217], v147 offset:37888
	ds_read_b128 v[218:221], v147 offset:38912
	ds_read_b128 v[222:225], v147 offset:39936
	global_load_lds_dwordx4 v[182:183], off
	v_lshl_add_u64 v[182:183], s[56:57], 0, v[132:133]
	s_mov_b32 m0, s53
	s_nop 0
	global_load_lds_dwordx4 v[182:183], off
	s_waitcnt vmcnt(8)
	s_waitcnt lgkmcnt(0)
	s_barrier
	s_setprio 1
	v_mfma_f32_16x16x32_bf16 v[126:129], v[140:143], v[194:197], v[126:129]
	v_mfma_f32_16x16x32_bf16 v[122:125], v[152:155], v[194:197], v[122:125]
	v_mfma_f32_16x16x32_bf16 v[110:113], v[140:143], v[202:205], v[110:113]
	v_mfma_f32_16x16x32_bf16 v[106:109], v[152:155], v[202:205], v[106:109]
	v_mfma_f32_16x16x32_bf16 v[94:97], v[140:143], v[210:213], v[94:97]
	v_mfma_f32_16x16x32_bf16 v[90:93], v[152:155], v[210:213], v[90:93]
	v_mfma_f32_16x16x32_bf16 v[78:81], v[140:143], v[218:221], v[78:81]
	v_mfma_f32_16x16x32_bf16 v[74:77], v[152:155], v[218:221], v[74:77]
	v_mfma_f32_16x16x32_bf16 v[126:129], v[148:151], v[198:201], v[126:129]
	v_mfma_f32_16x16x32_bf16 v[122:125], v[156:159], v[198:201], v[122:125]
	v_mfma_f32_16x16x32_bf16 v[110:113], v[148:151], v[206:209], v[110:113]
	v_mfma_f32_16x16x32_bf16 v[106:109], v[156:159], v[206:209], v[106:109]
	v_mfma_f32_16x16x32_bf16 v[94:97], v[148:151], v[214:217], v[94:97]
	v_mfma_f32_16x16x32_bf16 v[90:93], v[156:159], v[214:217], v[90:93]
	v_mfma_f32_16x16x32_bf16 v[78:81], v[148:151], v[222:225], v[78:81]
	v_mfma_f32_16x16x32_bf16 v[74:77], v[156:159], v[222:225], v[74:77]
	v_mfma_f32_16x16x32_bf16 v[118:121], v[160:163], v[194:197], v[118:121]
	v_mfma_f32_16x16x32_bf16 v[114:117], v[168:171], v[194:197], v[114:117]
	v_mfma_f32_16x16x32_bf16 v[102:105], v[160:163], v[202:205], v[102:105]
	v_mfma_f32_16x16x32_bf16 v[98:101], v[168:171], v[202:205], v[98:101]
	v_mfma_f32_16x16x32_bf16 v[86:89], v[160:163], v[210:213], v[86:89]
	v_mfma_f32_16x16x32_bf16 v[82:85], v[168:171], v[210:213], v[82:85]
	v_mfma_f32_16x16x32_bf16 v[70:73], v[160:163], v[218:221], v[70:73]
	v_mfma_f32_16x16x32_bf16 v[66:69], v[168:171], v[218:221], v[66:69]
	v_mfma_f32_16x16x32_bf16 v[118:121], v[164:167], v[198:201], v[118:121]
	v_mfma_f32_16x16x32_bf16 v[114:117], v[172:175], v[198:201], v[114:117]
	v_mfma_f32_16x16x32_bf16 v[102:105], v[164:167], v[206:209], v[102:105]
	v_mfma_f32_16x16x32_bf16 v[98:101], v[172:175], v[206:209], v[98:101]
	v_mfma_f32_16x16x32_bf16 v[86:89], v[164:167], v[214:217], v[86:89]
	v_mfma_f32_16x16x32_bf16 v[82:85], v[172:175], v[214:217], v[82:85]
	v_mfma_f32_16x16x32_bf16 v[70:73], v[164:167], v[222:225], v[70:73]
	v_mfma_f32_16x16x32_bf16 v[66:69], v[172:175], v[222:225], v[66:69]
	s_setprio 0
	s_barrier
; #define PG8_STAGE(bufoff, gbase, voff) do { _Pragma("unroll") for (int _i = 0; _i < 2; ++_i) \
;         __builtin_amdgcn_global_load_lds((const unsigned*)((const char*)(gbase) + (voff)[_i]), (LAS unsigned*)(lds + (bufoff) + ldsw + _i * 8192), 16, 0, 0); } while (0)
; #define PG8_LDA(dst, b, h) do { _Pragma("unroll") for (int m = 0; m < 4; ++m) _Pragma("unroll") for (int k = 0; k < 2; ++k) dst[m][k] = *(const LAS bf16x8*)(lds + PG8_SA(b, h) + aoff + m * 2048 + k * 1024); } while (0)
; #define PG8_MMA(ai, bj, At, Bt) do { __builtin_amdgcn_s_setprio(1); _Pragma("unroll") for (int m = 0; m < 4; ++m) _Pragma("unroll") for (int n = 0; n < 2; ++n) _Pragma("unroll") for (int k = 0; k < 2; ++k) \
;         acc[ai][bj][m][n] = __builtin_amdgcn_mfma_f32_16x16x32_bf16(Bt[n][k], At[m][k], acc[ai][bj][m][n], 0, 0, 0); __builtin_amdgcn_s_setprio(0); } while (0)
; #define PG8_WAIT_V(n) asm volatile("s_waitcnt vmcnt(" #n ")" ::: "memory")
; #define PG8_WAIT_L(n) asm volatile("s_waitcnt lgkmcnt(" #n ")" ::: "memory")
; #define PG8_BAR __builtin_amdgcn_s_barrier()
; #define PG8_SCHED __builtin_amdgcn_sched_barrier(0)
; template <class Epi, class Pre, bool AG = false>
; __device__ __forceinline__ void gemm_phase(LAS unsigned char* lds, const Gemm g, const StaticOrder& S, const Epi& E, const Pre& P) {
;     ...
;             PG8_LDA(At, 1, 1); PG8_STAGE(PG8_SB(1, 0), b3, voffB); PG8_STAGE(PG8_SB(1, 1), b3 + hstep, voffB); PG8_STAGE(PG8_SA(1, 0), a3, voffA);
;             PG8_WAIT_V(8); PG8_WAIT_L(0); PG8_BAR; PG8_MMA(1, 0, At, B0); PG8_MMA(1, 1, At, B1); PG8_BAR; PG8_SCHED;
;         }
;         if (wr == 0) PG8_BAR;
	s_add_i32 s56, s85, s31
	v_lshl_add_u64 v[144:145], v[144:145], 0, s[66:67]
	s_mov_b32 m0, s56
	ds_read_b128 v[194:197], v147 offset:49152
	ds_read_b128 v[198:201], v147 offset:50176
	ds_read_b128 v[202:205], v147 offset:51200
	ds_read_b128 v[206:209], v147 offset:52224
	ds_read_b128 v[210:213], v147 offset:53248
	ds_read_b128 v[214:217], v147 offset:54272
	ds_read_b128 v[218:221], v147 offset:55296
	ds_read_b128 v[222:225], v147 offset:56320
	global_load_lds_dwordx4 v[144:145], off
	s_add_i32 m0, s56, 0x2000
	s_add_u32 s54, s54, 0x40080
	v_lshl_add_u64 v[144:145], v[176:177], 0, s[66:67]
	s_addc_u32 s55, s55, 0
	s_add_i32 s56, s86, s31
	global_load_lds_dwordx4 v[144:145], off
	v_lshl_add_u64 v[144:145], s[54:55], 0, v[134:135]
	s_mov_b32 m0, s56
	s_nop 0
	global_load_lds_dwordx4 v[144:145], off
	v_lshl_add_u64 v[144:145], s[54:55], 0, v[130:131]
	s_add_i32 m0, s56, 0x2000
	s_nop 0
	global_load_lds_dwordx4 v[144:145], off
	v_lshl_add_u64 v[144:145], v[178:179], 0, s[66:67]
	s_mov_b32 m0, s60
	s_nop 0
	global_load_lds_dwordx4 v[144:145], off
	v_lshl_add_u64 v[144:145], v[180:181], 0, s[66:67]
	s_mov_b32 m0, s61
	s_nop 0
	global_load_lds_dwordx4 v[144:145], off
	s_waitcnt vmcnt(8)
	s_waitcnt lgkmcnt(0)
	s_barrier
	s_setprio 1
	v_mfma_f32_16x16x32_bf16 v[62:65], v[140:143], v[194:197], v[62:65]
	v_mfma_f32_16x16x32_bf16 v[58:61], v[152:155], v[194:197], v[58:61]
	v_mfma_f32_16x16x32_bf16 v[50:53], v[140:143], v[202:205], v[50:53]
	v_mfma_f32_16x16x32_bf16 v[42:45], v[152:155], v[202:205], v[42:45]
	v_mfma_f32_16x16x32_bf16 v[34:37], v[140:143], v[210:213], v[34:37]
	v_mfma_f32_16x16x32_bf16 v[26:29], v[152:155], v[210:213], v[26:29]
	v_mfma_f32_16x16x32_bf16 v[18:21], v[140:143], v[218:221], v[18:21]
	v_mfma_f32_16x16x32_bf16 v[10:13], v[152:155], v[218:221], v[10:13]
	v_mfma_f32_16x16x32_bf16 v[62:65], v[148:151], v[198:201], v[62:65]
	v_mfma_f32_16x16x32_bf16 v[58:61], v[156:159], v[198:201], v[58:61]
	v_mfma_f32_16x16x32_bf16 v[50:53], v[148:151], v[206:209], v[50:53]
	v_mfma_f32_16x16x32_bf16 v[42:45], v[156:159], v[206:209], v[42:45]
	v_mfma_f32_16x16x32_bf16 v[34:37], v[148:151], v[214:217], v[34:37]
	v_mfma_f32_16x16x32_bf16 v[26:29], v[156:159], v[214:217], v[26:29]
	v_mfma_f32_16x16x32_bf16 v[18:21], v[148:151], v[222:225], v[18:21]
	v_mfma_f32_16x16x32_bf16 v[10:13], v[156:159], v[222:225], v[10:13]
	v_mfma_f32_16x16x32_bf16 v[54:57], v[160:163], v[194:197], v[54:57]
	v_mfma_f32_16x16x32_bf16 v[46:49], v[168:171], v[194:197], v[46:49]
	v_mfma_f32_16x16x32_bf16 v[38:41], v[160:163], v[202:205], v[38:41]
	v_mfma_f32_16x16x32_bf16 v[30:33], v[168:171], v[202:205], v[30:33]
	v_mfma_f32_16x16x32_bf16 v[22:25], v[160:163], v[210:213], v[22:25]
	v_mfma_f32_16x16x32_bf16 v[14:17], v[168:171], v[210:213], v[14:17]
	v_mfma_f32_16x16x32_bf16 v[6:9], v[160:163], v[218:221], v[6:9]
	v_mfma_f32_16x16x32_bf16 v[2:5], v[168:171], v[218:221], v[2:5]
	v_mfma_f32_16x16x32_bf16 v[54:57], v[164:167], v[198:201], v[54:57]
	v_mfma_f32_16x16x32_bf16 v[46:49], v[172:175], v[198:201], v[46:49]
	v_mfma_f32_16x16x32_bf16 v[38:41], v[164:167], v[206:209], v[38:41]
	v_mfma_f32_16x16x32_bf16 v[30:33], v[172:175], v[206:209], v[30:33]
	v_mfma_f32_16x16x32_bf16 v[22:25], v[164:167], v[214:217], v[22:25]
	v_mfma_f32_16x16x32_bf16 v[14:17], v[172:175], v[214:217], v[14:17]
	v_mfma_f32_16x16x32_bf16 v[6:9], v[164:167], v[222:225], v[6:9]
	v_mfma_f32_16x16x32_bf16 v[2:5], v[172:175], v[222:225], v[2:5]
	s_setprio 0
	s_barrier
	s_add_i32 s84, s84, 2
	s_add_u32 s46, s46, 0x100
	s_addc_u32 s47, s47, 0
	s_add_u32 s78, s78, 0x100
	s_addc_u32 s79, s79, 0
	s_cmp_gt_u32 s84, 13
	s_cbranch_scc0 .LBB0_579
	s_and_b64 vcc, exec, s[16:17]
	s_cbranch_vccz .LBB0_582
	s_barrier

; #define PG8_STAGE(bufoff, gbase, voff) do { _Pragma("unroll") for (int _i = 0; _i < 2; ++_i) \
;         __builtin_amdgcn_global_load_lds((const unsigned*)((const char*)(gbase) + (voff)[_i]), (LAS unsigned*)(lds + (bufoff) + ldsw + _i * 8192), 16, 0, 0); } while (0)
; #define PG8_LDA(dst, b, h) do { _Pragma("unroll") for (int m = 0; m < 4; ++m) _Pragma("unroll") for (int k = 0; k < 2; ++k) dst[m][k] = *(const LAS bf16x8*)(lds + PG8_SA(b, h) + aoff + m * 2048 + k * 1024); } while (0)
; #define PG8_LDB(dst, b, h) do { _Pragma("unroll") for (int n = 0; n < 2; ++n) _Pragma("unroll") for (int k = 0; k < 2; ++k) dst[n][k] = *(const LAS bf16x8*)(lds + PG8_SB(b, h) + boff + n * 2048 + k * 1024); } while (0)
; #define PG8_MMA(ai, bj, At, Bt) do { __builtin_amdgcn_s_setprio(1); _Pragma("unroll") for (int m = 0; m < 4; ++m) _Pragma("unroll") for (int n = 0; n < 2; ++n) _Pragma("unroll") for (int k = 0; k < 2; ++k) \
;         acc[ai][bj][m][n] = __builtin_amdgcn_mfma_f32_16x16x32_bf16(Bt[n][k], At[m][k], acc[ai][bj][m][n], 0, 0, 0); __builtin_amdgcn_s_setprio(0); } while (0)
; #define PG8_WAIT_V(n) asm volatile("s_waitcnt vmcnt(" #n ")" ::: "memory")
; #define PG8_WAIT_L(n) asm volatile("s_waitcnt lgkmcnt(" #n ")" ::: "memory")
; #define PG8_BAR __builtin_amdgcn_s_barrier()
; template <class Epi, class Pre, bool AG = false>
; __device__ __forceinline__ void gemm_phase(LAS unsigned char* lds, const Gemm g, const StaticOrder& S, const Epi& E, const Pre& P) {
;     ...
;             const bool last = (t == nt - 2);
;             const char* a1 = cA + (size_t)(t + 1) * kstepA;
;             const char* a2 = last ? nA : cA + (size_t)(t + 2) * kstepA; const char* b2 = last ? nB : cB + (size_t)(t + 2) * kstep;
;             const char* a3 = a2 + kstepA; const char* b3 = b2 + kstep;
;             if constexpr (Epi::MIDK) { if (t == E.midk_t) E.mid(acc, cur, ui, wr, wc, fr, fq); }
;             PG8_LDB(B0, 0, 0); PG8_LDB(B1, 0, 1); PG8_SCHED; PG8_LDA(At, 0, 0); PG8_STAGE(PG8_SA(1, 1), a1 + hstepA, voffA);
;             PG8_WAIT_V(8); PG8_WAIT_L(0); PG8_BAR; PG8_MMA(0, 0, At, B0); PG8_MMA(0, 1, At, B1); PG8_BAR; PG8_SCHED;
;             PG8_LDA(At, 0, 1); PG8_STAGE(PG8_SB(0, 0), b2, voffB); PG8_STAGE(PG8_SB(0, 1), b2 + hstep, voffB); PG8_STAGE(PG8_SA(0, 0), a2, voffA);
;             PG8_WAIT_V(8); PG8_WAIT_L(0); PG8_BAR; PG8_MMA(1, 0, At, B0); PG8_MMA(1, 1, At, B1); PG8_BAR; PG8_SCHED;
.LBB0_741:
	s_add_u32 s54, s10, 0x400000
	s_addc_u32 s55, s11, 0
	s_cmp_eq_u32 s87, 4
	s_cselect_b32 s60, s13, s54
	s_cselect_b32 s61, s12, s55
	s_cselect_b32 s58, s29, vcc_lo
	s_cselect_b32 s59, s27, vcc_hi
	s_add_u32 s56, s60, 0x200000
	s_addc_u32 s57, s61, 0
	s_add_i32 s21, 0, 0x10000
	v_add_u32_e32 v0, s21, v238
	s_add_i32 s14, 0, 0x14000
	ds_read_b128 v[58:61], v0
	ds_read_b128 v[62:65], v0 offset:1024
	ds_read_b128 v[74:77], v0 offset:2048
	ds_read_b128 v[78:81], v0 offset:3072
	v_add_u32_e32 v0, s14, v238
	ds_read_b128 v[138:141], v0
	ds_read_b128 v[142:145], v0 offset:1024
	ds_read_b128 v[146:149], v0 offset:2048
	ds_read_b128 v[150:153], v0 offset:3072
	v_lshl_add_u64 v[178:179], s[10:11], 0, v[202:203]
	s_add_i32 m0, s49, 0xc000
	ds_read_b128 v[154:157], v239
	ds_read_b128 v[166:169], v239 offset:1024
	ds_read_b128 v[170:173], v239 offset:2048
	ds_read_b128 v[174:177], v239 offset:3072
	ds_read_b128 v[206:209], v239 offset:4096
	ds_read_b128 v[210:213], v239 offset:5120
	ds_read_b128 v[214:217], v239 offset:6144
	ds_read_b128 v[218:221], v239 offset:7168
	global_load_lds_dwordx4 v[178:179], off
	v_lshl_add_u64 v[178:179], s[10:11], 0, v[204:205]
	s_add_i32 m0, s49, 0xe000
	s_nop 0
	global_load_lds_dwordx4 v[178:179], off
	s_waitcnt vmcnt(8)
	s_waitcnt lgkmcnt(0)
	s_barrier
	s_setprio 1
	v_mfma_f32_16x16x32_bf16 v[162:165], v[58:61], v[154:157], v[162:165]
	v_mfma_f32_16x16x32_bf16 v[158:161], v[74:77], v[154:157], v[158:161]
	v_mfma_f32_16x16x32_bf16 v[126:129], v[58:61], v[170:173], v[126:129]
	v_mfma_f32_16x16x32_bf16 v[122:125], v[74:77], v[170:173], v[122:125]
	v_mfma_f32_16x16x32_bf16 v[110:113], v[58:61], v[206:209], v[110:113]
	v_mfma_f32_16x16x32_bf16 v[106:109], v[74:77], v[206:209], v[106:109]
	v_mfma_f32_16x16x32_bf16 v[94:97], v[58:61], v[214:217], v[94:97]
	v_mfma_f32_16x16x32_bf16 v[90:93], v[74:77], v[214:217], v[90:93]
	v_mfma_f32_16x16x32_bf16 v[162:165], v[62:65], v[166:169], v[162:165]
	v_mfma_f32_16x16x32_bf16 v[158:161], v[78:81], v[166:169], v[158:161]
	v_mfma_f32_16x16x32_bf16 v[126:129], v[62:65], v[174:177], v[126:129]
	v_mfma_f32_16x16x32_bf16 v[122:125], v[78:81], v[174:177], v[122:125]
	v_mfma_f32_16x16x32_bf16 v[110:113], v[62:65], v[210:213], v[110:113]
	v_mfma_f32_16x16x32_bf16 v[106:109], v[78:81], v[210:213], v[106:109]
	v_mfma_f32_16x16x32_bf16 v[94:97], v[62:65], v[218:221], v[94:97]
	v_mfma_f32_16x16x32_bf16 v[90:93], v[78:81], v[218:221], v[90:93]
	v_mfma_f32_16x16x32_bf16 v[134:137], v[138:141], v[154:157], v[134:137]
	v_mfma_f32_16x16x32_bf16 v[130:133], v[146:149], v[154:157], v[130:133]
	v_mfma_f32_16x16x32_bf16 v[118:121], v[138:141], v[170:173], v[118:121]
	v_mfma_f32_16x16x32_bf16 v[114:117], v[146:149], v[170:173], v[114:117]
	v_mfma_f32_16x16x32_bf16 v[102:105], v[138:141], v[206:209], v[102:105]
	v_mfma_f32_16x16x32_bf16 v[98:101], v[146:149], v[206:209], v[98:101]
	v_mfma_f32_16x16x32_bf16 v[86:89], v[138:141], v[214:217], v[86:89]
	v_mfma_f32_16x16x32_bf16 v[82:85], v[146:149], v[214:217], v[82:85]
	v_mfma_f32_16x16x32_bf16 v[134:137], v[142:145], v[166:169], v[134:137]
	v_mfma_f32_16x16x32_bf16 v[130:133], v[150:153], v[166:169], v[130:133]
	v_mfma_f32_16x16x32_bf16 v[118:121], v[142:145], v[174:177], v[118:121]
	v_mfma_f32_16x16x32_bf16 v[114:117], v[150:153], v[174:177], v[114:117]
	v_mfma_f32_16x16x32_bf16 v[102:105], v[142:145], v[210:213], v[102:105]
	v_mfma_f32_16x16x32_bf16 v[98:101], v[150:153], v[210:213], v[98:101]
	v_mfma_f32_16x16x32_bf16 v[86:89], v[142:145], v[218:221], v[86:89]
	v_mfma_f32_16x16x32_bf16 v[82:85], v[150:153], v[218:221], v[82:85]
	s_setprio 0
	s_barrier
	s_add_i32 s10, s21, s48
	v_lshl_add_u64 v[178:179], s[58:59], 0, v[198:199]
	s_mov_b32 m0, s10
	ds_read_b128 v[154:157], v239 offset:16384
	ds_read_b128 v[166:169], v239 offset:17408
	ds_read_b128 v[170:173], v239 offset:18432
	ds_read_b128 v[174:177], v239 offset:19456
	ds_read_b128 v[206:209], v239 offset:20480
	ds_read_b128 v[210:213], v239 offset:21504
	ds_read_b128 v[214:217], v239 offset:22528
	ds_read_b128 v[218:221], v239 offset:23552
	global_load_lds_dwordx4 v[178:179], off
	s_add_i32 m0, s10, 0x2000
	s_add_u32 s10, s58, 0x20000
	v_lshl_add_u64 v[180:181], s[58:59], 0, v[194:195]
	s_addc_u32 s11, s59, 0
	s_add_i32 s14, s14, s48
	global_load_lds_dwordx4 v[180:181], off
	v_lshl_add_u64 v[182:183], s[10:11], 0, v[198:199]
	s_mov_b32 m0, s14
	s_nop 0
	global_load_lds_dwordx4 v[182:183], off
	v_lshl_add_u64 v[182:183], s[10:11], 0, v[194:195]
	s_add_i32 m0, s14, 0x2000
	s_nop 0
	global_load_lds_dwordx4 v[182:183], off
	v_lshl_add_u64 v[182:183], s[60:61], 0, v[200:201]
	s_mov_b32 m0, s49
	s_nop 0
	global_load_lds_dwordx4 v[182:183], off
	v_lshl_add_u64 v[182:183], s[60:61], 0, v[196:197]
	s_mov_b32 m0, s76
	s_nop 0
	global_load_lds_dwordx4 v[182:183], off
	s_waitcnt vmcnt(8)
	s_waitcnt lgkmcnt(0)
	s_barrier
; #define PG8_STAGE(bufoff, gbase, voff) do { _Pragma("unroll") for (int _i = 0; _i < 2; ++_i) \
;         __builtin_amdgcn_global_load_lds((const unsigned*)((const char*)(gbase) + (voff)[_i]), (LAS unsigned*)(lds + (bufoff) + ldsw + _i * 8192), 16, 0, 0); } while (0)
; #define PG8_LDA(dst, b, h) do { _Pragma("unroll") for (int m = 0; m < 4; ++m) _Pragma("unroll") for (int k = 0; k < 2; ++k) dst[m][k] = *(const LAS bf16x8*)(lds + PG8_SA(b, h) + aoff + m * 2048 + k * 1024); } while (0)
; #define PG8_LDB(dst, b, h) do { _Pragma("unroll") for (int n = 0; n < 2; ++n) _Pragma("unroll") for (int k = 0; k < 2; ++k) dst[n][k] = *(const LAS bf16x8*)(lds + PG8_SB(b, h) + boff + n * 2048 + k * 1024); } while (0)
; #define PG8_MMA(ai, bj, At, Bt) do { __builtin_amdgcn_s_setprio(1); _Pragma("unroll") for (int m = 0; m < 4; ++m) _Pragma("unroll") for (int n = 0; n < 2; ++n) _Pragma("unroll") for (int k = 0; k < 2; ++k) \
;         acc[ai][bj][m][n] = __builtin_amdgcn_mfma_f32_16x16x32_bf16(Bt[n][k], At[m][k], acc[ai][bj][m][n], 0, 0, 0); __builtin_amdgcn_s_setprio(0); } while (0)
; #define PG8_WAIT_V(n) asm volatile("s_waitcnt vmcnt(" #n ")" ::: "memory")
; #define PG8_WAIT_L(n) asm volatile("s_waitcnt lgkmcnt(" #n ")" ::: "memory")
; #define PG8_BAR __builtin_amdgcn_s_barrier()
; #define PG8_SCHED __builtin_amdgcn_sched_barrier(0)
; template <class Epi, class Pre, bool AG = false>
; __device__ __forceinline__ void gemm_phase(LAS unsigned char* lds, const Gemm g, const StaticOrder& S, const Epi& E, const Pre& P) {
;     ...
;             PG8_WAIT_V(8); PG8_WAIT_L(0); PG8_BAR; PG8_MMA(1, 0, At, B0); PG8_MMA(1, 1, At, B1); PG8_BAR; PG8_SCHED;
;             PG8_LDB(B0, 1, 0); PG8_LDB(B1, 1, 1); PG8_SCHED; PG8_LDA(At, 1, 0); PG8_STAGE(PG8_SA(0, 1), a2 + hstepA, voffA);
;             PG8_WAIT_V(8); PG8_WAIT_L(0); PG8_BAR; PG8_MMA(0, 0, At, B0); PG8_MMA(0, 1, At, B1); PG8_BAR; PG8_SCHED;
	s_setprio 1
	v_mfma_f32_16x16x32_bf16 v[70:73], v[58:61], v[154:157], v[70:73]
	v_mfma_f32_16x16x32_bf16 v[66:69], v[74:77], v[154:157], v[66:69]
	v_mfma_f32_16x16x32_bf16 v[46:49], v[58:61], v[170:173], v[46:49]
	v_mfma_f32_16x16x32_bf16 v[42:45], v[74:77], v[170:173], v[42:45]
	v_mfma_f32_16x16x32_bf16 v[30:33], v[58:61], v[206:209], v[30:33]
	v_mfma_f32_16x16x32_bf16 v[26:29], v[74:77], v[206:209], v[26:29]
	v_mfma_f32_16x16x32_bf16 v[14:17], v[58:61], v[214:217], v[14:17]
	v_mfma_f32_16x16x32_bf16 v[10:13], v[74:77], v[214:217], v[10:13]
	v_mfma_f32_16x16x32_bf16 v[70:73], v[62:65], v[166:169], v[70:73]
	v_mfma_f32_16x16x32_bf16 v[66:69], v[78:81], v[166:169], v[66:69]
	v_mfma_f32_16x16x32_bf16 v[46:49], v[62:65], v[174:177], v[46:49]
	v_mfma_f32_16x16x32_bf16 v[42:45], v[78:81], v[174:177], v[42:45]
	v_mfma_f32_16x16x32_bf16 v[30:33], v[62:65], v[210:213], v[30:33]
	v_mfma_f32_16x16x32_bf16 v[26:29], v[78:81], v[210:213], v[26:29]
	v_mfma_f32_16x16x32_bf16 v[14:17], v[62:65], v[218:221], v[14:17]
	v_mfma_f32_16x16x32_bf16 v[10:13], v[78:81], v[218:221], v[10:13]
	v_mfma_f32_16x16x32_bf16 v[54:57], v[138:141], v[154:157], v[54:57]
	v_mfma_f32_16x16x32_bf16 v[50:53], v[146:149], v[154:157], v[50:53]
	v_mfma_f32_16x16x32_bf16 v[38:41], v[138:141], v[170:173], v[38:41]
	v_mfma_f32_16x16x32_bf16 v[34:37], v[146:149], v[170:173], v[34:37]
	v_mfma_f32_16x16x32_bf16 v[22:25], v[138:141], v[206:209], v[22:25]
	v_mfma_f32_16x16x32_bf16 v[18:21], v[146:149], v[206:209], v[18:21]
	v_mfma_f32_16x16x32_bf16 v[6:9], v[138:141], v[214:217], v[6:9]
	v_mfma_f32_16x16x32_bf16 v[2:5], v[146:149], v[214:217], v[2:5]
	v_mfma_f32_16x16x32_bf16 v[54:57], v[142:145], v[166:169], v[54:57]
	v_mfma_f32_16x16x32_bf16 v[50:53], v[150:153], v[166:169], v[50:53]
	v_mfma_f32_16x16x32_bf16 v[38:41], v[142:145], v[174:177], v[38:41]
	v_mfma_f32_16x16x32_bf16 v[34:37], v[150:153], v[174:177], v[34:37]
	v_mfma_f32_16x16x32_bf16 v[22:25], v[142:145], v[210:213], v[22:25]
	v_mfma_f32_16x16x32_bf16 v[18:21], v[150:153], v[210:213], v[18:21]
	v_mfma_f32_16x16x32_bf16 v[6:9], v[142:145], v[218:221], v[6:9]
	v_mfma_f32_16x16x32_bf16 v[2:5], v[150:153], v[218:221], v[2:5]
	s_setprio 0
	s_barrier
	s_add_i32 s14, 0, 0x18000
	v_add_u32_e32 v0, s14, v238
	s_add_i32 s21, 0, 0x1c000
	ds_read_b128 v[58:61], v0
	ds_read_b128 v[62:65], v0 offset:1024
	ds_read_b128 v[74:77], v0 offset:2048
	ds_read_b128 v[78:81], v0 offset:3072
	v_add_u32_e32 v0, s21, v238
	ds_read_b128 v[138:141], v0
	ds_read_b128 v[142:145], v0 offset:1024
	ds_read_b128 v[146:149], v0 offset:2048
	ds_read_b128 v[150:153], v0 offset:3072
	s_add_u32 s10, s60, 0x1000
	s_addc_u32 s11, s61, 0
	s_mov_b32 m0, s77
	v_lshl_add_u64 v[182:183], s[10:11], 0, v[200:201]
	ds_read_b128 v[154:157], v239 offset:32768
	ds_read_b128 v[166:169], v239 offset:33792
	ds_read_b128 v[170:173], v239 offset:34816
	ds_read_b128 v[174:177], v239 offset:35840
	ds_read_b128 v[206:209], v239 offset:36864
	ds_read_b128 v[210:213], v239 offset:37888
	ds_read_b128 v[214:217], v239 offset:38912
	ds_read_b128 v[218:221], v239 offset:39936
	global_load_lds_dwordx4 v[182:183], off
	v_lshl_add_u64 v[182:183], s[10:11], 0, v[196:197]
	s_mov_b32 m0, s84
	s_nop 0
	global_load_lds_dwordx4 v[182:183], off
	s_waitcnt vmcnt(8)
	s_waitcnt lgkmcnt(0)
	s_barrier
	s_setprio 1
	v_mfma_f32_16x16x32_bf16 v[162:165], v[58:61], v[154:157], v[162:165]
	v_mfma_f32_16x16x32_bf16 v[158:161], v[74:77], v[154:157], v[158:161]
	v_mfma_f32_16x16x32_bf16 v[126:129], v[58:61], v[170:173], v[126:129]
	v_mfma_f32_16x16x32_bf16 v[122:125], v[74:77], v[170:173], v[122:125]
	v_mfma_f32_16x16x32_bf16 v[110:113], v[58:61], v[206:209], v[110:113]
	v_mfma_f32_16x16x32_bf16 v[106:109], v[74:77], v[206:209], v[106:109]
	v_mfma_f32_16x16x32_bf16 v[94:97], v[58:61], v[214:217], v[94:97]
	v_mfma_f32_16x16x32_bf16 v[90:93], v[74:77], v[214:217], v[90:93]
	v_mfma_f32_16x16x32_bf16 v[162:165], v[62:65], v[166:169], v[162:165]
	v_mfma_f32_16x16x32_bf16 v[158:161], v[78:81], v[166:169], v[158:161]
	v_mfma_f32_16x16x32_bf16 v[126:129], v[62:65], v[174:177], v[126:129]
	v_mfma_f32_16x16x32_bf16 v[122:125], v[78:81], v[174:177], v[122:125]
	v_mfma_f32_16x16x32_bf16 v[110:113], v[62:65], v[210:213], v[110:113]
	v_mfma_f32_16x16x32_bf16 v[106:109], v[78:81], v[210:213], v[106:109]
	v_mfma_f32_16x16x32_bf16 v[94:97], v[62:65], v[218:221], v[94:97]
	v_mfma_f32_16x16x32_bf16 v[90:93], v[78:81], v[218:221], v[90:93]
	v_mfma_f32_16x16x32_bf16 v[134:137], v[138:141], v[154:157], v[134:137]
	v_mfma_f32_16x16x32_bf16 v[130:133], v[146:149], v[154:157], v[130:133]
	v_mfma_f32_16x16x32_bf16 v[118:121], v[138:141], v[170:173], v[118:121]
	v_mfma_f32_16x16x32_bf16 v[114:117], v[146:149], v[170:173], v[114:117]
	v_mfma_f32_16x16x32_bf16 v[102:105], v[138:141], v[206:209], v[102:105]
	v_mfma_f32_16x16x32_bf16 v[98:101], v[146:149], v[206:209], v[98:101]
	v_mfma_f32_16x16x32_bf16 v[86:89], v[138:141], v[214:217], v[86:89]
	v_mfma_f32_16x16x32_bf16 v[82:85], v[146:149], v[214:217], v[82:85]
	v_mfma_f32_16x16x32_bf16 v[134:137], v[142:145], v[166:169], v[134:137]
	v_mfma_f32_16x16x32_bf16 v[130:133], v[150:153], v[166:169], v[130:133]
	v_mfma_f32_16x16x32_bf16 v[118:121], v[142:145], v[174:177], v[118:121]
	v_mfma_f32_16x16x32_bf16 v[114:117], v[150:153], v[174:177], v[114:117]
	v_mfma_f32_16x16x32_bf16 v[102:105], v[142:145], v[210:213], v[102:105]
	v_mfma_f32_16x16x32_bf16 v[98:101], v[150:153], v[210:213], v[98:101]
	v_mfma_f32_16x16x32_bf16 v[86:89], v[142:145], v[218:221], v[86:89]
	v_mfma_f32_16x16x32_bf16 v[82:85], v[150:153], v[218:221], v[82:85]
	s_setprio 0
	s_barrier
; #define PG8_STAGE(bufoff, gbase, voff) do { _Pragma("unroll") for (int _i = 0; _i < 2; ++_i) \
;         __builtin_amdgcn_global_load_lds((const unsigned*)((const char*)(gbase) + (voff)[_i]), (LAS unsigned*)(lds + (bufoff) + ldsw + _i * 8192), 16, 0, 0); } while (0)
; #define PG8_LDA(dst, b, h) do { _Pragma("unroll") for (int m = 0; m < 4; ++m) _Pragma("unroll") for (int k = 0; k < 2; ++k) dst[m][k] = *(const LAS bf16x8*)(lds + PG8_SA(b, h) + aoff + m * 2048 + k * 1024); } while (0)
; #define PG8_MMA(ai, bj, At, Bt) do { __builtin_amdgcn_s_setprio(1); _Pragma("unroll") for (int m = 0; m < 4; ++m) _Pragma("unroll") for (int n = 0; n < 2; ++n) _Pragma("unroll") for (int k = 0; k < 2; ++k) \
;         acc[ai][bj][m][n] = __builtin_amdgcn_mfma_f32_16x16x32_bf16(Bt[n][k], At[m][k], acc[ai][bj][m][n], 0, 0, 0); __builtin_amdgcn_s_setprio(0); } while (0)
; #define PG8_WAIT_V(n) asm volatile("s_waitcnt vmcnt(" #n ")" ::: "memory")
; #define PG8_WAIT_L(n) asm volatile("s_waitcnt lgkmcnt(" #n ")" ::: "memory")
; #define PG8_BAR __builtin_amdgcn_s_barrier()
; #define PG8_SCHED __builtin_amdgcn_sched_barrier(0)
; template <class Epi, class Pre, bool AG = false>
; __device__ __forceinline__ void gemm_phase(LAS unsigned char* lds, const Gemm g, const StaticOrder& S, const Epi& E, const Pre& P) {
;     ...
;             PG8_LDA(At, 1, 1); PG8_STAGE(PG8_SB(1, 0), b3, voffB); PG8_STAGE(PG8_SB(1, 1), b3 + hstep, voffB); PG8_STAGE(PG8_SA(1, 0), a3, voffA);
;             PG8_WAIT_V(8); PG8_WAIT_L(0); PG8_BAR; PG8_MMA(1, 0, At, B0); PG8_MMA(1, 1, At, B1); PG8_BAR; PG8_SCHED;
;         }
;         if (wr == 0) PG8_BAR;
	s_add_i32 s10, s14, s48
	v_lshl_add_u64 v[178:179], v[178:179], 0, s[66:67]
	s_mov_b32 m0, s10
	ds_read_b128 v[154:157], v239 offset:49152
	ds_read_b128 v[166:169], v239 offset:50176
	ds_read_b128 v[170:173], v239 offset:51200
	ds_read_b128 v[174:177], v239 offset:52224
	ds_read_b128 v[206:209], v239 offset:53248
	ds_read_b128 v[210:213], v239 offset:54272
	ds_read_b128 v[214:217], v239 offset:55296
	ds_read_b128 v[218:221], v239 offset:56320
	global_load_lds_dwordx4 v[178:179], off
	s_add_i32 m0, s10, 0x2000
	s_add_u32 s10, s58, 0x20080
	v_lshl_add_u64 v[178:179], v[180:181], 0, s[66:67]
	s_addc_u32 s11, s59, 0
	s_add_i32 s14, s21, s48
	global_load_lds_dwordx4 v[178:179], off
	v_lshl_add_u64 v[178:179], s[10:11], 0, v[198:199]
	s_mov_b32 m0, s14
	s_nop 0
	global_load_lds_dwordx4 v[178:179], off
	v_lshl_add_u64 v[178:179], s[10:11], 0, v[194:195]
	s_add_i32 m0, s14, 0x2000
	s_nop 0
	global_load_lds_dwordx4 v[178:179], off
	v_lshl_add_u64 v[178:179], s[56:57], 0, v[200:201]
	s_mov_b32 m0, s24
	s_nop 0
	global_load_lds_dwordx4 v[178:179], off
	v_lshl_add_u64 v[178:179], s[56:57], 0, v[196:197]
	s_mov_b32 m0, s25
	s_nop 0
	global_load_lds_dwordx4 v[178:179], off
	s_waitcnt vmcnt(8)
	s_waitcnt lgkmcnt(0)
	s_barrier
	s_setprio 1
	v_mfma_f32_16x16x32_bf16 v[70:73], v[58:61], v[154:157], v[70:73]
	v_mfma_f32_16x16x32_bf16 v[66:69], v[74:77], v[154:157], v[66:69]
	v_mfma_f32_16x16x32_bf16 v[46:49], v[58:61], v[170:173], v[46:49]
	v_mfma_f32_16x16x32_bf16 v[42:45], v[74:77], v[170:173], v[42:45]
	v_mfma_f32_16x16x32_bf16 v[30:33], v[58:61], v[206:209], v[30:33]
	v_mfma_f32_16x16x32_bf16 v[26:29], v[74:77], v[206:209], v[26:29]
	v_mfma_f32_16x16x32_bf16 v[14:17], v[58:61], v[214:217], v[14:17]
	v_mfma_f32_16x16x32_bf16 v[10:13], v[74:77], v[214:217], v[10:13]
	v_mfma_f32_16x16x32_bf16 v[70:73], v[62:65], v[166:169], v[70:73]
	v_mfma_f32_16x16x32_bf16 v[66:69], v[78:81], v[166:169], v[66:69]
	v_mfma_f32_16x16x32_bf16 v[46:49], v[62:65], v[174:177], v[46:49]
	v_mfma_f32_16x16x32_bf16 v[42:45], v[78:81], v[174:177], v[42:45]
	v_mfma_f32_16x16x32_bf16 v[30:33], v[62:65], v[210:213], v[30:33]
	v_mfma_f32_16x16x32_bf16 v[26:29], v[78:81], v[210:213], v[26:29]
	v_mfma_f32_16x16x32_bf16 v[14:17], v[62:65], v[218:221], v[14:17]
	v_mfma_f32_16x16x32_bf16 v[10:13], v[78:81], v[218:221], v[10:13]
	v_mfma_f32_16x16x32_bf16 v[54:57], v[138:141], v[154:157], v[54:57]
	v_mfma_f32_16x16x32_bf16 v[50:53], v[146:149], v[154:157], v[50:53]
	v_mfma_f32_16x16x32_bf16 v[38:41], v[138:141], v[170:173], v[38:41]
	v_mfma_f32_16x16x32_bf16 v[34:37], v[146:149], v[170:173], v[34:37]
	v_mfma_f32_16x16x32_bf16 v[22:25], v[138:141], v[206:209], v[22:25]
	v_mfma_f32_16x16x32_bf16 v[18:21], v[146:149], v[206:209], v[18:21]
	v_mfma_f32_16x16x32_bf16 v[6:9], v[138:141], v[214:217], v[6:9]
	v_mfma_f32_16x16x32_bf16 v[2:5], v[146:149], v[214:217], v[2:5]
	v_mfma_f32_16x16x32_bf16 v[54:57], v[142:145], v[166:169], v[54:57]
	v_mfma_f32_16x16x32_bf16 v[50:53], v[150:153], v[166:169], v[50:53]
	v_mfma_f32_16x16x32_bf16 v[38:41], v[142:145], v[174:177], v[38:41]
	v_mfma_f32_16x16x32_bf16 v[34:37], v[150:153], v[174:177], v[34:37]
	v_mfma_f32_16x16x32_bf16 v[22:25], v[142:145], v[210:213], v[22:25]
	v_mfma_f32_16x16x32_bf16 v[18:21], v[150:153], v[210:213], v[18:21]
	v_mfma_f32_16x16x32_bf16 v[6:9], v[142:145], v[218:221], v[6:9]
	v_mfma_f32_16x16x32_bf16 v[2:5], v[150:153], v[218:221], v[2:5]
	s_setprio 0
	s_barrier
	s_add_i32 s87, s87, 2
	s_add_u32 vcc_lo, vcc_lo, 0x100
	s_addc_u32 vcc_hi, vcc_hi, 0
	s_cmp_gt_u32 s87, 5
	s_mov_b64 s[10:11], s[54:55]
	s_cbranch_scc0 .LBB0_741
	s_and_b64 vcc, exec, s[94:95]
	s_cbranch_vccz .LBB0_744
	s_barrier

; #define PG8_STAGE(bufoff, gbase, voff) do { _Pragma("unroll") for (int _i = 0; _i < 2; ++_i) \
;         __builtin_amdgcn_global_load_lds((const unsigned*)((const char*)(gbase) + (voff)[_i]), (LAS unsigned*)(lds + (bufoff) + ldsw + _i * 8192), 16, 0, 0); } while (0)
; #define PG8_LDA(dst, b, h) do { _Pragma("unroll") for (int m = 0; m < 4; ++m) _Pragma("unroll") for (int k = 0; k < 2; ++k) dst[m][k] = *(const LAS bf16x8*)(lds + PG8_SA(b, h) + aoff + m * 2048 + k * 1024); } while (0)
; #define PG8_LDB(dst, b, h) do { _Pragma("unroll") for (int n = 0; n < 2; ++n) _Pragma("unroll") for (int k = 0; k < 2; ++k) dst[n][k] = *(const LAS bf16x8*)(lds + PG8_SB(b, h) + boff + n * 2048 + k * 1024); } while (0)
; #define PG8_WAIT_V(n) asm volatile("s_waitcnt vmcnt(" #n ")" ::: "memory")
; #define PG8_WAIT_L(n) asm volatile("s_waitcnt lgkmcnt(" #n ")" ::: "memory")
; #define PG8_BAR __builtin_amdgcn_s_barrier()
; #define PG8_SCHED __builtin_amdgcn_sched_barrier(0)
; template <class Epi, class Pre, bool AG = false>
; __device__ __forceinline__ void gemm_phase(LAS unsigned char* lds, const Gemm g, const StaticOrder& S, const Epi& E, const Pre& P) {
;     ...
;         const bool has_next = S.next(ui + 1, nxt);
;         const char* nA = has_next ? (const char*)g.A + (size_t)nxt.pm * tstepA : cA; const char* nB = has_next ? (const char*)g.Bt + (size_t)nxt.pn * tstep : cB;
;         for (int t = 0; t < nt; t += 2) {
;             const bool last = (t == nt - 2);
;             const char* a1 = cA + (size_t)(t + 1) * kstepA;
;             const char* a2 = last ? nA : cA + (size_t)(t + 2) * kstepA; const char* b2 = last ? nB : cB + (size_t)(t + 2) * kstep;
;             const char* a3 = a2 + kstepA; const char* b3 = b2 + kstep;
;             if constexpr (Epi::MIDK) { if (t == E.midk_t) E.mid(acc, cur, ui, wr, wc, fr, fq); }
;             PG8_LDB(B0, 0, 0); PG8_LDB(B1, 0, 1); PG8_SCHED; PG8_LDA(At, 0, 0); PG8_STAGE(PG8_SA(1, 1), a1 + hstepA, voffA);
;             PG8_WAIT_V(8); PG8_WAIT_L(0); PG8_BAR; PG8_MMA(0, 0, At, B0); PG8_MMA(0, 1, At, B1); PG8_BAR; PG8_SCHED;
;             PG8_LDA(At, 0, 1); PG8_STAGE(PG8_SB(0, 0), b2, voffB); PG8_STAGE(PG8_SB(0, 1), b2 + hstep, voffB); PG8_STAGE(PG8_SA(0, 0), a2, voffA);
;             PG8_WAIT_V(8); PG8_WAIT_L(0); PG8_BAR; PG8_MMA(1, 0, At, B0); PG8_MMA(1, 1, At, B1); PG8_BAR; PG8_SCHED;
.LBB0_782:
	s_ashr_i32 s43, s42, 31
	s_lshl_b64 s[12:13], s[42:43], 17
	s_add_u32 s44, s25, s12
	s_addc_u32 s45, s30, s13
	s_and_b64 s[12:13], s[8:9], exec
	s_cselect_b32 s71, s45, s57
	s_cselect_b32 s70, s44, s56
	s_ashr_i32 s29, s28, 31
	s_lshl_b64 s[12:13], s[28:29], 17
	s_add_u32 s46, s31, s12
	s_addc_u32 s47, s38, s13
	s_and_b64 s[12:13], s[8:9], exec
	s_cselect_b32 s61, s47, s59
	s_cselect_b32 s60, s46, s58
	s_add_i32 s85, 0, 0x10000
	s_add_i32 s29, 0, 0x14000
	v_add_u32_e32 v184, s85, v138
	v_add_u32_e32 v185, s29, v138
	ds_read_b128 v[2:5], v184
	ds_read_b128 v[6:9], v184 offset:1024
	ds_read_b128 v[10:13], v184 offset:2048
	ds_read_b128 v[14:17], v184 offset:3072
	ds_read_b128 v[18:21], v185
	ds_read_b128 v[22:25], v185 offset:1024
	ds_read_b128 v[26:29], v185 offset:2048
	ds_read_b128 v[30:33], v185 offset:3072
	v_mov_b32_e32 v237, 0x358637bd
	v_mov_b32_e32 v236, v234
	s_add_u32 s12, s56, 0x10080
	s_addc_u32 s13, s57, 0
	s_add_i32 s87, s48, 0xc000
	v_lshl_add_u64 v[66:67], s[12:13], 0, v[130:131]
	s_mov_b32 m0, s87
	ds_read_b128 v[34:37], v139
	ds_read_b128 v[38:41], v139 offset:1024
	ds_read_b128 v[42:45], v139 offset:2048
	ds_read_b128 v[46:49], v139 offset:3072
	ds_read_b128 v[50:53], v139 offset:4096
	ds_read_b128 v[54:57], v139 offset:5120
	ds_read_b128 v[58:61], v139 offset:6144
	ds_read_b128 v[62:65], v139 offset:7168
	global_load_lds_dwordx4 v[66:67], off
	v_lshl_add_u64 v[66:67], s[12:13], 0, v[132:133]
	s_add_i32 s12, s48, 0xe000
	s_mov_b32 m0, s12
	s_nop 0
	global_load_lds_dwordx4 v[66:67], off
	s_waitcnt vmcnt(8)
	s_waitcnt lgkmcnt(0)
	s_barrier
	s_setprio 1
	v_mfma_f32_16x16x32_bf16 v[66:69], v[2:5], v[34:37], 0
	v_mfma_f32_16x16x32_bf16 v[70:73], v[10:13], v[34:37], 0
	v_mfma_f32_16x16x32_bf16 v[74:77], v[2:5], v[42:45], 0
	v_mfma_f32_16x16x32_bf16 v[78:81], v[10:13], v[42:45], 0
	v_mfma_f32_16x16x32_bf16 v[82:85], v[2:5], v[50:53], 0
	v_mfma_f32_16x16x32_bf16 v[86:89], v[10:13], v[50:53], 0
	v_mfma_f32_16x16x32_bf16 v[90:93], v[2:5], v[58:61], 0
	v_mfma_f32_16x16x32_bf16 v[94:97], v[10:13], v[58:61], 0
	v_mfma_f32_16x16x32_bf16 v[66:69], v[6:9], v[38:41], v[66:69]
	v_mfma_f32_16x16x32_bf16 v[70:73], v[14:17], v[38:41], v[70:73]
	v_mfma_f32_16x16x32_bf16 v[74:77], v[6:9], v[46:49], v[74:77]
	v_mfma_f32_16x16x32_bf16 v[78:81], v[14:17], v[46:49], v[78:81]
	v_mfma_f32_16x16x32_bf16 v[82:85], v[6:9], v[54:57], v[82:85]
	v_mfma_f32_16x16x32_bf16 v[86:89], v[14:17], v[54:57], v[86:89]
	v_mfma_f32_16x16x32_bf16 v[90:93], v[6:9], v[62:65], v[90:93]
	v_mfma_f32_16x16x32_bf16 v[94:97], v[14:17], v[62:65], v[94:97]
	v_mfma_f32_16x16x32_bf16 v[98:101], v[18:21], v[34:37], 0
	v_mfma_f32_16x16x32_bf16 v[34:37], v[26:29], v[34:37], 0
	v_mfma_f32_16x16x32_bf16 v[98:101], v[22:25], v[38:41], v[98:101]
	v_mfma_f32_16x16x32_bf16 v[34:37], v[30:33], v[38:41], v[34:37]
	v_mfma_f32_16x16x32_bf16 v[38:41], v[18:21], v[42:45], 0
	v_mfma_f32_16x16x32_bf16 v[42:45], v[26:29], v[42:45], 0
	v_mfma_f32_16x16x32_bf16 v[38:41], v[22:25], v[46:49], v[38:41]
	v_mfma_f32_16x16x32_bf16 v[42:45], v[30:33], v[46:49], v[42:45]
	v_mfma_f32_16x16x32_bf16 v[46:49], v[18:21], v[50:53], 0
	v_mfma_f32_16x16x32_bf16 v[50:53], v[26:29], v[50:53], 0
	v_mfma_f32_16x16x32_bf16 v[46:49], v[22:25], v[54:57], v[46:49]
	v_mfma_f32_16x16x32_bf16 v[50:53], v[30:33], v[54:57], v[50:53]
	v_mfma_f32_16x16x32_bf16 v[54:57], v[18:21], v[58:61], 0
	v_mfma_f32_16x16x32_bf16 v[58:61], v[26:29], v[58:61], 0
	v_mfma_f32_16x16x32_bf16 v[54:57], v[22:25], v[62:65], v[54:57]
	v_mfma_f32_16x16x32_bf16 v[58:61], v[30:33], v[62:65], v[58:61]
	s_setprio 0
	s_barrier
	s_add_i32 s85, s85, s24
	v_lshl_add_u64 v[136:137], s[58:59], 0, v[0:1]
	s_add_i32 s13, s85, 0x2000
	v_lshl_add_u64 v[140:141], v[136:137], 0, s[68:69]
	s_mov_b32 m0, s85
	v_lshl_add_u64 v[176:177], s[58:59], 0, v[134:135]
	s_add_u32 s94, s58, 0x10100
	ds_read_b128 v[62:65], v139 offset:16384
	ds_read_b128 v[102:105], v139 offset:17408
	ds_read_b128 v[106:109], v139 offset:18432
	ds_read_b128 v[110:113], v139 offset:19456
	ds_read_b128 v[114:117], v139 offset:20480
	ds_read_b128 v[118:121], v139 offset:21504
	ds_read_b128 v[122:125], v139 offset:22528
	ds_read_b128 v[126:129], v139 offset:23552
	global_load_lds_dwordx4 v[140:141], off
	v_lshl_add_u64 v[140:141], v[176:177], 0, s[68:69]
	s_mov_b32 m0, s13
	s_addc_u32 s95, s59, 0
	s_add_i32 s29, s29, s24
	global_load_lds_dwordx4 v[140:141], off
	v_lshl_add_u64 v[140:141], s[94:95], 0, v[0:1]
	s_mov_b32 m0, s29
	s_add_i32 s43, s29, 0x2000
	global_load_lds_dwordx4 v[140:141], off
	v_lshl_add_u64 v[140:141], s[94:95], 0, v[134:135]
	s_mov_b32 m0, s43
	v_lshl_add_u64 v[178:179], s[56:57], 0, v[130:131]
	global_load_lds_dwordx4 v[140:141], off
	v_lshl_add_u64 v[140:141], v[178:179], 0, s[68:69]
	s_mov_b32 m0, s48
	v_lshl_add_u64 v[180:181], s[56:57], 0, v[132:133]
	global_load_lds_dwordx4 v[140:141], off
	v_lshl_add_u64 v[140:141], v[180:181], 0, s[68:69]
	s_mov_b32 m0, s49
	s_nop 0
	global_load_lds_dwordx4 v[140:141], off
	s_waitcnt vmcnt(8)
	s_waitcnt lgkmcnt(0)
	s_barrier
; #define PG8_STAGE(bufoff, gbase, voff) do { _Pragma("unroll") for (int _i = 0; _i < 2; ++_i) \
;         __builtin_amdgcn_global_load_lds((const unsigned*)((const char*)(gbase) + (voff)[_i]), (LAS unsigned*)(lds + (bufoff) + ldsw + _i * 8192), 16, 0, 0); } while (0)
; #define PG8_LDA(dst, b, h) do { _Pragma("unroll") for (int m = 0; m < 4; ++m) _Pragma("unroll") for (int k = 0; k < 2; ++k) dst[m][k] = *(const LAS bf16x8*)(lds + PG8_SA(b, h) + aoff + m * 2048 + k * 1024); } while (0)
; #define PG8_LDB(dst, b, h) do { _Pragma("unroll") for (int n = 0; n < 2; ++n) _Pragma("unroll") for (int k = 0; k < 2; ++k) dst[n][k] = *(const LAS bf16x8*)(lds + PG8_SB(b, h) + boff + n * 2048 + k * 1024); } while (0)
; #define PG8_MMA(ai, bj, At, Bt) do { __builtin_amdgcn_s_setprio(1); _Pragma("unroll") for (int m = 0; m < 4; ++m) _Pragma("unroll") for (int n = 0; n < 2; ++n) _Pragma("unroll") for (int k = 0; k < 2; ++k) \
;         acc[ai][bj][m][n] = __builtin_amdgcn_mfma_f32_16x16x32_bf16(Bt[n][k], At[m][k], acc[ai][bj][m][n], 0, 0, 0); __builtin_amdgcn_s_setprio(0); } while (0)
; #define PG8_WAIT_V(n) asm volatile("s_waitcnt vmcnt(" #n ")" ::: "memory")
; #define PG8_WAIT_L(n) asm volatile("s_waitcnt lgkmcnt(" #n ")" ::: "memory")
; #define PG8_BAR __builtin_amdgcn_s_barrier()
; #define PG8_SCHED __builtin_amdgcn_sched_barrier(0)
; template <class Epi, class Pre, bool AG = false>
; __device__ __forceinline__ void gemm_phase(LAS unsigned char* lds, const Gemm g, const StaticOrder& S, const Epi& E, const Pre& P) {
;     ...
;             PG8_WAIT_V(8); PG8_WAIT_L(0); PG8_BAR; PG8_MMA(1, 0, At, B0); PG8_MMA(1, 1, At, B1); PG8_BAR; PG8_SCHED;
;             PG8_LDB(B0, 1, 0); PG8_LDB(B1, 1, 1); PG8_SCHED; PG8_LDA(At, 1, 0); PG8_STAGE(PG8_SA(0, 1), a2 + hstepA, voffA);
;             PG8_WAIT_V(8); PG8_WAIT_L(0); PG8_BAR; PG8_MMA(0, 0, At, B0); PG8_MMA(0, 1, At, B1); PG8_BAR; PG8_SCHED;
	s_setprio 1
	v_mfma_f32_16x16x32_bf16 v[140:143], v[2:5], v[62:65], 0
	v_mfma_f32_16x16x32_bf16 v[148:151], v[2:5], v[106:109], 0
	v_mfma_f32_16x16x32_bf16 v[156:159], v[2:5], v[114:117], 0
	v_mfma_f32_16x16x32_bf16 v[2:5], v[2:5], v[122:125], 0
	v_mfma_f32_16x16x32_bf16 v[140:143], v[6:9], v[102:105], v[140:143]
	v_mfma_f32_16x16x32_bf16 v[148:151], v[6:9], v[110:113], v[148:151]
	v_mfma_f32_16x16x32_bf16 v[156:159], v[6:9], v[118:121], v[156:159]
	v_mfma_f32_16x16x32_bf16 v[2:5], v[6:9], v[126:129], v[2:5]
	v_mfma_f32_16x16x32_bf16 v[6:9], v[10:13], v[122:125], 0
	v_mfma_f32_16x16x32_bf16 v[144:147], v[10:13], v[62:65], 0
	v_mfma_f32_16x16x32_bf16 v[152:155], v[10:13], v[106:109], 0
	v_mfma_f32_16x16x32_bf16 v[160:163], v[10:13], v[114:117], 0
	v_mfma_f32_16x16x32_bf16 v[6:9], v[14:17], v[126:129], v[6:9]
	v_mfma_f32_16x16x32_bf16 v[144:147], v[14:17], v[102:105], v[144:147]
	v_mfma_f32_16x16x32_bf16 v[152:155], v[14:17], v[110:113], v[152:155]
	v_mfma_f32_16x16x32_bf16 v[160:163], v[14:17], v[118:121], v[160:163]
	v_mfma_f32_16x16x32_bf16 v[10:13], v[18:21], v[62:65], 0
	v_mfma_f32_16x16x32_bf16 v[14:17], v[26:29], v[62:65], 0
	v_mfma_f32_16x16x32_bf16 v[10:13], v[22:25], v[102:105], v[10:13]
	v_mfma_f32_16x16x32_bf16 v[14:17], v[30:33], v[102:105], v[14:17]
	v_mfma_f32_16x16x32_bf16 v[62:65], v[18:21], v[106:109], 0
	v_mfma_f32_16x16x32_bf16 v[102:105], v[26:29], v[106:109], 0
	v_mfma_f32_16x16x32_bf16 v[106:109], v[18:21], v[114:117], 0
	v_mfma_f32_16x16x32_bf16 v[18:21], v[18:21], v[122:125], 0
	v_mfma_f32_16x16x32_bf16 v[62:65], v[22:25], v[110:113], v[62:65]
	v_mfma_f32_16x16x32_bf16 v[102:105], v[30:33], v[110:113], v[102:105]
	v_mfma_f32_16x16x32_bf16 v[106:109], v[22:25], v[118:121], v[106:109]
	v_mfma_f32_16x16x32_bf16 v[110:113], v[26:29], v[114:117], 0
	v_mfma_f32_16x16x32_bf16 v[18:21], v[22:25], v[126:129], v[18:21]
	v_mfma_f32_16x16x32_bf16 v[22:25], v[26:29], v[122:125], 0
	v_mfma_f32_16x16x32_bf16 v[110:113], v[30:33], v[118:121], v[110:113]
	v_mfma_f32_16x16x32_bf16 v[22:25], v[30:33], v[126:129], v[22:25]
	s_setprio 0
	s_barrier
	s_add_i32 s14, 0, 0x18000
	s_add_i32 s21, 0, 0x1c000
	v_add_u32_e32 v188, s14, v138
	v_add_u32_e32 v189, s21, v138
	ds_read_b128 v[26:29], v188
	ds_read_b128 v[30:33], v188 offset:1024
	ds_read_b128 v[114:117], v188 offset:2048
	ds_read_b128 v[118:121], v188 offset:3072
	ds_read_b128 v[122:125], v189
	ds_read_b128 v[126:129], v189 offset:1024
	ds_read_b128 v[164:167], v189 offset:2048
	ds_read_b128 v[168:171], v189 offset:3072
	s_add_u32 s94, s56, 0x10100
	s_addc_u32 s95, s57, 0
	s_mov_b32 m0, s53
	v_lshl_add_u64 v[182:183], s[94:95], 0, v[130:131]
	ds_read_b128 v[172:175], v139 offset:32768
	ds_read_b128 v[194:197], v139 offset:33792
	ds_read_b128 v[198:201], v139 offset:34816
	ds_read_b128 v[202:205], v139 offset:35840
	ds_read_b128 v[206:209], v139 offset:36864
	ds_read_b128 v[210:213], v139 offset:37888
	ds_read_b128 v[214:217], v139 offset:38912
	ds_read_b128 v[218:221], v139 offset:39936
	global_load_lds_dwordx4 v[182:183], off
	v_lshl_add_u64 v[182:183], s[94:95], 0, v[132:133]
	s_mov_b32 m0, s55
	s_nop 0
	global_load_lds_dwordx4 v[182:183], off
	s_waitcnt vmcnt(8)
	s_waitcnt lgkmcnt(0)
	s_barrier
	s_setprio 1
	v_mfma_f32_16x16x32_bf16 v[66:69], v[26:29], v[172:175], v[66:69]
	v_mfma_f32_16x16x32_bf16 v[70:73], v[114:117], v[172:175], v[70:73]
	v_mfma_f32_16x16x32_bf16 v[74:77], v[26:29], v[198:201], v[74:77]
	v_mfma_f32_16x16x32_bf16 v[78:81], v[114:117], v[198:201], v[78:81]
	v_mfma_f32_16x16x32_bf16 v[82:85], v[26:29], v[206:209], v[82:85]
	v_mfma_f32_16x16x32_bf16 v[86:89], v[114:117], v[206:209], v[86:89]
	v_mfma_f32_16x16x32_bf16 v[90:93], v[26:29], v[214:217], v[90:93]
	v_mfma_f32_16x16x32_bf16 v[94:97], v[114:117], v[214:217], v[94:97]
	v_mfma_f32_16x16x32_bf16 v[66:69], v[30:33], v[194:197], v[66:69]
	v_mfma_f32_16x16x32_bf16 v[70:73], v[118:121], v[194:197], v[70:73]
	v_mfma_f32_16x16x32_bf16 v[74:77], v[30:33], v[202:205], v[74:77]
	v_mfma_f32_16x16x32_bf16 v[78:81], v[118:121], v[202:205], v[78:81]
	v_mfma_f32_16x16x32_bf16 v[82:85], v[30:33], v[210:213], v[82:85]
	v_mfma_f32_16x16x32_bf16 v[86:89], v[118:121], v[210:213], v[86:89]
	v_mfma_f32_16x16x32_bf16 v[90:93], v[30:33], v[218:221], v[90:93]
	v_mfma_f32_16x16x32_bf16 v[94:97], v[118:121], v[218:221], v[94:97]
	v_mfma_f32_16x16x32_bf16 v[98:101], v[122:125], v[172:175], v[98:101]
	v_mfma_f32_16x16x32_bf16 v[34:37], v[164:167], v[172:175], v[34:37]
	v_mfma_f32_16x16x32_bf16 v[38:41], v[122:125], v[198:201], v[38:41]
	v_mfma_f32_16x16x32_bf16 v[42:45], v[164:167], v[198:201], v[42:45]
	v_mfma_f32_16x16x32_bf16 v[46:49], v[122:125], v[206:209], v[46:49]
	v_mfma_f32_16x16x32_bf16 v[50:53], v[164:167], v[206:209], v[50:53]
	v_mfma_f32_16x16x32_bf16 v[54:57], v[122:125], v[214:217], v[54:57]
	v_mfma_f32_16x16x32_bf16 v[58:61], v[164:167], v[214:217], v[58:61]
	v_mfma_f32_16x16x32_bf16 v[98:101], v[126:129], v[194:197], v[98:101]
	v_mfma_f32_16x16x32_bf16 v[34:37], v[168:171], v[194:197], v[34:37]
	v_mfma_f32_16x16x32_bf16 v[38:41], v[126:129], v[202:205], v[38:41]
	v_mfma_f32_16x16x32_bf16 v[42:45], v[168:171], v[202:205], v[42:45]
	v_mfma_f32_16x16x32_bf16 v[46:49], v[126:129], v[210:213], v[46:49]
	v_mfma_f32_16x16x32_bf16 v[50:53], v[168:171], v[210:213], v[50:53]
	v_mfma_f32_16x16x32_bf16 v[54:57], v[126:129], v[218:221], v[54:57]
	v_mfma_f32_16x16x32_bf16 v[58:61], v[168:171], v[218:221], v[58:61]
	s_setprio 0
	s_barrier
; #define PG8_STAGE(bufoff, gbase, voff) do { _Pragma("unroll") for (int _i = 0; _i < 2; ++_i) \
;         __builtin_amdgcn_global_load_lds((const unsigned*)((const char*)(gbase) + (voff)[_i]), (LAS unsigned*)(lds + (bufoff) + ldsw + _i * 8192), 16, 0, 0); } while (0)
; #define PG8_LDA(dst, b, h) do { _Pragma("unroll") for (int m = 0; m < 4; ++m) _Pragma("unroll") for (int k = 0; k < 2; ++k) dst[m][k] = *(const LAS bf16x8*)(lds + PG8_SA(b, h) + aoff + m * 2048 + k * 1024); } while (0)
; #define PG8_LDB(dst, b, h) do { _Pragma("unroll") for (int n = 0; n < 2; ++n) _Pragma("unroll") for (int k = 0; k < 2; ++k) dst[n][k] = *(const LAS bf16x8*)(lds + PG8_SB(b, h) + boff + n * 2048 + k * 1024); } while (0)
; #define PG8_MMA(ai, bj, At, Bt) do { __builtin_amdgcn_s_setprio(1); _Pragma("unroll") for (int m = 0; m < 4; ++m) _Pragma("unroll") for (int n = 0; n < 2; ++n) _Pragma("unroll") for (int k = 0; k < 2; ++k) \
;         acc[ai][bj][m][n] = __builtin_amdgcn_mfma_f32_16x16x32_bf16(Bt[n][k], At[m][k], acc[ai][bj][m][n], 0, 0, 0); __builtin_amdgcn_s_setprio(0); } while (0)
; #define PG8_WAIT_V(n) asm volatile("s_waitcnt vmcnt(" #n ")" ::: "memory")
; template <class Epi, class Pre, bool AG = false>
; __device__ __forceinline__ void gemm_phase(LAS unsigned char* lds, const Gemm g, const StaticOrder& S, const Epi& E, const Pre& P) {
;     ...
;             PG8_LDB(B0, 0, 0); PG8_LDB(B1, 0, 1); PG8_SCHED; PG8_LDA(At, 0, 0); PG8_STAGE(PG8_SA(1, 1), a1 + hstepA, voffA);
;             PG8_WAIT_V(8); PG8_WAIT_L(0); PG8_BAR; PG8_MMA(0, 0, At, B0); PG8_MMA(0, 1, At, B1); PG8_BAR; PG8_SCHED;
;             PG8_LDA(At, 0, 1); PG8_STAGE(PG8_SB(0, 0), b2, voffB); PG8_STAGE(PG8_SB(0, 1), b2 + hstep, voffB); PG8_STAGE(PG8_SA(0, 0), a2, voffA);
;             PG8_WAIT_V(8); PG8_WAIT_L(0); PG8_BAR; PG8_MMA(1, 0, At, B0); PG8_MMA(1, 1, At, B1); PG8_BAR; PG8_SCHED;
;             PG8_LDB(B0, 1, 0); PG8_LDB(B1, 1, 1); PG8_SCHED; PG8_LDA(At, 1, 0); PG8_STAGE(PG8_SA(0, 1), a2 + hstepA, voffA);
;             PG8_WAIT_V(8); PG8_WAIT_L(0); PG8_BAR; PG8_MMA(0, 0, At, B0); PG8_MMA(0, 1, At, B1); PG8_BAR; PG8_SCHED;
;             PG8_LDA(At, 1, 1); PG8_STAGE(PG8_SB(1, 0), b3, voffB); PG8_STAGE(PG8_SB(1, 1), b3 + hstep, voffB); PG8_STAGE(PG8_SA(1, 0), a3, voffA);
;             PG8_WAIT_V(8); PG8_WAIT_L(0); PG8_BAR; PG8_MMA(1, 0, At, B0); PG8_MMA(1, 1, At, B1); PG8_BAR; PG8_SCHED;
	s_add_i32 s94, s14, s24
	s_add_i32 s86, s94, 0x2000
	v_lshl_add_u64 v[136:137], v[136:137], 0, s[80:81]
	s_mov_b32 m0, s94
	s_add_u32 vcc_lo, s58, 0x10180
	ds_read_b128 v[172:175], v139 offset:49152
	ds_read_b128 v[194:197], v139 offset:50176
	ds_read_b128 v[198:201], v139 offset:51200
	ds_read_b128 v[202:205], v139 offset:52224
	ds_read_b128 v[206:209], v139 offset:53248
	ds_read_b128 v[210:213], v139 offset:54272
	ds_read_b128 v[214:217], v139 offset:55296
	ds_read_b128 v[218:221], v139 offset:56320
	global_load_lds_dwordx4 v[136:137], off
	v_lshl_add_u64 v[136:137], v[176:177], 0, s[80:81]
	s_mov_b32 m0, s86
	s_addc_u32 vcc_hi, s59, 0
	s_add_i32 s58, s21, s24
	global_load_lds_dwordx4 v[136:137], off
	v_lshl_add_u64 v[136:137], vcc, 0, v[0:1]
	s_mov_b32 m0, s58
	s_add_i32 s59, s58, 0x2000
	global_load_lds_dwordx4 v[136:137], off
	v_lshl_add_u64 v[136:137], vcc, 0, v[134:135]
	s_mov_b32 m0, s59
	s_nop 0
	global_load_lds_dwordx4 v[136:137], off
	v_lshl_add_u64 v[136:137], v[178:179], 0, s[80:81]
	s_mov_b32 m0, s77
	s_nop 0
	global_load_lds_dwordx4 v[136:137], off
	v_lshl_add_u64 v[136:137], v[180:181], 0, s[80:81]
	s_mov_b32 m0, s78
	s_nop 0
	global_load_lds_dwordx4 v[136:137], off
	s_waitcnt vmcnt(8)
	s_waitcnt lgkmcnt(0)
	s_barrier
	s_setprio 1
	v_mfma_f32_16x16x32_bf16 v[2:5], v[26:29], v[214:217], v[2:5]
	v_mfma_f32_16x16x32_bf16 v[6:9], v[114:117], v[214:217], v[6:9]
	v_mfma_f32_16x16x32_bf16 v[140:143], v[26:29], v[172:175], v[140:143]
	v_mfma_f32_16x16x32_bf16 v[144:147], v[114:117], v[172:175], v[144:147]
	v_mfma_f32_16x16x32_bf16 v[148:151], v[26:29], v[198:201], v[148:151]
	v_mfma_f32_16x16x32_bf16 v[152:155], v[114:117], v[198:201], v[152:155]
	v_mfma_f32_16x16x32_bf16 v[156:159], v[26:29], v[206:209], v[156:159]
	v_mfma_f32_16x16x32_bf16 v[160:163], v[114:117], v[206:209], v[160:163]
	v_mfma_f32_16x16x32_bf16 v[2:5], v[30:33], v[218:221], v[2:5]
	v_mfma_f32_16x16x32_bf16 v[6:9], v[118:121], v[218:221], v[6:9]
	v_mfma_f32_16x16x32_bf16 v[140:143], v[30:33], v[194:197], v[140:143]
	v_mfma_f32_16x16x32_bf16 v[144:147], v[118:121], v[194:197], v[144:147]
	v_mfma_f32_16x16x32_bf16 v[148:151], v[30:33], v[202:205], v[148:151]
	v_mfma_f32_16x16x32_bf16 v[152:155], v[118:121], v[202:205], v[152:155]
	v_mfma_f32_16x16x32_bf16 v[156:159], v[30:33], v[210:213], v[156:159]
	v_mfma_f32_16x16x32_bf16 v[160:163], v[118:121], v[210:213], v[160:163]
	v_mfma_f32_16x16x32_bf16 v[10:13], v[122:125], v[172:175], v[10:13]
	v_mfma_f32_16x16x32_bf16 v[14:17], v[164:167], v[172:175], v[14:17]
	v_mfma_f32_16x16x32_bf16 v[26:29], v[122:125], v[198:201], v[62:65]
	v_mfma_f32_16x16x32_bf16 v[30:33], v[164:167], v[198:201], v[102:105]
	v_mfma_f32_16x16x32_bf16 v[62:65], v[122:125], v[206:209], v[106:109]
	v_mfma_f32_16x16x32_bf16 v[102:105], v[164:167], v[206:209], v[110:113]
	v_mfma_f32_16x16x32_bf16 v[18:21], v[122:125], v[214:217], v[18:21]
	v_mfma_f32_16x16x32_bf16 v[22:25], v[164:167], v[214:217], v[22:25]
	v_mfma_f32_16x16x32_bf16 v[10:13], v[126:129], v[194:197], v[10:13]
	v_mfma_f32_16x16x32_bf16 v[14:17], v[168:171], v[194:197], v[14:17]
	v_mfma_f32_16x16x32_bf16 v[26:29], v[126:129], v[202:205], v[26:29]
	v_mfma_f32_16x16x32_bf16 v[30:33], v[168:171], v[202:205], v[30:33]
	v_mfma_f32_16x16x32_bf16 v[62:65], v[126:129], v[210:213], v[62:65]
	v_mfma_f32_16x16x32_bf16 v[102:105], v[168:171], v[210:213], v[102:105]
	v_mfma_f32_16x16x32_bf16 v[18:21], v[126:129], v[218:221], v[18:21]
	v_mfma_f32_16x16x32_bf16 v[22:25], v[168:171], v[218:221], v[22:25]
	s_setprio 0
	s_barrier
	ds_read_b128 v[106:109], v184
	ds_read_b128 v[110:113], v184 offset:1024
	ds_read_b128 v[114:117], v184 offset:2048
	ds_read_b128 v[118:121], v184 offset:3072
	ds_read_b128 v[122:125], v185
	ds_read_b128 v[126:129], v185 offset:1024
	ds_read_b128 v[164:167], v185 offset:2048
	ds_read_b128 v[168:171], v185 offset:3072
	s_add_u32 s56, s56, 0x10180
	s_addc_u32 s57, s57, 0
	s_mov_b32 m0, s87
	v_lshl_add_u64 v[136:137], s[56:57], 0, v[130:131]
	ds_read_b128 v[172:175], v139
	ds_read_b128 v[194:197], v139 offset:1024
	ds_read_b128 v[198:201], v139 offset:2048
	ds_read_b128 v[202:205], v139 offset:3072
	ds_read_b128 v[206:209], v139 offset:4096
	ds_read_b128 v[210:213], v139 offset:5120
	ds_read_b128 v[214:217], v139 offset:6144
	ds_read_b128 v[218:221], v139 offset:7168
	global_load_lds_dwordx4 v[136:137], off
	v_lshl_add_u64 v[136:137], s[56:57], 0, v[132:133]
	s_mov_b32 m0, s12
	s_nop 0
	global_load_lds_dwordx4 v[136:137], off
	s_waitcnt vmcnt(8)
	s_waitcnt lgkmcnt(0)
	s_barrier
; #define PG8_STAGE(bufoff, gbase, voff) do { _Pragma("unroll") for (int _i = 0; _i < 2; ++_i) \
;         __builtin_amdgcn_global_load_lds((const unsigned*)((const char*)(gbase) + (voff)[_i]), (LAS unsigned*)(lds + (bufoff) + ldsw + _i * 8192), 16, 0, 0); } while (0)
; #define PG8_LDA(dst, b, h) do { _Pragma("unroll") for (int m = 0; m < 4; ++m) _Pragma("unroll") for (int k = 0; k < 2; ++k) dst[m][k] = *(const LAS bf16x8*)(lds + PG8_SA(b, h) + aoff + m * 2048 + k * 1024); } while (0)
; #define PG8_MMA(ai, bj, At, Bt) do { __builtin_amdgcn_s_setprio(1); _Pragma("unroll") for (int m = 0; m < 4; ++m) _Pragma("unroll") for (int n = 0; n < 2; ++n) _Pragma("unroll") for (int k = 0; k < 2; ++k) \
;         acc[ai][bj][m][n] = __builtin_amdgcn_mfma_f32_16x16x32_bf16(Bt[n][k], At[m][k], acc[ai][bj][m][n], 0, 0, 0); __builtin_amdgcn_s_setprio(0); } while (0)
; #define PG8_WAIT_V(n) asm volatile("s_waitcnt vmcnt(" #n ")" ::: "memory")
; #define PG8_WAIT_L(n) asm volatile("s_waitcnt lgkmcnt(" #n ")" ::: "memory")
; #define PG8_BAR __builtin_amdgcn_s_barrier()
; #define PG8_SCHED __builtin_amdgcn_sched_barrier(0)
; template <class Epi, class Pre, bool AG = false>
; __device__ __forceinline__ void gemm_phase(LAS unsigned char* lds, const Gemm g, const StaticOrder& S, const Epi& E, const Pre& P) {
;     ...
;             PG8_WAIT_V(8); PG8_WAIT_L(0); PG8_BAR; PG8_MMA(0, 0, At, B0); PG8_MMA(0, 1, At, B1); PG8_BAR; PG8_SCHED;
;             PG8_LDA(At, 0, 1); PG8_STAGE(PG8_SB(0, 0), b2, voffB); PG8_STAGE(PG8_SB(0, 1), b2 + hstep, voffB); PG8_STAGE(PG8_SA(0, 0), a2, voffA);
;             PG8_WAIT_V(8); PG8_WAIT_L(0); PG8_BAR; PG8_MMA(1, 0, At, B0); PG8_MMA(1, 1, At, B1); PG8_BAR; PG8_SCHED;
	s_setprio 1
	v_mfma_f32_16x16x32_bf16 v[90:93], v[106:109], v[214:217], v[90:93]
	v_mfma_f32_16x16x32_bf16 v[66:69], v[106:109], v[172:175], v[66:69]
	v_mfma_f32_16x16x32_bf16 v[70:73], v[114:117], v[172:175], v[70:73]
	v_mfma_f32_16x16x32_bf16 v[74:77], v[106:109], v[198:201], v[74:77]
	v_mfma_f32_16x16x32_bf16 v[78:81], v[114:117], v[198:201], v[78:81]
	v_mfma_f32_16x16x32_bf16 v[82:85], v[106:109], v[206:209], v[82:85]
	v_mfma_f32_16x16x32_bf16 v[86:89], v[114:117], v[206:209], v[86:89]
	v_mfma_f32_16x16x32_bf16 v[222:225], v[110:113], v[218:221], v[90:93]
	v_mfma_f32_16x16x32_bf16 v[90:93], v[114:117], v[214:217], v[94:97]
	v_mfma_f32_16x16x32_bf16 v[66:69], v[110:113], v[194:197], v[66:69]
	v_mfma_f32_16x16x32_bf16 v[70:73], v[118:121], v[194:197], v[70:73]
	v_mfma_f32_16x16x32_bf16 v[74:77], v[110:113], v[202:205], v[74:77]
	v_mfma_f32_16x16x32_bf16 v[78:81], v[118:121], v[202:205], v[78:81]
	v_mfma_f32_16x16x32_bf16 v[82:85], v[110:113], v[210:213], v[82:85]
	v_mfma_f32_16x16x32_bf16 v[86:89], v[118:121], v[210:213], v[86:89]
	v_mfma_f32_16x16x32_bf16 v[94:97], v[118:121], v[218:221], v[90:93]
	v_mfma_f32_16x16x32_bf16 v[50:53], v[164:167], v[206:209], v[50:53]
	v_mfma_f32_16x16x32_bf16 v[90:93], v[122:125], v[172:175], v[98:101]
	v_mfma_f32_16x16x32_bf16 v[34:37], v[164:167], v[172:175], v[34:37]
	v_mfma_f32_16x16x32_bf16 v[38:41], v[122:125], v[198:201], v[38:41]
	v_mfma_f32_16x16x32_bf16 v[42:45], v[164:167], v[198:201], v[42:45]
	v_mfma_f32_16x16x32_bf16 v[46:49], v[122:125], v[206:209], v[46:49]
	v_mfma_f32_16x16x32_bf16 v[172:175], v[168:171], v[210:213], v[50:53]
	v_mfma_f32_16x16x32_bf16 v[50:53], v[122:125], v[214:217], v[54:57]
	v_mfma_f32_16x16x32_bf16 v[34:37], v[168:171], v[194:197], v[34:37]
	v_mfma_f32_16x16x32_bf16 v[38:41], v[126:129], v[202:205], v[38:41]
	v_mfma_f32_16x16x32_bf16 v[42:45], v[168:171], v[202:205], v[42:45]
	v_mfma_f32_16x16x32_bf16 v[46:49], v[126:129], v[210:213], v[46:49]
	v_mfma_f32_16x16x32_bf16 v[54:57], v[126:129], v[218:221], v[50:53]
	v_mfma_f32_16x16x32_bf16 v[50:53], v[164:167], v[214:217], v[58:61]
	v_mfma_f32_16x16x32_bf16 v[226:229], v[126:129], v[194:197], v[90:93]
	v_mfma_f32_16x16x32_bf16 v[194:197], v[168:171], v[218:221], v[50:53]
	s_setprio 0
	s_barrier
	s_mov_b32 m0, s85
	v_lshl_add_u64 v[136:137], s[60:61], 0, v[0:1]
	s_add_u32 s12, s60, 0x10000
	s_nop 0
	ds_read_b128 v[50:53], v139 offset:16384
	ds_read_b128 v[58:61], v139 offset:17408
	ds_read_b128 v[90:93], v139 offset:18432
	ds_read_b128 v[98:101], v139 offset:19456
	ds_read_b128 v[198:201], v139 offset:20480
	ds_read_b128 v[202:205], v139 offset:21504
	ds_read_b128 v[206:209], v139 offset:22528
	ds_read_b128 v[210:213], v139 offset:23552
	global_load_lds_dwordx4 v[136:137], off
	v_lshl_add_u64 v[192:193], s[60:61], 0, v[134:135]
	s_mov_b32 m0, s13
	s_addc_u32 s13, s61, 0
	global_load_lds_dwordx4 v[192:193], off
	v_lshl_add_u64 v[176:177], s[12:13], 0, v[0:1]
	s_mov_b32 m0, s29
	v_lshl_add_u64 v[186:187], s[70:71], 0, v[130:131]
	global_load_lds_dwordx4 v[176:177], off
	v_lshl_add_u64 v[176:177], s[12:13], 0, v[134:135]
	s_mov_b32 m0, s43
	v_lshl_add_u64 v[184:185], s[70:71], 0, v[132:133]
	global_load_lds_dwordx4 v[176:177], off
	s_mov_b32 m0, s48
	s_nop 0
	global_load_lds_dwordx4 v[186:187], off
	s_mov_b32 m0, s49
	s_nop 0
	global_load_lds_dwordx4 v[184:185], off
	s_waitcnt vmcnt(8)
	s_waitcnt lgkmcnt(0)
	s_barrier
	s_setprio 1
	v_mfma_f32_16x16x32_bf16 v[2:5], v[106:109], v[206:209], v[2:5]
	v_mfma_f32_16x16x32_bf16 v[6:9], v[114:117], v[206:209], v[6:9]
	v_mfma_f32_16x16x32_bf16 v[140:143], v[106:109], v[50:53], v[140:143]
	v_mfma_f32_16x16x32_bf16 v[144:147], v[114:117], v[50:53], v[144:147]
	v_mfma_f32_16x16x32_bf16 v[148:151], v[106:109], v[90:93], v[148:151]
	v_mfma_f32_16x16x32_bf16 v[152:155], v[114:117], v[90:93], v[152:155]
	v_mfma_f32_16x16x32_bf16 v[156:159], v[106:109], v[198:201], v[156:159]
	v_mfma_f32_16x16x32_bf16 v[160:163], v[114:117], v[198:201], v[160:163]
	v_mfma_f32_16x16x32_bf16 v[2:5], v[110:113], v[210:213], v[2:5]
	v_mfma_f32_16x16x32_bf16 v[6:9], v[118:121], v[210:213], v[6:9]
	v_mfma_f32_16x16x32_bf16 v[140:143], v[110:113], v[58:61], v[140:143]
	v_mfma_f32_16x16x32_bf16 v[144:147], v[118:121], v[58:61], v[144:147]
	v_mfma_f32_16x16x32_bf16 v[148:151], v[110:113], v[98:101], v[148:151]
	v_mfma_f32_16x16x32_bf16 v[152:155], v[118:121], v[98:101], v[152:155]
	v_mfma_f32_16x16x32_bf16 v[156:159], v[110:113], v[202:205], v[156:159]
	v_mfma_f32_16x16x32_bf16 v[160:163], v[118:121], v[202:205], v[160:163]
	v_mfma_f32_16x16x32_bf16 v[10:13], v[122:125], v[50:53], v[10:13]
	v_mfma_f32_16x16x32_bf16 v[214:217], v[126:129], v[58:61], v[10:13]
	v_mfma_f32_16x16x32_bf16 v[10:13], v[164:167], v[50:53], v[14:17]
	v_mfma_f32_16x16x32_bf16 v[14:17], v[168:171], v[58:61], v[10:13]
	v_mfma_f32_16x16x32_bf16 v[10:13], v[122:125], v[90:93], v[26:29]
	v_mfma_f32_16x16x32_bf16 v[218:221], v[126:129], v[98:101], v[10:13]
	v_mfma_f32_16x16x32_bf16 v[10:13], v[164:167], v[90:93], v[30:33]
	v_mfma_f32_16x16x32_bf16 v[30:33], v[168:171], v[98:101], v[10:13]
	v_mfma_f32_16x16x32_bf16 v[10:13], v[122:125], v[198:201], v[62:65]
	v_mfma_f32_16x16x32_bf16 v[238:241], v[126:129], v[202:205], v[10:13]
	v_mfma_f32_16x16x32_bf16 v[10:13], v[164:167], v[198:201], v[102:105]
	v_mfma_f32_16x16x32_bf16 v[198:201], v[168:171], v[202:205], v[10:13]
	v_mfma_f32_16x16x32_bf16 v[10:13], v[122:125], v[206:209], v[18:21]
	v_mfma_f32_16x16x32_bf16 v[202:205], v[126:129], v[210:213], v[10:13]
	v_mfma_f32_16x16x32_bf16 v[10:13], v[164:167], v[206:209], v[22:25]
	v_mfma_f32_16x16x32_bf16 v[164:167], v[168:171], v[210:213], v[10:13]
	s_setprio 0
	s_barrier
; #define PG8_STAGE(bufoff, gbase, voff) do { _Pragma("unroll") for (int _i = 0; _i < 2; ++_i) \
;         __builtin_amdgcn_global_load_lds((const unsigned*)((const char*)(gbase) + (voff)[_i]), (LAS unsigned*)(lds + (bufoff) + ldsw + _i * 8192), 16, 0, 0); } while (0)
; #define PG8_LDA(dst, b, h) do { _Pragma("unroll") for (int m = 0; m < 4; ++m) _Pragma("unroll") for (int k = 0; k < 2; ++k) dst[m][k] = *(const LAS bf16x8*)(lds + PG8_SA(b, h) + aoff + m * 2048 + k * 1024); } while (0)
; #define PG8_LDB(dst, b, h) do { _Pragma("unroll") for (int n = 0; n < 2; ++n) _Pragma("unroll") for (int k = 0; k < 2; ++k) dst[n][k] = *(const LAS bf16x8*)(lds + PG8_SB(b, h) + boff + n * 2048 + k * 1024); } while (0)
; #define PG8_MMA(ai, bj, At, Bt) do { __builtin_amdgcn_s_setprio(1); _Pragma("unroll") for (int m = 0; m < 4; ++m) _Pragma("unroll") for (int n = 0; n < 2; ++n) _Pragma("unroll") for (int k = 0; k < 2; ++k) \
;         acc[ai][bj][m][n] = __builtin_amdgcn_mfma_f32_16x16x32_bf16(Bt[n][k], At[m][k], acc[ai][bj][m][n], 0, 0, 0); __builtin_amdgcn_s_setprio(0); } while (0)
; #define PG8_WAIT_V(n) asm volatile("s_waitcnt vmcnt(" #n ")" ::: "memory")
; #define PG8_WAIT_L(n) asm volatile("s_waitcnt lgkmcnt(" #n ")" ::: "memory")
; #define PG8_BAR __builtin_amdgcn_s_barrier()
; #define PG8_SCHED __builtin_amdgcn_sched_barrier(0)
; template <class Epi, class Pre, bool AG = false>
; __device__ __forceinline__ void gemm_phase(LAS unsigned char* lds, const Gemm g, const StaticOrder& S, const Epi& E, const Pre& P) {
;     ...
;             PG8_LDB(B0, 1, 0); PG8_LDB(B1, 1, 1); PG8_SCHED; PG8_LDA(At, 1, 0); PG8_STAGE(PG8_SA(0, 1), a2 + hstepA, voffA);
;             PG8_WAIT_V(8); PG8_WAIT_L(0); PG8_BAR; PG8_MMA(0, 0, At, B0); PG8_MMA(0, 1, At, B1); PG8_BAR; PG8_SCHED;
;             PG8_LDA(At, 1, 1); PG8_STAGE(PG8_SB(1, 0), b3, voffB); PG8_STAGE(PG8_SB(1, 1), b3 + hstep, voffB); PG8_STAGE(PG8_SA(1, 0), a3, voffA);
;             PG8_WAIT_V(8); PG8_WAIT_L(0); PG8_BAR; PG8_MMA(1, 0, At, B0); PG8_MMA(1, 1, At, B1); PG8_BAR; PG8_SCHED;
;         }
;         if (wr == 0) PG8_BAR;
	s_nop 4
	ds_read_b128 v[10:13], v188
	ds_read_b128 v[22:25], v188 offset:1024
	ds_read_b128 v[168:171], v188 offset:2048
	ds_read_b128 v[206:209], v188 offset:3072
	ds_read_b128 v[210:213], v189
	ds_read_b128 v[242:245], v189 offset:1024
	ds_read_b128 v[246:249], v189 offset:2048
	ds_read_b128 v[250:253], v189 offset:3072
	s_add_u32 s12, s70, 0x10000
	s_addc_u32 s13, s71, 0
	s_mov_b32 m0, s53
	v_lshl_add_u64 v[50:51], s[12:13], 0, v[130:131]
	ds_read_b128 v[18:21], v139 offset:32768
	ds_read_b128 v[26:29], v139 offset:33792
	ds_read_b128 v[62:65], v139 offset:34816
	ds_read_b128 v[102:105], v139 offset:35840
	ds_read_b128 v[232:235], v139 offset:36864
	ds_read_b128 v[188:191], v139 offset:37888
	ds_read_b128 v[176:179], v139 offset:38912
	ds_read_b128 v[180:183], v139 offset:39936
	global_load_lds_dwordx4 v[50:51], off
	v_lshl_add_u64 v[50:51], s[12:13], 0, v[132:133]
	s_mov_b32 m0, s55
	s_nop 0
	global_load_lds_dwordx4 v[50:51], off
	s_waitcnt vmcnt(8)
	s_waitcnt lgkmcnt(0)
	s_barrier
	s_setprio 1
	v_mfma_f32_16x16x32_bf16 v[50:53], v[10:13], v[18:21], v[66:69]
	v_mfma_f32_16x16x32_bf16 v[122:125], v[22:25], v[26:29], v[50:53]
	v_mfma_f32_16x16x32_bf16 v[50:53], v[168:171], v[18:21], v[70:73]
	v_mfma_f32_16x16x32_bf16 v[114:117], v[206:209], v[26:29], v[50:53]
	v_mfma_f32_16x16x32_bf16 v[50:53], v[10:13], v[62:65], v[74:77]
	v_mfma_f32_16x16x32_bf16 v[106:109], v[22:25], v[102:105], v[50:53]
	v_mfma_f32_16x16x32_bf16 v[50:53], v[168:171], v[62:65], v[78:81]
	v_mfma_f32_16x16x32_bf16 v[98:101], v[206:209], v[102:105], v[50:53]
	v_mfma_f32_16x16x32_bf16 v[50:53], v[10:13], v[232:235], v[82:85]
	v_mfma_f32_16x16x32_bf16 v[90:93], v[22:25], v[188:191], v[50:53]
	v_mfma_f32_16x16x32_bf16 v[50:53], v[168:171], v[232:235], v[86:89]
	v_mfma_f32_16x16x32_bf16 v[82:85], v[206:209], v[188:191], v[50:53]
	v_mfma_f32_16x16x32_bf16 v[50:53], v[10:13], v[176:179], v[222:225]
	v_mfma_f32_16x16x32_bf16 v[58:61], v[22:25], v[180:183], v[50:53]
	v_mfma_f32_16x16x32_bf16 v[50:53], v[168:171], v[176:179], v[94:97]
	v_mfma_f32_16x16x32_bf16 v[50:53], v[206:209], v[180:183], v[50:53]
	v_mfma_f32_16x16x32_bf16 v[66:69], v[210:213], v[18:21], v[226:229]
	v_mfma_f32_16x16x32_bf16 v[18:21], v[246:249], v[18:21], v[34:37]
	v_mfma_f32_16x16x32_bf16 v[118:121], v[250:253], v[26:29], v[18:21]
	v_mfma_f32_16x16x32_bf16 v[18:21], v[210:213], v[62:65], v[38:41]
	v_mfma_f32_16x16x32_bf16 v[110:113], v[242:245], v[102:105], v[18:21]
	v_mfma_f32_16x16x32_bf16 v[18:21], v[246:249], v[62:65], v[42:45]
	v_mfma_f32_16x16x32_bf16 v[102:105], v[250:253], v[102:105], v[18:21]
	v_mfma_f32_16x16x32_bf16 v[18:21], v[210:213], v[232:235], v[46:49]
	v_mfma_f32_16x16x32_bf16 v[94:97], v[242:245], v[188:191], v[18:21]
	v_mfma_f32_16x16x32_bf16 v[18:21], v[246:249], v[232:235], v[172:175]
	v_mfma_f32_16x16x32_bf16 v[86:89], v[250:253], v[188:191], v[18:21]
	v_mfma_f32_16x16x32_bf16 v[18:21], v[210:213], v[176:179], v[54:57]
	v_mfma_f32_16x16x32_bf16 v[62:65], v[242:245], v[180:183], v[18:21]
	v_mfma_f32_16x16x32_bf16 v[18:21], v[246:249], v[176:179], v[194:197]
	v_mfma_f32_16x16x32_bf16 v[126:129], v[242:245], v[26:29], v[66:69]
	v_mfma_f32_16x16x32_bf16 v[54:57], v[250:253], v[180:183], v[18:21]
	s_setprio 0
	s_barrier
	s_mov_b32 m0, s94
	s_nop 2
	v_lshl_add_u64 v[18:19], v[136:137], 0, s[66:67]
	s_add_u32 s12, s60, 0x10080
	ds_read_b128 v[38:41], v139 offset:49152
	ds_read_b128 v[46:49], v139 offset:50176
	ds_read_b128 v[172:175], v139 offset:51200
	ds_read_b128 v[176:179], v139 offset:52224
	ds_read_b128 v[180:183], v139 offset:53248
	ds_read_b128 v[188:191], v139 offset:54272
	ds_read_b128 v[194:197], v139 offset:55296
	ds_read_b128 v[222:225], v139 offset:56320
	global_load_lds_dwordx4 v[18:19], off
	v_lshl_add_u64 v[18:19], v[192:193], 0, s[66:67]
	s_mov_b32 m0, s86
	s_addc_u32 s13, s61, 0
	global_load_lds_dwordx4 v[18:19], off
	v_lshl_add_u64 v[18:19], s[12:13], 0, v[0:1]
	s_mov_b32 m0, s58
	s_nop 0
	global_load_lds_dwordx4 v[18:19], off
	v_lshl_add_u64 v[18:19], s[12:13], 0, v[134:135]
	s_mov_b32 m0, s59
	s_nop 0
	global_load_lds_dwordx4 v[18:19], off
	v_lshl_add_u64 v[18:19], v[186:187], 0, s[66:67]
	s_mov_b32 m0, s77
	s_nop 0
	global_load_lds_dwordx4 v[18:19], off
	v_lshl_add_u64 v[18:19], v[184:185], 0, s[66:67]
	s_mov_b32 m0, s78
	s_nop 0
	global_load_lds_dwordx4 v[18:19], off
	s_waitcnt vmcnt(8)
	s_waitcnt lgkmcnt(0)
	s_barrier
	s_setprio 1
	v_mfma_f32_16x16x32_bf16 v[18:21], v[10:13], v[38:41], v[140:143]
	v_mfma_f32_16x16x32_bf16 v[74:77], v[22:25], v[46:49], v[18:21]
	v_mfma_f32_16x16x32_bf16 v[18:21], v[168:171], v[38:41], v[144:147]
	v_mfma_f32_16x16x32_bf16 v[66:69], v[206:209], v[46:49], v[18:21]
	v_mfma_f32_16x16x32_bf16 v[18:21], v[10:13], v[172:175], v[148:151]
	v_mfma_f32_16x16x32_bf16 v[42:45], v[22:25], v[176:179], v[18:21]
	v_mfma_f32_16x16x32_bf16 v[18:21], v[168:171], v[172:175], v[152:155]
	v_mfma_f32_16x16x32_bf16 v[34:37], v[206:209], v[176:179], v[18:21]
	v_mfma_f32_16x16x32_bf16 v[18:21], v[10:13], v[180:183], v[156:159]
	v_mfma_f32_16x16x32_bf16 v[2:5], v[10:13], v[194:197], v[2:5]
	v_mfma_f32_16x16x32_bf16 v[26:29], v[22:25], v[188:191], v[18:21]
	v_mfma_f32_16x16x32_bf16 v[18:21], v[168:171], v[180:183], v[160:163]
	v_mfma_f32_16x16x32_bf16 v[10:13], v[22:25], v[222:225], v[2:5]
	v_mfma_f32_16x16x32_bf16 v[2:5], v[168:171], v[194:197], v[6:9]
	v_mfma_f32_16x16x32_bf16 v[18:21], v[206:209], v[188:191], v[18:21]
	v_mfma_f32_16x16x32_bf16 v[2:5], v[206:209], v[222:225], v[2:5]
	v_mfma_f32_16x16x32_bf16 v[6:9], v[210:213], v[38:41], v[214:217]
	v_mfma_f32_16x16x32_bf16 v[78:81], v[242:245], v[46:49], v[6:9]
	v_mfma_f32_16x16x32_bf16 v[6:9], v[246:249], v[38:41], v[14:17]
	v_mfma_f32_16x16x32_bf16 v[70:73], v[250:253], v[46:49], v[6:9]
	v_mfma_f32_16x16x32_bf16 v[6:9], v[210:213], v[172:175], v[218:221]
	v_mfma_f32_16x16x32_bf16 v[46:49], v[242:245], v[176:179], v[6:9]
	v_mfma_f32_16x16x32_bf16 v[6:9], v[246:249], v[172:175], v[30:33]
	v_mfma_f32_16x16x32_bf16 v[38:41], v[250:253], v[176:179], v[6:9]
	v_mfma_f32_16x16x32_bf16 v[6:9], v[210:213], v[180:183], v[238:241]
	v_mfma_f32_16x16x32_bf16 v[30:33], v[242:245], v[188:191], v[6:9]
	v_mfma_f32_16x16x32_bf16 v[6:9], v[246:249], v[180:183], v[198:201]
	v_mfma_f32_16x16x32_bf16 v[22:25], v[250:253], v[188:191], v[6:9]
	v_mfma_f32_16x16x32_bf16 v[6:9], v[210:213], v[194:197], v[202:205]
	v_mfma_f32_16x16x32_bf16 v[14:17], v[242:245], v[222:225], v[6:9]
	v_mfma_f32_16x16x32_bf16 v[6:9], v[246:249], v[194:197], v[164:167]
	v_mfma_f32_16x16x32_bf16 v[6:9], v[250:253], v[222:225], v[6:9]
	s_setprio 0
	s_barrier
	s_andn2_b64 vcc, exec, s[16:17]
	s_cbranch_vccnz .LBB0_784
	s_barrier

; #define PG8_STAGE(bufoff, gbase, voff) do { _Pragma("unroll") for (int _i = 0; _i < 2; ++_i) \
;         __builtin_amdgcn_global_load_lds((const unsigned*)((const char*)(gbase) + (voff)[_i]), (LAS unsigned*)(lds + (bufoff) + ldsw + _i * 8192), 16, 0, 0); } while (0)
; #define PG8_LDA(dst, b, h) do { _Pragma("unroll") for (int m = 0; m < 4; ++m) _Pragma("unroll") for (int k = 0; k < 2; ++k) dst[m][k] = *(const LAS bf16x8*)(lds + PG8_SA(b, h) + aoff + m * 2048 + k * 1024); } while (0)
; #define PG8_LDB(dst, b, h) do { _Pragma("unroll") for (int n = 0; n < 2; ++n) _Pragma("unroll") for (int k = 0; k < 2; ++k) dst[n][k] = *(const LAS bf16x8*)(lds + PG8_SB(b, h) + boff + n * 2048 + k * 1024); } while (0)
; #define PG8_MMA(ai, bj, At, Bt) do { __builtin_amdgcn_s_setprio(1); _Pragma("unroll") for (int m = 0; m < 4; ++m) _Pragma("unroll") for (int n = 0; n < 2; ++n) _Pragma("unroll") for (int k = 0; k < 2; ++k) \
;         acc[ai][bj][m][n] = __builtin_amdgcn_mfma_f32_16x16x32_bf16(Bt[n][k], At[m][k], acc[ai][bj][m][n], 0, 0, 0); __builtin_amdgcn_s_setprio(0); } while (0)
; #define PG8_WAIT_V(n) asm volatile("s_waitcnt vmcnt(" #n ")" ::: "memory")
; #define PG8_WAIT_L(n) asm volatile("s_waitcnt lgkmcnt(" #n ")" ::: "memory")
; #define PG8_BAR __builtin_amdgcn_s_barrier()
; template <class Epi, class Pre, bool AG = false>
; __device__ __forceinline__ void gemm_phase(LAS unsigned char* lds, const Gemm g, const StaticOrder& S, const Epi& E, const Pre& P) {
;     ...
;             const bool last = (t == nt - 2);
;             const char* a1 = cA + (size_t)(t + 1) * kstepA;
;             const char* a2 = last ? nA : cA + (size_t)(t + 2) * kstepA; const char* b2 = last ? nB : cB + (size_t)(t + 2) * kstep;
;             const char* a3 = a2 + kstepA; const char* b3 = b2 + kstep;
;             if constexpr (Epi::MIDK) { if (t == E.midk_t) E.mid(acc, cur, ui, wr, wc, fr, fq); }
;             PG8_LDB(B0, 0, 0); PG8_LDB(B1, 0, 1); PG8_SCHED; PG8_LDA(At, 0, 0); PG8_STAGE(PG8_SA(1, 1), a1 + hstepA, voffA);
;             PG8_WAIT_V(8); PG8_WAIT_L(0); PG8_BAR; PG8_MMA(0, 0, At, B0); PG8_MMA(0, 1, At, B1); PG8_BAR; PG8_SCHED;
;             PG8_LDA(At, 0, 1); PG8_STAGE(PG8_SB(0, 0), b2, voffB); PG8_STAGE(PG8_SB(0, 1), b2 + hstep, voffB); PG8_STAGE(PG8_SA(0, 0), a2, voffA);
;             PG8_WAIT_V(8); PG8_WAIT_L(0); PG8_BAR; PG8_MMA(1, 0, At, B0); PG8_MMA(1, 1, At, B1); PG8_BAR; PG8_SCHED;
.LBB0_863:
	s_add_u32 s14, s8, s54
	s_addc_u32 s21, s9, s55
	s_add_u32 s14, s14, 0x100
	s_addc_u32 s21, s21, 0
	s_add_u32 s56, s79, s54
	s_addc_u32 s57, s84, s55
	s_cmpk_eq_i32 s54, 0x700
	s_cselect_b32 s59, s12, s21
	s_cselect_b32 s58, s13, s14
	s_cselect_b32 s57, s29, s57
	s_cselect_b32 s56, s43, s56
	s_add_i32 s14, 0, 0x10000
	v_add_u32_e32 v0, s14, v200
	s_add_i32 s21, 0, 0x14000
	ds_read_b128 v[122:125], v0
	ds_read_b128 v[126:129], v0 offset:1024
	ds_read_b128 v[140:143], v0 offset:2048
	ds_read_b128 v[152:155], v0 offset:3072
	v_add_u32_e32 v0, s21, v200
	ds_read_b128 v[168:171], v0
	ds_read_b128 v[172:175], v0 offset:1024
	ds_read_b128 v[176:179], v0 offset:2048
	ds_read_b128 v[180:183], v0 offset:3072
	v_lshl_add_u64 v[2:3], v[116:117], 0, s[54:55]
	s_add_i32 m0, s38, 0xc000
	ds_read_b128 v[188:191], v202
	ds_read_b128 v[194:197], v202 offset:1024
	ds_read_b128 v[204:207], v202 offset:2048
	ds_read_b128 v[208:211], v202 offset:3072
	ds_read_b128 v[212:215], v202 offset:4096
	ds_read_b128 v[216:219], v202 offset:5120
	ds_read_b128 v[220:223], v202 offset:6144
	ds_read_b128 v[224:227], v202 offset:7168
	global_load_lds_dwordx4 v[2:3], off
	v_lshl_add_u64 v[2:3], v[118:119], 0, s[54:55]
	s_add_i32 m0, s38, 0xe000
	s_nop 0
	global_load_lds_dwordx4 v[2:3], off
	s_waitcnt vmcnt(8)
	s_waitcnt lgkmcnt(0)
	s_barrier
	s_setprio 1
	v_mfma_f32_16x16x32_bf16 v[148:151], v[122:125], v[188:191], v[148:151]
	v_mfma_f32_16x16x32_bf16 v[144:147], v[140:143], v[188:191], v[144:147]
	v_mfma_f32_16x16x32_bf16 v[112:115], v[122:125], v[204:207], v[112:115]
	v_mfma_f32_16x16x32_bf16 v[108:111], v[140:143], v[204:207], v[108:111]
	v_mfma_f32_16x16x32_bf16 v[96:99], v[122:125], v[212:215], v[96:99]
	v_mfma_f32_16x16x32_bf16 v[92:95], v[140:143], v[212:215], v[92:95]
	v_mfma_f32_16x16x32_bf16 v[80:83], v[122:125], v[220:223], v[80:83]
	v_mfma_f32_16x16x32_bf16 v[76:79], v[140:143], v[220:223], v[76:79]
	v_mfma_f32_16x16x32_bf16 v[148:151], v[126:129], v[194:197], v[148:151]
	v_mfma_f32_16x16x32_bf16 v[144:147], v[152:155], v[194:197], v[144:147]
	v_mfma_f32_16x16x32_bf16 v[112:115], v[126:129], v[208:211], v[112:115]
	v_mfma_f32_16x16x32_bf16 v[108:111], v[152:155], v[208:211], v[108:111]
	v_mfma_f32_16x16x32_bf16 v[96:99], v[126:129], v[216:219], v[96:99]
	v_mfma_f32_16x16x32_bf16 v[92:95], v[152:155], v[216:219], v[92:95]
	v_mfma_f32_16x16x32_bf16 v[80:83], v[126:129], v[224:227], v[80:83]
	v_mfma_f32_16x16x32_bf16 v[76:79], v[152:155], v[224:227], v[76:79]
	v_mfma_f32_16x16x32_bf16 v[136:139], v[168:171], v[188:191], v[136:139]
	v_mfma_f32_16x16x32_bf16 v[130:133], v[176:179], v[188:191], v[132:135]
	v_mfma_f32_16x16x32_bf16 v[104:107], v[168:171], v[204:207], v[104:107]
	v_mfma_f32_16x16x32_bf16 v[100:103], v[176:179], v[204:207], v[100:103]
	v_mfma_f32_16x16x32_bf16 v[88:91], v[168:171], v[212:215], v[88:91]
	v_mfma_f32_16x16x32_bf16 v[84:87], v[176:179], v[212:215], v[84:87]
	v_mfma_f32_16x16x32_bf16 v[72:75], v[168:171], v[220:223], v[72:75]
	v_mfma_f32_16x16x32_bf16 v[68:71], v[176:179], v[220:223], v[68:71]
	v_mfma_f32_16x16x32_bf16 v[136:139], v[172:175], v[194:197], v[136:139]
	v_mfma_f32_16x16x32_bf16 v[130:133], v[180:183], v[194:197], v[130:133]
	v_mfma_f32_16x16x32_bf16 v[104:107], v[172:175], v[208:211], v[104:107]
	v_mfma_f32_16x16x32_bf16 v[100:103], v[180:183], v[208:211], v[100:103]
	v_mfma_f32_16x16x32_bf16 v[88:91], v[172:175], v[216:219], v[88:91]
	v_mfma_f32_16x16x32_bf16 v[84:87], v[180:183], v[216:219], v[84:87]
	v_mfma_f32_16x16x32_bf16 v[72:75], v[172:175], v[224:227], v[72:75]
	v_mfma_f32_16x16x32_bf16 v[68:71], v[180:183], v[224:227], v[68:71]
	s_setprio 0
	s_barrier
	s_add_i32 s14, s14, s31
	v_lshl_add_u64 v[184:185], s[56:57], 0, v[160:161]
	s_mov_b32 m0, s14
	ds_read_b128 v[188:191], v202 offset:16384
	ds_read_b128 v[194:197], v202 offset:17408
	ds_read_b128 v[204:207], v202 offset:18432
	ds_read_b128 v[208:211], v202 offset:19456
	ds_read_b128 v[212:215], v202 offset:20480
	ds_read_b128 v[216:219], v202 offset:21504
	ds_read_b128 v[220:223], v202 offset:22528
	ds_read_b128 v[224:227], v202 offset:23552
	global_load_lds_dwordx4 v[184:185], off
	s_add_i32 m0, s14, 0x2000
	s_add_u32 s86, s56, 0x40000
	v_lshl_add_u64 v[186:187], s[56:57], 0, v[156:157]
	s_addc_u32 s87, s57, 0
	s_add_i32 s14, s21, s31
	global_load_lds_dwordx4 v[186:187], off
	v_lshl_add_u64 v[2:3], s[86:87], 0, v[160:161]
	s_mov_b32 m0, s14
	v_lshl_add_u64 v[192:193], s[58:59], 0, v[162:163]
	global_load_lds_dwordx4 v[2:3], off
	v_lshl_add_u64 v[2:3], s[86:87], 0, v[156:157]
	s_add_i32 m0, s14, 0x2000
	v_lshl_add_u64 v[198:199], s[58:59], 0, v[158:159]
	global_load_lds_dwordx4 v[2:3], off
	s_mov_b32 m0, s38
	s_nop 0
	global_load_lds_dwordx4 v[192:193], off
	s_mov_b32 m0, s48
	s_nop 0
	global_load_lds_dwordx4 v[198:199], off
	s_waitcnt vmcnt(8)
	s_waitcnt lgkmcnt(0)
	s_barrier
; #define PG8_STAGE(bufoff, gbase, voff) do { _Pragma("unroll") for (int _i = 0; _i < 2; ++_i) \
;         __builtin_amdgcn_global_load_lds((const unsigned*)((const char*)(gbase) + (voff)[_i]), (LAS unsigned*)(lds + (bufoff) + ldsw + _i * 8192), 16, 0, 0); } while (0)
; #define PG8_LDA(dst, b, h) do { _Pragma("unroll") for (int m = 0; m < 4; ++m) _Pragma("unroll") for (int k = 0; k < 2; ++k) dst[m][k] = *(const LAS bf16x8*)(lds + PG8_SA(b, h) + aoff + m * 2048 + k * 1024); } while (0)
; #define PG8_LDB(dst, b, h) do { _Pragma("unroll") for (int n = 0; n < 2; ++n) _Pragma("unroll") for (int k = 0; k < 2; ++k) dst[n][k] = *(const LAS bf16x8*)(lds + PG8_SB(b, h) + boff + n * 2048 + k * 1024); } while (0)
; #define PG8_MMA(ai, bj, At, Bt) do { __builtin_amdgcn_s_setprio(1); _Pragma("unroll") for (int m = 0; m < 4; ++m) _Pragma("unroll") for (int n = 0; n < 2; ++n) _Pragma("unroll") for (int k = 0; k < 2; ++k) \
;         acc[ai][bj][m][n] = __builtin_amdgcn_mfma_f32_16x16x32_bf16(Bt[n][k], At[m][k], acc[ai][bj][m][n], 0, 0, 0); __builtin_amdgcn_s_setprio(0); } while (0)
; #define PG8_WAIT_V(n) asm volatile("s_waitcnt vmcnt(" #n ")" ::: "memory")
; #define PG8_WAIT_L(n) asm volatile("s_waitcnt lgkmcnt(" #n ")" ::: "memory")
; #define PG8_BAR __builtin_amdgcn_s_barrier()
; #define PG8_SCHED __builtin_amdgcn_sched_barrier(0)
; template <class Epi, class Pre, bool AG = false>
; __device__ __forceinline__ void gemm_phase(LAS unsigned char* lds, const Gemm g, const StaticOrder& S, const Epi& E, const Pre& P) {
;     ...
;             PG8_WAIT_V(8); PG8_WAIT_L(0); PG8_BAR; PG8_MMA(1, 0, At, B0); PG8_MMA(1, 1, At, B1); PG8_BAR; PG8_SCHED;
;             PG8_LDB(B0, 1, 0); PG8_LDB(B1, 1, 1); PG8_SCHED; PG8_LDA(At, 1, 0); PG8_STAGE(PG8_SA(0, 1), a2 + hstepA, voffA);
;             PG8_WAIT_V(8); PG8_WAIT_L(0); PG8_BAR; PG8_MMA(0, 0, At, B0); PG8_MMA(0, 1, At, B1); PG8_BAR; PG8_SCHED;
	s_setprio 1
	v_mfma_f32_16x16x32_bf16 v[64:67], v[122:125], v[188:191], v[64:67]
	v_mfma_f32_16x16x32_bf16 v[60:63], v[140:143], v[188:191], v[60:63]
	v_mfma_f32_16x16x32_bf16 v[48:51], v[122:125], v[204:207], v[48:51]
	v_mfma_f32_16x16x32_bf16 v[44:47], v[140:143], v[204:207], v[44:47]
	v_mfma_f32_16x16x32_bf16 v[32:35], v[122:125], v[212:215], v[32:35]
	v_mfma_f32_16x16x32_bf16 v[28:31], v[140:143], v[212:215], v[28:31]
	v_mfma_f32_16x16x32_bf16 v[16:19], v[122:125], v[220:223], v[16:19]
	v_mfma_f32_16x16x32_bf16 v[12:15], v[140:143], v[220:223], v[12:15]
	v_mfma_f32_16x16x32_bf16 v[64:67], v[126:129], v[194:197], v[64:67]
	v_mfma_f32_16x16x32_bf16 v[60:63], v[152:155], v[194:197], v[60:63]
	v_mfma_f32_16x16x32_bf16 v[48:51], v[126:129], v[208:211], v[48:51]
	v_mfma_f32_16x16x32_bf16 v[44:47], v[152:155], v[208:211], v[44:47]
	v_mfma_f32_16x16x32_bf16 v[32:35], v[126:129], v[216:219], v[32:35]
	v_mfma_f32_16x16x32_bf16 v[28:31], v[152:155], v[216:219], v[28:31]
	v_mfma_f32_16x16x32_bf16 v[16:19], v[126:129], v[224:227], v[16:19]
	v_mfma_f32_16x16x32_bf16 v[12:15], v[152:155], v[224:227], v[12:15]
	v_mfma_f32_16x16x32_bf16 v[56:59], v[168:171], v[188:191], v[56:59]
	v_mfma_f32_16x16x32_bf16 v[52:55], v[176:179], v[188:191], v[52:55]
	v_mfma_f32_16x16x32_bf16 v[40:43], v[168:171], v[204:207], v[40:43]
	v_mfma_f32_16x16x32_bf16 v[36:39], v[176:179], v[204:207], v[36:39]
	v_mfma_f32_16x16x32_bf16 v[24:27], v[168:171], v[212:215], v[24:27]
	v_mfma_f32_16x16x32_bf16 v[20:23], v[176:179], v[212:215], v[20:23]
	v_mfma_f32_16x16x32_bf16 v[8:11], v[168:171], v[220:223], v[8:11]
	v_mfma_f32_16x16x32_bf16 v[2:5], v[176:179], v[220:223], v[4:7]
	v_mfma_f32_16x16x32_bf16 v[56:59], v[172:175], v[194:197], v[56:59]
	v_mfma_f32_16x16x32_bf16 v[52:55], v[180:183], v[194:197], v[52:55]
	v_mfma_f32_16x16x32_bf16 v[40:43], v[172:175], v[208:211], v[40:43]
	v_mfma_f32_16x16x32_bf16 v[36:39], v[180:183], v[208:211], v[36:39]
	v_mfma_f32_16x16x32_bf16 v[24:27], v[172:175], v[216:219], v[24:27]
	v_mfma_f32_16x16x32_bf16 v[20:23], v[180:183], v[216:219], v[20:23]
	v_mfma_f32_16x16x32_bf16 v[8:11], v[172:175], v[224:227], v[8:11]
	v_mfma_f32_16x16x32_bf16 v[2:5], v[180:183], v[224:227], v[2:5]
	s_setprio 0
	s_barrier
	s_add_i32 s14, 0, 0x18000
	v_add_u32_e32 v0, s14, v200
	s_add_i32 s21, 0, 0x1c000
	ds_read_b128 v[122:125], v0
	ds_read_b128 v[126:129], v0 offset:1024
	ds_read_b128 v[140:143], v0 offset:2048
	ds_read_b128 v[152:155], v0 offset:3072
	v_add_u32_e32 v0, s21, v200
	ds_read_b128 v[168:171], v0
	ds_read_b128 v[172:175], v0 offset:1024
	ds_read_b128 v[176:179], v0 offset:2048
	ds_read_b128 v[180:183], v0 offset:3072
	s_add_u32 s58, s58, 0x40000
	s_addc_u32 s59, s59, 0
	s_mov_b32 m0, s49
	v_lshl_add_u64 v[6:7], s[58:59], 0, v[162:163]
	ds_read_b128 v[188:191], v202 offset:32768
	ds_read_b128 v[194:197], v202 offset:33792
	ds_read_b128 v[204:207], v202 offset:34816
	ds_read_b128 v[208:211], v202 offset:35840
	ds_read_b128 v[212:215], v202 offset:36864
	ds_read_b128 v[216:219], v202 offset:37888
	ds_read_b128 v[220:223], v202 offset:38912
	ds_read_b128 v[224:227], v202 offset:39936
	global_load_lds_dwordx4 v[6:7], off
	v_lshl_add_u64 v[6:7], s[58:59], 0, v[158:159]
	s_mov_b32 m0, s53
	s_nop 0
	global_load_lds_dwordx4 v[6:7], off
	s_waitcnt vmcnt(8)
	s_waitcnt lgkmcnt(0)
	s_barrier
	s_setprio 1
	v_mfma_f32_16x16x32_bf16 v[148:151], v[122:125], v[188:191], v[148:151]
	v_mfma_f32_16x16x32_bf16 v[144:147], v[140:143], v[188:191], v[144:147]
	v_mfma_f32_16x16x32_bf16 v[112:115], v[122:125], v[204:207], v[112:115]
	v_mfma_f32_16x16x32_bf16 v[108:111], v[140:143], v[204:207], v[108:111]
	v_mfma_f32_16x16x32_bf16 v[96:99], v[122:125], v[212:215], v[96:99]
	v_mfma_f32_16x16x32_bf16 v[92:95], v[140:143], v[212:215], v[92:95]
	v_mfma_f32_16x16x32_bf16 v[80:83], v[122:125], v[220:223], v[80:83]
	v_mfma_f32_16x16x32_bf16 v[76:79], v[140:143], v[220:223], v[76:79]
	v_mfma_f32_16x16x32_bf16 v[148:151], v[126:129], v[194:197], v[148:151]
	v_mfma_f32_16x16x32_bf16 v[144:147], v[152:155], v[194:197], v[144:147]
	v_mfma_f32_16x16x32_bf16 v[112:115], v[126:129], v[208:211], v[112:115]
	v_mfma_f32_16x16x32_bf16 v[108:111], v[152:155], v[208:211], v[108:111]
	v_mfma_f32_16x16x32_bf16 v[96:99], v[126:129], v[216:219], v[96:99]
	v_mfma_f32_16x16x32_bf16 v[92:95], v[152:155], v[216:219], v[92:95]
	v_mfma_f32_16x16x32_bf16 v[80:83], v[126:129], v[224:227], v[80:83]
	v_mfma_f32_16x16x32_bf16 v[76:79], v[152:155], v[224:227], v[76:79]
	v_mfma_f32_16x16x32_bf16 v[134:137], v[168:171], v[188:191], v[136:139]
	v_mfma_f32_16x16x32_bf16 v[130:133], v[176:179], v[188:191], v[130:133]
	v_mfma_f32_16x16x32_bf16 v[104:107], v[168:171], v[204:207], v[104:107]
	v_mfma_f32_16x16x32_bf16 v[100:103], v[176:179], v[204:207], v[100:103]
	v_mfma_f32_16x16x32_bf16 v[88:91], v[168:171], v[212:215], v[88:91]
	v_mfma_f32_16x16x32_bf16 v[84:87], v[176:179], v[212:215], v[84:87]
	v_mfma_f32_16x16x32_bf16 v[72:75], v[168:171], v[220:223], v[72:75]
	v_mfma_f32_16x16x32_bf16 v[68:71], v[176:179], v[220:223], v[68:71]
	v_mfma_f32_16x16x32_bf16 v[136:139], v[172:175], v[194:197], v[134:137]
	v_mfma_f32_16x16x32_bf16 v[132:135], v[180:183], v[194:197], v[130:133]
	v_mfma_f32_16x16x32_bf16 v[104:107], v[172:175], v[208:211], v[104:107]
	v_mfma_f32_16x16x32_bf16 v[100:103], v[180:183], v[208:211], v[100:103]
	v_mfma_f32_16x16x32_bf16 v[88:91], v[172:175], v[216:219], v[88:91]
	v_mfma_f32_16x16x32_bf16 v[84:87], v[180:183], v[216:219], v[84:87]
	v_mfma_f32_16x16x32_bf16 v[72:75], v[172:175], v[224:227], v[72:75]
	v_mfma_f32_16x16x32_bf16 v[68:71], v[180:183], v[224:227], v[68:71]
	s_setprio 0
	s_barrier
; #define PG8_STAGE(bufoff, gbase, voff) do { _Pragma("unroll") for (int _i = 0; _i < 2; ++_i) \
;         __builtin_amdgcn_global_load_lds((const unsigned*)((const char*)(gbase) + (voff)[_i]), (LAS unsigned*)(lds + (bufoff) + ldsw + _i * 8192), 16, 0, 0); } while (0)
; #define PG8_LDA(dst, b, h) do { _Pragma("unroll") for (int m = 0; m < 4; ++m) _Pragma("unroll") for (int k = 0; k < 2; ++k) dst[m][k] = *(const LAS bf16x8*)(lds + PG8_SA(b, h) + aoff + m * 2048 + k * 1024); } while (0)
; #define PG8_MMA(ai, bj, At, Bt) do { __builtin_amdgcn_s_setprio(1); _Pragma("unroll") for (int m = 0; m < 4; ++m) _Pragma("unroll") for (int n = 0; n < 2; ++n) _Pragma("unroll") for (int k = 0; k < 2; ++k) \
;         acc[ai][bj][m][n] = __builtin_amdgcn_mfma_f32_16x16x32_bf16(Bt[n][k], At[m][k], acc[ai][bj][m][n], 0, 0, 0); __builtin_amdgcn_s_setprio(0); } while (0)
; #define PG8_WAIT_V(n) asm volatile("s_waitcnt vmcnt(" #n ")" ::: "memory")
; #define PG8_WAIT_L(n) asm volatile("s_waitcnt lgkmcnt(" #n ")" ::: "memory")
; #define PG8_BAR __builtin_amdgcn_s_barrier()
; #define PG8_SCHED __builtin_amdgcn_sched_barrier(0)
; template <class Epi, class Pre, bool AG = false>
; __device__ __forceinline__ void gemm_phase(LAS unsigned char* lds, const Gemm g, const StaticOrder& S, const Epi& E, const Pre& P) {
;     ...
;             PG8_LDA(At, 1, 1); PG8_STAGE(PG8_SB(1, 0), b3, voffB); PG8_STAGE(PG8_SB(1, 1), b3 + hstep, voffB); PG8_STAGE(PG8_SA(1, 0), a3, voffA);
;             PG8_WAIT_V(8); PG8_WAIT_L(0); PG8_BAR; PG8_MMA(1, 0, At, B0); PG8_MMA(1, 1, At, B1); PG8_BAR; PG8_SCHED;
;         }
	s_add_i32 s14, s14, s31
	v_lshl_add_u64 v[6:7], v[184:185], 0, s[66:67]
	s_mov_b32 m0, s14
	ds_read_b128 v[188:191], v202 offset:49152
	ds_read_b128 v[194:197], v202 offset:50176
	ds_read_b128 v[204:207], v202 offset:51200
	ds_read_b128 v[208:211], v202 offset:52224
	ds_read_b128 v[212:215], v202 offset:53248
	ds_read_b128 v[216:219], v202 offset:54272
	ds_read_b128 v[220:223], v202 offset:55296
	ds_read_b128 v[224:227], v202 offset:56320
	global_load_lds_dwordx4 v[6:7], off
	s_add_i32 m0, s14, 0x2000
	s_add_u32 s56, s56, 0x40080
	v_lshl_add_u64 v[6:7], v[186:187], 0, s[66:67]
	s_addc_u32 s57, s57, 0
	s_add_i32 s14, s21, s31
	global_load_lds_dwordx4 v[6:7], off
	v_lshl_add_u64 v[6:7], s[56:57], 0, v[160:161]
	s_mov_b32 m0, s14
	s_nop 0
	global_load_lds_dwordx4 v[6:7], off
	v_lshl_add_u64 v[6:7], s[56:57], 0, v[156:157]
	s_add_i32 m0, s14, 0x2000
	s_nop 0
	global_load_lds_dwordx4 v[6:7], off
	v_lshl_add_u64 v[6:7], v[192:193], 0, s[66:67]
	s_mov_b32 m0, s71
	s_nop 0
	global_load_lds_dwordx4 v[6:7], off
	v_lshl_add_u64 v[6:7], v[198:199], 0, s[66:67]
	s_mov_b32 m0, s76
	s_nop 0
	global_load_lds_dwordx4 v[6:7], off
	s_waitcnt vmcnt(8)
	s_waitcnt lgkmcnt(0)
	s_barrier
	s_setprio 1
	v_mfma_f32_16x16x32_bf16 v[64:67], v[122:125], v[188:191], v[64:67]
	v_mfma_f32_16x16x32_bf16 v[60:63], v[140:143], v[188:191], v[60:63]
	v_mfma_f32_16x16x32_bf16 v[48:51], v[122:125], v[204:207], v[48:51]
	v_mfma_f32_16x16x32_bf16 v[44:47], v[140:143], v[204:207], v[44:47]
	v_mfma_f32_16x16x32_bf16 v[32:35], v[122:125], v[212:215], v[32:35]
	v_mfma_f32_16x16x32_bf16 v[28:31], v[140:143], v[212:215], v[28:31]
	v_mfma_f32_16x16x32_bf16 v[16:19], v[122:125], v[220:223], v[16:19]
	v_mfma_f32_16x16x32_bf16 v[12:15], v[140:143], v[220:223], v[12:15]
	v_mfma_f32_16x16x32_bf16 v[64:67], v[126:129], v[194:197], v[64:67]
	v_mfma_f32_16x16x32_bf16 v[60:63], v[152:155], v[194:197], v[60:63]
	v_mfma_f32_16x16x32_bf16 v[48:51], v[126:129], v[208:211], v[48:51]
	v_mfma_f32_16x16x32_bf16 v[44:47], v[152:155], v[208:211], v[44:47]
	v_mfma_f32_16x16x32_bf16 v[32:35], v[126:129], v[216:219], v[32:35]
	v_mfma_f32_16x16x32_bf16 v[28:31], v[152:155], v[216:219], v[28:31]
	v_mfma_f32_16x16x32_bf16 v[16:19], v[126:129], v[224:227], v[16:19]
	v_mfma_f32_16x16x32_bf16 v[12:15], v[152:155], v[224:227], v[12:15]
	v_mfma_f32_16x16x32_bf16 v[56:59], v[168:171], v[188:191], v[56:59]
	v_mfma_f32_16x16x32_bf16 v[52:55], v[176:179], v[188:191], v[52:55]
	v_mfma_f32_16x16x32_bf16 v[40:43], v[168:171], v[204:207], v[40:43]
	v_mfma_f32_16x16x32_bf16 v[36:39], v[176:179], v[204:207], v[36:39]
	v_mfma_f32_16x16x32_bf16 v[24:27], v[168:171], v[212:215], v[24:27]
	v_mfma_f32_16x16x32_bf16 v[20:23], v[176:179], v[212:215], v[20:23]
	v_mfma_f32_16x16x32_bf16 v[6:9], v[168:171], v[220:223], v[8:11]
	v_mfma_f32_16x16x32_bf16 v[2:5], v[176:179], v[220:223], v[2:5]
	v_mfma_f32_16x16x32_bf16 v[56:59], v[172:175], v[194:197], v[56:59]
	v_mfma_f32_16x16x32_bf16 v[52:55], v[180:183], v[194:197], v[52:55]
	v_mfma_f32_16x16x32_bf16 v[40:43], v[172:175], v[208:211], v[40:43]
	v_mfma_f32_16x16x32_bf16 v[36:39], v[180:183], v[208:211], v[36:39]
	v_mfma_f32_16x16x32_bf16 v[24:27], v[172:175], v[216:219], v[24:27]
	v_mfma_f32_16x16x32_bf16 v[20:23], v[180:183], v[216:219], v[20:23]
	v_mfma_f32_16x16x32_bf16 v[8:11], v[172:175], v[224:227], v[6:9]
	v_mfma_f32_16x16x32_bf16 v[4:7], v[180:183], v[224:227], v[2:5]
	s_setprio 0
	s_barrier
	s_add_i32 s85, s85, 2
	s_add_u32 s54, s54, 0x100
	s_addc_u32 s55, s55, 0
	s_cmp_gt_u32 s85, 13
	s_cbranch_scc1 .LBB0_866
